# phase 4: blocks sharing a CU with a scan block leave the attention queue to the others and scan blocks join the queue after their chain; K/V/Q projection epilogues: rstd and gain loads hoisted above t
# speedup vs baseline: 1.0329x; 1.0196x over previous
; #define LAS __attribute__((address_space(3)))
; template <int KSEL> DI void run_phase(const Params& p, int ph, char* lds) {
;     ...
;       const int natt = 768 + (last ? 0 : 96);
;       if (KSEL != 11) { if (bid < 192) { scan_task(p, l, bid / 24, (bid % 24) >> 2, (bid >> 1) & 1, bid & 1, lds); break; } if (KSEL == 4) break; }
;       const int aoff = KSEL == 11 ? 0 : 192;
;       if (KSEL == 11) {
;         for (int t = bid; t < natt + NCONV_FF; t += G) {
;           if (t < 768) { int bh = t >> 4, qb = t & 15; attn_task(p, bh / 6, bh % 6, NCTX + qb * 128, 0, TB, lds); }
;           else if (t < natt) { int u = t - 768; int bh = u >> 1, qb = u & 1; attn_task(p, bh / 6, bh % 6, qb * 128, 0, NCTX, lds); }
;           else conv_ff_task(p, l, t - natt, lds);
;         }
;       } else {
;         volatile LAS unsigned* slot = (volatile LAS unsigned*)(lds + 65536 + 8);
;         for (;;) {
;           __syncthreads();
;           if (tid == 0) *slot = __hip_atomic_fetch_add(p.BAR + 3456   + 64 * l, 1u, __ATOMIC_RELAXED, __HIP_MEMORY_SCOPE_AGENT);
;           __syncthreads();
;           const int t = (int)*slot;
;           if (t >= natt + NCONV_FF) break;
;           if (t < 768) { int bh = t >> 4, qb = t & 15; attn_task(p, bh / 6, bh % 6, NCTX + qb * 128, 0, TB, lds); }
;           else if (t < natt) { int u = t - 768; int bh = u >> 1, qb = u & 1; attn_task(p, bh / 6, bh % 6, qb * 128, 0, NCTX, lds); }
;           else conv_ff_task(p, l, t - natt, lds);
;         }
;       }
.Lscan_joins_queue:
	v_writelane_b32 v250, s82, 10
	v_readlane_b32 s26, v252, 13
	v_readlane_b32 s0, v250, 4
	v_readlane_b32 s1, v250, 5
	s_and_b64 s[0:1], s[0:1], exec
	s_movk_i32 s0, 0x360
	s_cselect_b32 s46, 0x300, s0
	s_lshl_b32 s0, s49, 6
	s_ashr_i32 s1, s0, 31
	s_add_i32 s47, s46, 0x840
	s_lshl_b64 s[0:1], s[0:1], 2
	s_add_u32 s0, s26, s0
	v_readlane_b32 s26, v252, 14
	v_readlane_b32 s72, v251, 51
	s_mul_i32 s3, s49, 0xb00000
	s_addc_u32 s1, s26, s1
	v_readlane_b32 s86, v252, 1
	s_mul_hi_i32 s2, s49, 0xb00000
	v_readlane_b32 s87, v252, 2
	s_add_u32 s38, s86, s3
	s_mul_i32 s21, s49, 0x1600000
	v_readlane_b32 s73, v251, 52
	v_readlane_b32 s74, v251, 53
	v_readlane_b32 s75, v251, 54
	v_readlane_b32 s84, v251, 63
	s_addc_u32 s39, s87, s2
	s_mul_hi_i32 s20, s49, 0x1600000
	v_readlane_b32 s85, v252, 0
	s_add_u32 s40, s84, s21
	v_readlane_b32 s72, v253, 5
	v_readlane_b32 s74, v253, 34
	v_cmp_eq_u32_e64 s[36:37], 0, v114
	s_addc_u32 s41, s85, s20
	v_readlane_b32 s73, v253, 6
	v_readlane_b32 s75, v253, 35
	s_mov_b32 s94, 0x2aaaaaab
	v_readlane_b32 s76, v251, 55
	v_readlane_b32 s77, v251, 56
	v_readlane_b32 s78, v251, 57
	v_readlane_b32 s79, v251, 58
	v_readlane_b32 s80, v251, 59
	v_readlane_b32 s81, v251, 60
	v_readlane_b32 s82, v251, 61
	v_readlane_b32 s83, v251, 62
	v_readlane_b32 s2, v254, 48
	s_nop 3
	s_cmpk_lt_i32 s2, 0x100
	s_cbranch_scc1 .LBB0_365
	s_cmpk_ge_i32 s2, 0x1c0
	s_cbranch_scc1 .LBB0_365
	s_branch .LBB0_407

; DI float red16(float x) { x = red8(x); x += dppf<0x140>(x); return x; }
; DI void unpack4(u32x2 v, float* f) { f[0] = bflo(v[0]); f[1] = bfhi(v[0]); f[2] = bflo(v[1]); f[3] = bfhi(v[1]); }
; DI void scan_task(const Params& p, int l, int b, int h, int dir, int half, char* lds) {
;     ...
;     for (int sec = 0; sec < 3; ++sec) {
;       float pc[4], pp[4], pn[4];
;       unpack4(ld[sec][1], pc); unpack4(ld[sec][0], pp); unpack4(ld[sec][2], pn);
; #pragma unroll
;       for (int j = 0; j < 4; ++j) ts[sec][j] = pc[j] + mu0[sec][j] * (pp[j] * mprev - pc[j]) + mu1[sec][j] * (pn[j] * mnext - pc[j]);
;     }
;     *(f32x4*)(cb + VR * CP + st_p * CS + c4 * 4) = (f32x4){ts[0][0], ts[0][1], ts[0][2], ts[0][3]};
;     *(f32x4*)(cb + VV * CP + st_p * CS + c4 * 4) = (f32x4){ts[2][0], ts[2][1], ts[2][2], ts[2][3]};
;     *(f32x4*)(tk + st_p * CS + c4 * 4) = (f32x4){ts[1][0], ts[1][1], ts[1][2], ts[1][3]};
;     ...
;       for (int ii = 0; ii < 16; ++ii) {
;         f32x4 nw = cw, nkk = ckk, nbb = cbb, nkd = ckd, nrr = crr; f32x2 nvv = cvv;
;         if (ii < 15) {
;           ps += inc; pv += inc;
;           nw = *(const f32x4*)(ps + VW * CP); nkk = *(const f32x4*)(ps + VKK * CP); nbb = *(const f32x4*)(ps + VB * CP);
;           nkd = *(const f32x4*)(ps + VKD * CP); nrr = *(const f32x4*)(ps + VR * CP); nvv = *(const f32x2*)pv;
;         }
;         __builtin_amdgcn_sched_barrier(0x7);
;         const f32x2 kk0 = {ckk[0], ckk[1]}, kk1 = {ckk[2], ckk[3]}, w0 = {cw[0], cw[1]}, w1 = {cw[2], cw[3]};
;         const f32x2 b0 = {cbb[0], cbb[1]}, b1 = {cbb[2], cbb[3]}, kd0 = {ckd[0], ckd[1]}, kd1 = {ckd[2], ckd[3]};
;         const f32x2 r0 = {crr[0], crr[1]}, r1 = {crr[2], crr[3]};
;         const f32x2 p0 = S0[0] * kk0 + S0[1] * kk1, p1 = S1[0] * kk0 + S1[1] * kk1;
;         const f32x2 u00 = S0[0] * w0 + kd0 * cvv[0], u01 = S0[1] * w1 + kd1 * cvv[0];
;         const f32x2 u10 = S1[0] * w0 + kd0 * cvv[1], u11 = S1[1] * w1 + kd1 * cvv[1];
;         const float q0 = red16(p0[0] + p0[1]), q1 = red16(p1[0] + p1[1]);
;         S0[0] = u00 - b0 * q0; S0[1] = u01 - b1 * q0;
;         S1[0] = u10 - b0 * q1; S1[1] = u11 - b1 * q1;
;         const f32x2 y0 = S0[0] * r0 + S0[1] * r1, y1 = S1[0] * r0 + S1[1] * r1;
;         *(f32x2*)py = (f32x2){y0[0] + y0[1], y1[0] + y1[1]};
;         py += dir ? -512 : 512;
;         cw = nw; ckk = nkk; cbb = nbb; ckd = nkd; crr = nrr; cvv = nvv;
;       }
.Lscan_loop:
	s_add_i32 s20, s38, 2
	s_min_u32 s20, s20, 0x8f
	s_lshl_b32 s21, s20, 4
	s_cmp_lt_u32 s20, 16
	s_movk_i32 s28, 0x9f0
	s_cselect_b32 s28, 0xf0, s28
	s_sub_u32 s28, s28, s21
	s_cmp_eq_u32 s26, 0
	s_cselect_b32 s28, s21, s28
	ds_read_b128 v[226:229], v244 offset:4624
	s_waitcnt vmcnt(8)
	ds_read_b128 v[222:225], v244 offset:272
	ds_read_b128 v[234:237], v244 offset:13328
	v_lshlrev_b32_e32 v202, 16, v78
	ds_read_b128 v[230:233], v244 offset:8976
	ds_read_b128 v[238:241], v244 offset:17680
	ds_read_b64 v[242:243], v245 offset:22032
	v_and_b32_e32 v203, 0xffff0000, v78
	v_pk_mul_f32 v[128:129], v[116:117], v[164:165]
	v_pk_mul_f32 v[130:131], v[120:121], v[164:165]
	v_lshlrev_b32_e32 v204, 16, v80
	v_pk_fma_f32 v[128:129], v[118:119], v[166:167], v[128:129]
	v_pk_fma_f32 v[130:131], v[122:123], v[166:167], v[130:131]
	v_and_b32_e32 v205, 0xffff0000, v80
	v_pk_mul_f32 v[136:137], v[172:173], v[180:181] op_sel_hi:[1,0]
	v_pk_mul_f32 v[182:183], v[174:175], v[180:181] op_sel_hi:[1,0]
	v_add_f32_e32 v132, v128, v129
	v_lshlrev_b32_e32 v206, 16, v84
	v_add_f32_e32 v134, v130, v131
	v_pk_mul_f32 v[184:185], v[172:173], v[180:181] op_sel:[0,1]
	v_pk_mul_f32 v[186:187], v[174:175], v[180:181] op_sel:[0,1]
	v_and_b32_e32 v207, 0xffff0000, v84
	v_add_f32_dpp v132, v132, v132 quad_perm:[1,0,3,2] row_mask:0xf bank_mask:0xf bound_ctrl:1
	v_add_f32_dpp v134, v134, v134 quad_perm:[1,0,3,2] row_mask:0xf bank_mask:0xf bound_ctrl:1
	v_pk_fma_f32 v[136:137], v[116:117], v[160:161], v[136:137]
	v_pk_fma_f32 v[204:205], v[96:97], v[204:205], v[202:203] op_sel_hi:[0,1,1] neg_lo:[0,0,1] neg_hi:[0,0,1]
	v_add_f32_dpp v132, v132, v132 quad_perm:[2,3,0,1] row_mask:0xf bank_mask:0xf bound_ctrl:1
	v_add_f32_dpp v134, v134, v134 quad_perm:[2,3,0,1] row_mask:0xf bank_mask:0xf bound_ctrl:1
	v_pk_fma_f32 v[204:205], v[22:23], v[204:205], v[202:203]
	v_pk_fma_f32 v[182:183], v[118:119], v[162:163], v[182:183]
	v_add_f32_dpp v132, v132, v132 row_half_mirror row_mask:0xf bank_mask:0xf bound_ctrl:1
	v_add_f32_dpp v134, v134, v134 row_half_mirror row_mask:0xf bank_mask:0xf bound_ctrl:1
	v_pk_fma_f32 v[202:203], v[98:99], v[206:207], v[202:203] op_sel_hi:[0,1,1] neg_lo:[0,0,1] neg_hi:[0,0,1]
	v_pk_fma_f32 v[184:185], v[120:121], v[160:161], v[184:185]
	v_add_f32_dpp v132, v132, v132 row_mirror row_mask:0xf bank_mask:0xf bound_ctrl:1
	v_add_f32_dpp v134, v134, v134 row_mirror row_mask:0xf bank_mask:0xf bound_ctrl:1
	v_pk_fma_f32 v[202:203], v[18:19], v[202:203], v[204:205]
	v_pk_fma_f32 v[186:187], v[122:123], v[162:163], v[186:187]
	v_pk_fma_f32 v[116:117], v[168:169], v[132:133], v[136:137] op_sel_hi:[1,0,1] neg_lo:[1,0,0] neg_hi:[1,0,0]
	v_lshlrev_b32_e32 v204, 16, v79
	v_pk_fma_f32 v[118:119], v[170:171], v[132:133], v[182:183] op_sel_hi:[1,0,1] neg_lo:[1,0,0] neg_hi:[1,0,0]
	v_pk_fma_f32 v[120:121], v[168:169], v[134:135], v[184:185] op_sel_hi:[1,0,1] neg_lo:[1,0,0] neg_hi:[1,0,0]
	v_pk_fma_f32 v[122:123], v[170:171], v[134:135], v[186:187] op_sel_hi:[1,0,1] neg_lo:[1,0,0] neg_hi:[1,0,0]
	v_and_b32_e32 v205, 0xffff0000, v79
	v_pk_mul_f32 v[188:189], v[116:117], v[176:177]
	v_pk_mul_f32 v[190:191], v[120:121], v[176:177]
	v_pk_fma_f32 v[188:189], v[118:119], v[178:179], v[188:189]
	v_lshlrev_b32_e32 v206, 16, v81
	v_pk_fma_f32 v[190:191], v[122:123], v[178:179], v[190:191]
	v_add_f32_e32 v246, v188, v189
	v_add_f32_e32 v247, v190, v191
	v_and_b32_e32 v207, 0xffff0000, v81
	ds_write_b64 v159, v[246:247] offset:52224
	ds_read_b128 v[164:167], v244 offset:4896
	v_lshlrev_b32_e32 v208, 16, v85
	ds_read_b128 v[160:163], v244 offset:544
	ds_read_b128 v[172:175], v244 offset:13600
	ds_read_b128 v[168:171], v244 offset:9248
	v_and_b32_e32 v209, 0xffff0000, v85
	ds_read_b128 v[176:179], v244 offset:17952
	ds_read_b64 v[180:181], v245 offset:22304
	s_waitcnt lgkmcnt(7)
	v_pk_fma_f32 v[206:207], v[96:97], v[206:207], v[204:205] op_sel_hi:[0,1,1] neg_lo:[0,0,1] neg_hi:[0,0,1]
	v_pk_mul_f32 v[128:129], v[116:117], v[226:227]
	v_pk_mul_f32 v[130:131], v[120:121], v[226:227]
	v_pk_fma_f32 v[206:207], v[24:25], v[206:207], v[204:205]
	v_pk_fma_f32 v[128:129], v[118:119], v[228:229], v[128:129]
	v_pk_fma_f32 v[130:131], v[122:123], v[228:229], v[130:131]
	v_pk_mul_f32 v[136:137], v[234:235], v[242:243] op_sel_hi:[1,0]
	v_pk_fma_f32 v[204:205], v[98:99], v[208:209], v[204:205] op_sel_hi:[0,1,1] neg_lo:[0,0,1] neg_hi:[0,0,1]
	v_pk_mul_f32 v[182:183], v[236:237], v[242:243] op_sel_hi:[1,0]
	v_add_f32_e32 v132, v128, v129
	v_add_f32_e32 v134, v130, v131
	v_pk_fma_f32 v[204:205], v[20:21], v[204:205], v[206:207]
	v_pk_mul_f32 v[184:185], v[234:235], v[242:243] op_sel:[0,1]
	v_pk_mul_f32 v[186:187], v[236:237], v[242:243] op_sel:[0,1]
	v_add_f32_dpp v132, v132, v132 quad_perm:[1,0,3,2] row_mask:0xf bank_mask:0xf bound_ctrl:1
	v_lshlrev_b32_e32 v206, 16, v82
	v_add_f32_dpp v134, v134, v134 quad_perm:[1,0,3,2] row_mask:0xf bank_mask:0xf bound_ctrl:1
	v_pk_fma_f32 v[136:137], v[116:117], v[222:223], v[136:137]
	v_and_b32_e32 v207, 0xffff0000, v82
	v_add_f32_dpp v132, v132, v132 quad_perm:[2,3,0,1] row_mask:0xf bank_mask:0xf bound_ctrl:1
	v_add_f32_dpp v134, v134, v134 quad_perm:[2,3,0,1] row_mask:0xf bank_mask:0xf bound_ctrl:1
	v_pk_fma_f32 v[182:183], v[118:119], v[224:225], v[182:183]
	v_lshlrev_b32_e32 v208, 16, v88
	v_add_f32_dpp v132, v132, v132 row_half_mirror row_mask:0xf bank_mask:0xf bound_ctrl:1
	v_add_f32_dpp v134, v134, v134 row_half_mirror row_mask:0xf bank_mask:0xf bound_ctrl:1
	v_pk_fma_f32 v[184:185], v[120:121], v[222:223], v[184:185]
	v_and_b32_e32 v209, 0xffff0000, v88
	v_add_f32_dpp v132, v132, v132 row_mirror row_mask:0xf bank_mask:0xf bound_ctrl:1
; DI float red16(float x) { x = red8(x); x += dppf<0x140>(x); return x; }
; DI void unpack4(u32x2 v, float* f) { f[0] = bflo(v[0]); f[1] = bfhi(v[0]); f[2] = bflo(v[1]); f[3] = bfhi(v[1]); }
; DI void scan_task(const Params& p, int l, int b, int h, int dir, int half, char* lds) {
;     ...
;     for (int sec = 0; sec < 3; ++sec) {
;       float pc[4], pp[4], pn[4];
;       unpack4(ld[sec][1], pc); unpack4(ld[sec][0], pp); unpack4(ld[sec][2], pn);
; #pragma unroll
;       for (int j = 0; j < 4; ++j) ts[sec][j] = pc[j] + mu0[sec][j] * (pp[j] * mprev - pc[j]) + mu1[sec][j] * (pn[j] * mnext - pc[j]);
;     }
;     *(f32x4*)(cb + VR * CP + st_p * CS + c4 * 4) = (f32x4){ts[0][0], ts[0][1], ts[0][2], ts[0][3]};
;     *(f32x4*)(cb + VV * CP + st_p * CS + c4 * 4) = (f32x4){ts[2][0], ts[2][1], ts[2][2], ts[2][3]};
;     *(f32x4*)(tk + st_p * CS + c4 * 4) = (f32x4){ts[1][0], ts[1][1], ts[1][2], ts[1][3]};
;     ...
;       for (int ii = 0; ii < 16; ++ii) {
;         f32x4 nw = cw, nkk = ckk, nbb = cbb, nkd = ckd, nrr = crr; f32x2 nvv = cvv;
;         if (ii < 15) {
;           ps += inc; pv += inc;
;           nw = *(const f32x4*)(ps + VW * CP); nkk = *(const f32x4*)(ps + VKK * CP); nbb = *(const f32x4*)(ps + VB * CP);
;           nkd = *(const f32x4*)(ps + VKD * CP); nrr = *(const f32x4*)(ps + VR * CP); nvv = *(const f32x2*)pv;
;         }
;         __builtin_amdgcn_sched_barrier(0x7);
;         const f32x2 kk0 = {ckk[0], ckk[1]}, kk1 = {ckk[2], ckk[3]}, w0 = {cw[0], cw[1]}, w1 = {cw[2], cw[3]};
;         const f32x2 b0 = {cbb[0], cbb[1]}, b1 = {cbb[2], cbb[3]}, kd0 = {ckd[0], ckd[1]}, kd1 = {ckd[2], ckd[3]};
;         const f32x2 r0 = {crr[0], crr[1]}, r1 = {crr[2], crr[3]};
;         const f32x2 p0 = S0[0] * kk0 + S0[1] * kk1, p1 = S1[0] * kk0 + S1[1] * kk1;
;         const f32x2 u00 = S0[0] * w0 + kd0 * cvv[0], u01 = S0[1] * w1 + kd1 * cvv[0];
;         const f32x2 u10 = S1[0] * w0 + kd0 * cvv[1], u11 = S1[1] * w1 + kd1 * cvv[1];
;         const float q0 = red16(p0[0] + p0[1]), q1 = red16(p1[0] + p1[1]);
;         S0[0] = u00 - b0 * q0; S0[1] = u01 - b1 * q0;
;         S1[0] = u10 - b0 * q1; S1[1] = u11 - b1 * q1;
;         const f32x2 y0 = S0[0] * r0 + S0[1] * r1, y1 = S1[0] * r0 + S1[1] * r1;
;         *(f32x2*)py = (f32x2){y0[0] + y0[1], y1[0] + y1[1]};
;         py += dir ? -512 : 512;
;         cw = nw; ckk = nkk; cbb = nbb; ckd = nkd; crr = nrr; cvv = nvv;
;       }
	v_add_f32_dpp v134, v134, v134 row_mirror row_mask:0xf bank_mask:0xf bound_ctrl:1
	v_lshlrev_b32_e32 v210, 16, v90
	v_pk_fma_f32 v[186:187], v[122:123], v[224:225], v[186:187]
	v_pk_fma_f32 v[116:117], v[230:231], v[132:133], v[136:137] op_sel_hi:[1,0,1] neg_lo:[1,0,0] neg_hi:[1,0,0]
	v_pk_fma_f32 v[118:119], v[232:233], v[132:133], v[182:183] op_sel_hi:[1,0,1] neg_lo:[1,0,0] neg_hi:[1,0,0]
	v_and_b32_e32 v211, 0xffff0000, v90
	v_pk_fma_f32 v[120:121], v[230:231], v[134:135], v[184:185] op_sel_hi:[1,0,1] neg_lo:[1,0,0] neg_hi:[1,0,0]
	v_pk_fma_f32 v[122:123], v[232:233], v[134:135], v[186:187] op_sel_hi:[1,0,1] neg_lo:[1,0,0] neg_hi:[1,0,0]
	v_pk_mul_f32 v[188:189], v[116:117], v[238:239]
	v_pk_fma_f32 v[208:209], v[96:97], v[208:209], v[206:207] op_sel_hi:[0,1,1] neg_lo:[0,0,1] neg_hi:[0,0,1]
	v_pk_mul_f32 v[190:191], v[120:121], v[238:239]
	v_pk_fma_f32 v[188:189], v[118:119], v[240:241], v[188:189]
	v_pk_fma_f32 v[190:191], v[122:123], v[240:241], v[190:191]
	v_pk_fma_f32 v[208:209], v[26:27], v[208:209], v[206:207]
	v_add_f32_e32 v246, v188, v189
	v_add_f32_e32 v247, v190, v191
	v_pk_fma_f32 v[206:207], v[98:99], v[210:211], v[206:207] op_sel_hi:[0,1,1] neg_lo:[0,0,1] neg_hi:[0,0,1]
	ds_write_b64 v159, v[246:247] offset:54272
	ds_read_b128 v[226:229], v244 offset:5168
	ds_read_b128 v[222:225], v244 offset:816
	v_pk_fma_f32 v[206:207], v[30:31], v[206:207], v[208:209]
	ds_read_b128 v[234:237], v244 offset:13872
	ds_read_b128 v[230:233], v244 offset:9520
	ds_read_b128 v[238:241], v244 offset:18224
	v_lshlrev_b32_e32 v208, 16, v83
	ds_read_b64 v[242:243], v245 offset:22576
	s_waitcnt lgkmcnt(7)
	v_and_b32_e32 v209, 0xffff0000, v83
	v_pk_mul_f32 v[128:129], v[116:117], v[164:165]
	v_pk_mul_f32 v[130:131], v[120:121], v[164:165]
	v_pk_fma_f32 v[128:129], v[118:119], v[166:167], v[128:129]
	v_lshlrev_b32_e32 v210, 16, v89
	v_pk_fma_f32 v[130:131], v[122:123], v[166:167], v[130:131]
	v_pk_mul_f32 v[136:137], v[172:173], v[180:181] op_sel_hi:[1,0]
	v_pk_mul_f32 v[182:183], v[174:175], v[180:181] op_sel_hi:[1,0]
	v_and_b32_e32 v211, 0xffff0000, v89
	v_add_f32_e32 v132, v128, v129
	v_add_f32_e32 v134, v130, v131
	v_pk_mul_f32 v[184:185], v[172:173], v[180:181] op_sel:[0,1]
	v_lshlrev_b32_e32 v212, 16, v91
	v_pk_mul_f32 v[186:187], v[174:175], v[180:181] op_sel:[0,1]
	v_add_f32_dpp v132, v132, v132 quad_perm:[1,0,3,2] row_mask:0xf bank_mask:0xf bound_ctrl:1
	v_and_b32_e32 v213, 0xffff0000, v91
	v_add_f32_dpp v134, v134, v134 quad_perm:[1,0,3,2] row_mask:0xf bank_mask:0xf bound_ctrl:1
	v_pk_fma_f32 v[136:137], v[116:117], v[160:161], v[136:137]
	v_add_f32_dpp v132, v132, v132 quad_perm:[2,3,0,1] row_mask:0xf bank_mask:0xf bound_ctrl:1
	v_pk_fma_f32 v[210:211], v[96:97], v[210:211], v[208:209] op_sel_hi:[0,1,1] neg_lo:[0,0,1] neg_hi:[0,0,1]
	v_add_f32_dpp v134, v134, v134 quad_perm:[2,3,0,1] row_mask:0xf bank_mask:0xf bound_ctrl:1
	v_pk_fma_f32 v[182:183], v[118:119], v[162:163], v[182:183]
	v_add_f32_dpp v132, v132, v132 row_half_mirror row_mask:0xf bank_mask:0xf bound_ctrl:1
	v_pk_fma_f32 v[210:211], v[28:29], v[210:211], v[208:209]
	v_add_f32_dpp v134, v134, v134 row_half_mirror row_mask:0xf bank_mask:0xf bound_ctrl:1
	v_pk_fma_f32 v[184:185], v[120:121], v[160:161], v[184:185]
	v_add_f32_dpp v132, v132, v132 row_mirror row_mask:0xf bank_mask:0xf bound_ctrl:1
	v_pk_fma_f32 v[208:209], v[98:99], v[212:213], v[208:209] op_sel_hi:[0,1,1] neg_lo:[0,0,1] neg_hi:[0,0,1]
	v_add_f32_dpp v134, v134, v134 row_mirror row_mask:0xf bank_mask:0xf bound_ctrl:1
	v_pk_fma_f32 v[186:187], v[122:123], v[162:163], v[186:187]
	v_pk_fma_f32 v[208:209], v[32:33], v[208:209], v[210:211]
	v_pk_fma_f32 v[116:117], v[168:169], v[132:133], v[136:137] op_sel_hi:[1,0,1] neg_lo:[1,0,0] neg_hi:[1,0,0]
	v_pk_fma_f32 v[118:119], v[170:171], v[132:133], v[182:183] op_sel_hi:[1,0,1] neg_lo:[1,0,0] neg_hi:[1,0,0]
	v_pk_fma_f32 v[120:121], v[168:169], v[134:135], v[184:185] op_sel_hi:[1,0,1] neg_lo:[1,0,0] neg_hi:[1,0,0]
	v_lshlrev_b32_e32 v210, 16, v86
	v_pk_fma_f32 v[122:123], v[170:171], v[134:135], v[186:187] op_sel_hi:[1,0,1] neg_lo:[1,0,0] neg_hi:[1,0,0]
	v_pk_mul_f32 v[188:189], v[116:117], v[176:177]
	v_pk_mul_f32 v[190:191], v[120:121], v[176:177]
	v_and_b32_e32 v211, 0xffff0000, v86
	v_pk_fma_f32 v[188:189], v[118:119], v[178:179], v[188:189]
	v_pk_fma_f32 v[190:191], v[122:123], v[178:179], v[190:191]
	v_lshlrev_b32_e32 v212, 16, v92
	v_add_f32_e32 v246, v188, v189
	v_add_f32_e32 v247, v190, v191
	ds_write_b64 v159, v[246:247] offset:56320
	v_and_b32_e32 v213, 0xffff0000, v92
	ds_read_b128 v[164:167], v244 offset:5440
	ds_read_b128 v[160:163], v244 offset:1088
	ds_read_b128 v[172:175], v244 offset:14144
	v_lshlrev_b32_e32 v214, 16, v94
	ds_read_b128 v[168:171], v244 offset:9792
	ds_read_b128 v[176:179], v244 offset:18496
	ds_read_b64 v[180:181], v245 offset:22848
	v_and_b32_e32 v215, 0xffff0000, v94
	s_waitcnt lgkmcnt(7)
; DI void scan_task(const Params& p, int l, int b, int h, int dir, int half, char* lds) {
;     ...
;     *(f32x4*)(cb + VR * CP + st_p * CS + c4 * 4) = (f32x4){ts[0][0], ts[0][1], ts[0][2], ts[0][3]};
;     *(f32x4*)(cb + VV * CP + st_p * CS + c4 * 4) = (f32x4){ts[2][0], ts[2][1], ts[2][2], ts[2][3]};
;     *(f32x4*)(tk + st_p * CS + c4 * 4) = (f32x4){ts[1][0], ts[1][1], ts[1][2], ts[1][3]};
;     float kx[4], ss = 0.f;
; #pragma unroll
;     ...
;       for (int ii = 0; ii < 16; ++ii) {
;         f32x4 nw = cw, nkk = ckk, nbb = cbb, nkd = ckd, nrr = crr; f32x2 nvv = cvv;
;         if (ii < 15) {
;           ps += inc; pv += inc;
;           nw = *(const f32x4*)(ps + VW * CP); nkk = *(const f32x4*)(ps + VKK * CP); nbb = *(const f32x4*)(ps + VB * CP);
;           nkd = *(const f32x4*)(ps + VKD * CP); nrr = *(const f32x4*)(ps + VR * CP); nvv = *(const f32x2*)pv;
;         }
;         __builtin_amdgcn_sched_barrier(0x7);
;         const f32x2 kk0 = {ckk[0], ckk[1]}, kk1 = {ckk[2], ckk[3]}, w0 = {cw[0], cw[1]}, w1 = {cw[2], cw[3]};
;         const f32x2 b0 = {cbb[0], cbb[1]}, b1 = {cbb[2], cbb[3]}, kd0 = {ckd[0], ckd[1]}, kd1 = {ckd[2], ckd[3]};
;         const f32x2 r0 = {crr[0], crr[1]}, r1 = {crr[2], crr[3]};
;         const f32x2 p0 = S0[0] * kk0 + S0[1] * kk1, p1 = S1[0] * kk0 + S1[1] * kk1;
;         const f32x2 u00 = S0[0] * w0 + kd0 * cvv[0], u01 = S0[1] * w1 + kd1 * cvv[0];
;         const f32x2 u10 = S1[0] * w0 + kd0 * cvv[1], u11 = S1[1] * w1 + kd1 * cvv[1];
;         const float q0 = red16(p0[0] + p0[1]), q1 = red16(p1[0] + p1[1]);
;         S0[0] = u00 - b0 * q0; S0[1] = u01 - b1 * q0;
;         S1[0] = u10 - b0 * q1; S1[1] = u11 - b1 * q1;
;         const f32x2 y0 = S0[0] * r0 + S0[1] * r1, y1 = S1[0] * r0 + S1[1] * r1;
;         *(f32x2*)py = (f32x2){y0[0] + y0[1], y1[0] + y1[1]};
;         py += dir ? -512 : 512;
;         cw = nw; ckk = nkk; cbb = nbb; ckd = nkd; crr = nrr; cvv = nvv;
;       }
;     }
;     __syncthreads();
;     {
;       const int slo = chunk_lo(c);
;       const float* yp = ybuf + (st_p * 16 + c4) * 32;
;       f32x4 a = *(const f32x4*)(yp + 4 * (c4 & 7));
; #pragma unroll
;       for (int i = 1; i < 8; ++i) a += *(const f32x4*)(yp + 4 * ((i + c4) & 7));
;       *(f32x2*)(p.Y + (size_t)dir * T_TOK * 384 + (size_t)(b * TB + slo + st_p) * 384 + hc + half * 32 + c4 * 2) = (f32x2){a[0] + a[2], a[1] + a[3]};
	v_pk_mul_f32 v[128:129], v[116:117], v[226:227]
	v_pk_fma_f32 v[212:213], v[96:97], v[212:213], v[210:211] op_sel_hi:[0,1,1] neg_lo:[0,0,1] neg_hi:[0,0,1]
	v_pk_mul_f32 v[130:131], v[120:121], v[226:227]
	v_pk_fma_f32 v[128:129], v[118:119], v[228:229], v[128:129]
	v_pk_fma_f32 v[130:131], v[122:123], v[228:229], v[130:131]
	v_pk_fma_f32 v[212:213], v[38:39], v[212:213], v[210:211]
	v_pk_mul_f32 v[136:137], v[234:235], v[242:243] op_sel_hi:[1,0]
	v_pk_mul_f32 v[182:183], v[236:237], v[242:243] op_sel_hi:[1,0]
	v_add_f32_e32 v132, v128, v129
	v_pk_fma_f32 v[210:211], v[98:99], v[214:215], v[210:211] op_sel_hi:[0,1,1] neg_lo:[0,0,1] neg_hi:[0,0,1]
	v_add_f32_e32 v134, v130, v131
	v_pk_mul_f32 v[184:185], v[234:235], v[242:243] op_sel:[0,1]
	v_pk_fma_f32 v[210:211], v[34:35], v[210:211], v[212:213]
	v_pk_mul_f32 v[186:187], v[236:237], v[242:243] op_sel:[0,1]
	v_add_f32_dpp v132, v132, v132 quad_perm:[1,0,3,2] row_mask:0xf bank_mask:0xf bound_ctrl:1
	v_add_f32_dpp v134, v134, v134 quad_perm:[1,0,3,2] row_mask:0xf bank_mask:0xf bound_ctrl:1
	v_lshlrev_b32_e32 v212, 16, v87
	v_pk_fma_f32 v[136:137], v[116:117], v[222:223], v[136:137]
	v_add_f32_dpp v132, v132, v132 quad_perm:[2,3,0,1] row_mask:0xf bank_mask:0xf bound_ctrl:1
	v_add_f32_dpp v134, v134, v134 quad_perm:[2,3,0,1] row_mask:0xf bank_mask:0xf bound_ctrl:1
	v_and_b32_e32 v213, 0xffff0000, v87
	v_pk_fma_f32 v[182:183], v[118:119], v[224:225], v[182:183]
	v_add_f32_dpp v132, v132, v132 row_half_mirror row_mask:0xf bank_mask:0xf bound_ctrl:1
	v_add_f32_dpp v134, v134, v134 row_half_mirror row_mask:0xf bank_mask:0xf bound_ctrl:1
	v_lshlrev_b32_e32 v214, 16, v93
	v_pk_fma_f32 v[184:185], v[120:121], v[222:223], v[184:185]
	v_add_f32_dpp v132, v132, v132 row_mirror row_mask:0xf bank_mask:0xf bound_ctrl:1
	v_and_b32_e32 v215, 0xffff0000, v93
	v_add_f32_dpp v134, v134, v134 row_mirror row_mask:0xf bank_mask:0xf bound_ctrl:1
	v_pk_fma_f32 v[186:187], v[122:123], v[224:225], v[186:187]
	v_pk_fma_f32 v[116:117], v[230:231], v[132:133], v[136:137] op_sel_hi:[1,0,1] neg_lo:[1,0,0] neg_hi:[1,0,0]
	v_lshlrev_b32_e32 v216, 16, v95
	v_pk_fma_f32 v[118:119], v[232:233], v[132:133], v[182:183] op_sel_hi:[1,0,1] neg_lo:[1,0,0] neg_hi:[1,0,0]
	v_pk_fma_f32 v[120:121], v[230:231], v[134:135], v[184:185] op_sel_hi:[1,0,1] neg_lo:[1,0,0] neg_hi:[1,0,0]
	v_pk_fma_f32 v[122:123], v[232:233], v[134:135], v[186:187] op_sel_hi:[1,0,1] neg_lo:[1,0,0] neg_hi:[1,0,0]
	v_and_b32_e32 v217, 0xffff0000, v95
	v_pk_mul_f32 v[188:189], v[116:117], v[238:239]
	v_pk_mul_f32 v[190:191], v[120:121], v[238:239]
	v_pk_fma_f32 v[214:215], v[96:97], v[214:215], v[212:213] op_sel_hi:[0,1,1] neg_lo:[0,0,1] neg_hi:[0,0,1]
	v_pk_fma_f32 v[188:189], v[118:119], v[240:241], v[188:189]
	v_pk_fma_f32 v[190:191], v[122:123], v[240:241], v[190:191]
	v_add_f32_e32 v246, v188, v189
	v_pk_fma_f32 v[214:215], v[40:41], v[214:215], v[212:213]
	v_add_f32_e32 v247, v190, v191
	ds_write_b64 v159, v[246:247] offset:58368
	ds_read_b128 v[192:195], v124 offset:52224
	v_pk_fma_f32 v[212:213], v[98:99], v[216:217], v[212:213] op_sel_hi:[0,1,1] neg_lo:[0,0,1] neg_hi:[0,0,1]
	ds_read_b128 v[196:199], v124 offset:52240
	s_mul_i32 s20, s26, 15
	s_add_i32 s20, s20, 0
	v_pk_fma_f32 v[212:213], v[36:37], v[212:213], v[214:215]
	s_add_i32 s20, s20, s27
	s_add_i32 s20, s20, s100
	v_pk_mul_f32 v[214:215], v[42:43], v[206:207]
	s_mulk_i32 s20, 0x600
	s_waitcnt lgkmcnt(0)
	v_pk_add_f32 v[192:193], v[192:193], v[194:195]
	v_pk_mul_f32 v[218:219], v[44:45], v[208:209]
	v_pk_add_f32 v[196:197], v[196:197], v[198:199]
	v_add_u32_e32 v125, s20, v200
	v_pk_add_f32 v[192:193], v[192:193], v[196:197]
	v_pk_mul_f32 v[216:217], v[214:215], v[214:215]
	s_nop 1
	v_add_f32_dpp v192, v192, v192 quad_perm:[1,0,3,2] row_mask:0xf bank_mask:0xf bound_ctrl:1
	v_pk_mul_f32 v[220:221], v[218:219], v[218:219]
	v_add_f32_dpp v193, v193, v193 quad_perm:[1,0,3,2] row_mask:0xf bank_mask:0xf bound_ctrl:1
	s_nop 0
	v_add_f32_dpp v192, v192, v192 quad_perm:[2,3,0,1] row_mask:0xf bank_mask:0xf bound_ctrl:1
	v_add_f32_e32 v110, v216, v217
	v_add_f32_dpp v193, v193, v193 quad_perm:[2,3,0,1] row_mask:0xf bank_mask:0xf bound_ctrl:1
	global_store_dwordx2 v125, v[192:193], s[98:99]
	ds_read_b128 v[226:229], v244 offset:5712
	v_add_f32_e32 v110, v220, v110
	ds_read_b128 v[222:225], v244 offset:1360
	ds_read_b128 v[234:237], v244 offset:14416
	ds_read_b128 v[230:233], v244 offset:10064
	v_add_f32_e32 v110, v221, v110
	ds_read_b128 v[238:241], v244 offset:18768
	ds_read_b64 v[242:243], v245 offset:23120
	ds_write_b128 v100, v[202:205] offset:17408
	v_pk_mul_f32 v[128:129], v[116:117], v[164:165]
	v_pk_mul_f32 v[130:131], v[120:121], v[164:165]
	ds_write_b128 v100, v[210:213] offset:21760
	v_pk_fma_f32 v[128:129], v[118:119], v[166:167], v[128:129]
	v_pk_fma_f32 v[130:131], v[122:123], v[166:167], v[130:131]
	v_pk_mul_f32 v[136:137], v[172:173], v[180:181] op_sel_hi:[1,0]
	ds_write_b128 v100, v[206:209] offset:13056
	v_pk_mul_f32 v[182:183], v[174:175], v[180:181] op_sel_hi:[1,0]
	v_add_f32_e32 v132, v128, v129
	v_add_f32_e32 v134, v130, v131
	v_add_f32_dpp v110, v110, v110 quad_perm:[1,0,3,2] row_mask:0xf bank_mask:0xf bound_ctrl:1
	v_pk_mul_f32 v[184:185], v[172:173], v[180:181] op_sel:[0,1]
	v_pk_mul_f32 v[186:187], v[174:175], v[180:181] op_sel:[0,1]
	s_waitcnt vmcnt(4)
; DI float red16(float x) { x = red8(x); x += dppf<0x140>(x); return x; }
; DI void scan_task(const Params& p, int l, int b, int h, int dir, int half, char* lds) {
;     ...
;     float kx[4], ss = 0.f;
; #pragma unroll
;     for (int j = 0; j < 4; ++j) { kx[j] = ts[1][j] * kkg[j]; ss += kx[j] * kx[j]; }
;     ss = red16(ss);
;     const float inv = rsqrtf(ss + 1e-12f);
;     *(f32x4*)(cb + VKK * CP + st_p * CS + c4 * 4) = (f32x4){kx[0] * inv, kx[1] * inv, kx[2] * inv, kx[3] * inv};
;     __syncthreads();
;     f32x4 dw = {0.f, 0.f, 0.f, 0.f}, da = {0.f, 0.f, 0.f, 0.f};
; #pragma unroll
;     for (int ks = 0; ks < 2; ++ks) {
;       dw = __builtin_amdgcn_mfma_f32_16x16x32_bf16(bw[ks], aw[ks], dw, 0, 0, 0);
;       da = __builtin_amdgcn_mfma_f32_16x16x32_bf16(ba[ks], aa[ks], da, 0, 0, 0);
;     }
;     ...
;       for (int ii = 0; ii < 16; ++ii) {
;         f32x4 nw = cw, nkk = ckk, nbb = cbb, nkd = ckd, nrr = crr; f32x2 nvv = cvv;
;         if (ii < 15) {
;           ps += inc; pv += inc;
;           nw = *(const f32x4*)(ps + VW * CP); nkk = *(const f32x4*)(ps + VKK * CP); nbb = *(const f32x4*)(ps + VB * CP);
;           nkd = *(const f32x4*)(ps + VKD * CP); nrr = *(const f32x4*)(ps + VR * CP); nvv = *(const f32x2*)pv;
;         }
;         __builtin_amdgcn_sched_barrier(0x7);
;         const f32x2 kk0 = {ckk[0], ckk[1]}, kk1 = {ckk[2], ckk[3]}, w0 = {cw[0], cw[1]}, w1 = {cw[2], cw[3]};
;         const f32x2 b0 = {cbb[0], cbb[1]}, b1 = {cbb[2], cbb[3]}, kd0 = {ckd[0], ckd[1]}, kd1 = {ckd[2], ckd[3]};
;         const f32x2 r0 = {crr[0], crr[1]}, r1 = {crr[2], crr[3]};
;         const f32x2 p0 = S0[0] * kk0 + S0[1] * kk1, p1 = S1[0] * kk0 + S1[1] * kk1;
;         const f32x2 u00 = S0[0] * w0 + kd0 * cvv[0], u01 = S0[1] * w1 + kd1 * cvv[0];
;         const f32x2 u10 = S1[0] * w0 + kd0 * cvv[1], u11 = S1[1] * w1 + kd1 * cvv[1];
;         const float q0 = red16(p0[0] + p0[1]), q1 = red16(p1[0] + p1[1]);
;         S0[0] = u00 - b0 * q0; S0[1] = u01 - b1 * q0;
;         S1[0] = u10 - b0 * q1; S1[1] = u11 - b1 * q1;
;         const f32x2 y0 = S0[0] * r0 + S0[1] * r1, y1 = S1[0] * r0 + S1[1] * r1;
;         *(f32x2*)py = (f32x2){y0[0] + y0[1], y1[0] + y1[1]};
;         py += dir ? -512 : 512;
;         cw = nw; ckk = nkk; cbb = nbb; ckd = nkd; crr = nrr; cvv = nvv;
;       }
	v_add_f32_dpp v132, v132, v132 quad_perm:[1,0,3,2] row_mask:0xf bank_mask:0xf bound_ctrl:1
	v_add_f32_dpp v134, v134, v134 quad_perm:[1,0,3,2] row_mask:0xf bank_mask:0xf bound_ctrl:1
	v_pk_fma_f32 v[136:137], v[116:117], v[160:161], v[136:137]
	v_mfma_f32_16x16x32_bf16 v[206:209], v[2:5], v[62:65], 0
	v_add_f32_dpp v132, v132, v132 quad_perm:[2,3,0,1] row_mask:0xf bank_mask:0xf bound_ctrl:1
	v_add_f32_dpp v134, v134, v134 quad_perm:[2,3,0,1] row_mask:0xf bank_mask:0xf bound_ctrl:1
	v_pk_fma_f32 v[182:183], v[118:119], v[162:163], v[182:183]
	v_add_f32_dpp v110, v110, v110 quad_perm:[2,3,0,1] row_mask:0xf bank_mask:0xf bound_ctrl:1
	v_add_f32_dpp v132, v132, v132 row_half_mirror row_mask:0xf bank_mask:0xf bound_ctrl:1
	v_add_f32_dpp v134, v134, v134 row_half_mirror row_mask:0xf bank_mask:0xf bound_ctrl:1
	s_nop 1
	v_pk_fma_f32 v[184:185], v[120:121], v[160:161], v[184:185]
	v_add_f32_dpp v132, v132, v132 row_mirror row_mask:0xf bank_mask:0xf bound_ctrl:1
	v_add_f32_dpp v134, v134, v134 row_mirror row_mask:0xf bank_mask:0xf bound_ctrl:1
	v_add_f32_dpp v110, v110, v110 row_half_mirror row_mask:0xf bank_mask:0xf bound_ctrl:1
	v_pk_fma_f32 v[186:187], v[122:123], v[162:163], v[186:187]
	v_pk_fma_f32 v[116:117], v[168:169], v[132:133], v[136:137] op_sel_hi:[1,0,1] neg_lo:[1,0,0] neg_hi:[1,0,0]
	v_pk_fma_f32 v[118:119], v[170:171], v[132:133], v[182:183] op_sel_hi:[1,0,1] neg_lo:[1,0,0] neg_hi:[1,0,0]
	s_nop 1
	v_pk_fma_f32 v[120:121], v[168:169], v[134:135], v[184:185] op_sel_hi:[1,0,1] neg_lo:[1,0,0] neg_hi:[1,0,0]
	v_pk_fma_f32 v[122:123], v[170:171], v[134:135], v[186:187] op_sel_hi:[1,0,1] neg_lo:[1,0,0] neg_hi:[1,0,0]
	v_pk_mul_f32 v[188:189], v[116:117], v[176:177]
	v_add_f32_dpp v110, v110, v110 row_mirror row_mask:0xf bank_mask:0xf bound_ctrl:1
	v_pk_mul_f32 v[190:191], v[120:121], v[176:177]
	v_pk_fma_f32 v[188:189], v[118:119], v[178:179], v[188:189]
	v_add_f32_e32 v110, 0x2b8cbccc, v110
	v_pk_fma_f32 v[190:191], v[122:123], v[178:179], v[190:191]
	v_add_f32_e32 v246, v188, v189
	v_add_f32_e32 v247, v190, v191
	v_mul_f32_e32 v201, 0x4b800000, v110
	ds_write_b64 v159, v[246:247] offset:52224
	ds_read_b128 v[164:167], v244 offset:5984
	ds_read_b128 v[160:163], v244 offset:1632
	v_cmp_gt_f32_e32 vcc, s53, v110
	ds_read_b128 v[172:175], v244 offset:14688
	ds_read_b128 v[168:171], v244 offset:10336
	s_nop 1
	ds_read_b128 v[176:179], v244 offset:19040
	ds_read_b64 v[180:181], v245 offset:23392
	s_waitcnt lgkmcnt(10)
	v_cndmask_b32_e32 v110, v110, v201, vcc
	v_pk_mul_f32 v[128:129], v[116:117], v[226:227]
	v_pk_mul_f32 v[130:131], v[120:121], v[226:227]
	v_pk_fma_f32 v[128:129], v[118:119], v[228:229], v[128:129]
	v_rsq_f32_e32 v110, v110
	v_pk_fma_f32 v[130:131], v[122:123], v[228:229], v[130:131]
	v_pk_mul_f32 v[136:137], v[234:235], v[242:243] op_sel_hi:[1,0]
	v_pk_mul_f32 v[182:183], v[236:237], v[242:243] op_sel_hi:[1,0]
	s_nop 0
	v_add_f32_e32 v132, v128, v129
	v_add_f32_e32 v134, v130, v131
	v_mul_f32_e32 v201, 0x45800000, v110
	v_pk_mul_f32 v[184:185], v[234:235], v[242:243] op_sel:[0,1]
	v_pk_mul_f32 v[186:187], v[236:237], v[242:243] op_sel:[0,1]
	v_add_f32_dpp v132, v132, v132 quad_perm:[1,0,3,2] row_mask:0xf bank_mask:0xf bound_ctrl:1
	v_cndmask_b32_e32 v110, v110, v201, vcc
	v_add_f32_dpp v134, v134, v134 quad_perm:[1,0,3,2] row_mask:0xf bank_mask:0xf bound_ctrl:1
	v_pk_fma_f32 v[136:137], v[116:117], v[222:223], v[136:137]
	v_add_f32_dpp v132, v132, v132 quad_perm:[2,3,0,1] row_mask:0xf bank_mask:0xf bound_ctrl:1
	v_pk_mul_f32 v[204:205], v[218:219], v[110:111] op_sel_hi:[1,0]
	v_add_f32_dpp v134, v134, v134 quad_perm:[2,3,0,1] row_mask:0xf bank_mask:0xf bound_ctrl:1
	v_pk_fma_f32 v[182:183], v[118:119], v[224:225], v[182:183]
	v_pk_mul_f32 v[202:203], v[214:215], v[110:111] op_sel_hi:[1,0]
	v_add_f32_dpp v132, v132, v132 row_half_mirror row_mask:0xf bank_mask:0xf bound_ctrl:1
	v_add_f32_dpp v134, v134, v134 row_half_mirror row_mask:0xf bank_mask:0xf bound_ctrl:1
	v_pk_fma_f32 v[184:185], v[120:121], v[222:223], v[184:185]
	ds_write_b128 v100, v[202:205] offset:4352
	v_add_f32_dpp v132, v132, v132 row_mirror row_mask:0xf bank_mask:0xf bound_ctrl:1
	v_add_f32_dpp v134, v134, v134 row_mirror row_mask:0xf bank_mask:0xf bound_ctrl:1
	v_pk_fma_f32 v[186:187], v[122:123], v[224:225], v[186:187]
	s_nop 0
	v_pk_fma_f32 v[116:117], v[230:231], v[132:133], v[136:137] op_sel_hi:[1,0,1] neg_lo:[1,0,0] neg_hi:[1,0,0]
	v_pk_fma_f32 v[118:119], v[232:233], v[132:133], v[182:183] op_sel_hi:[1,0,1] neg_lo:[1,0,0] neg_hi:[1,0,0]
	v_pk_fma_f32 v[120:121], v[230:231], v[134:135], v[184:185] op_sel_hi:[1,0,1] neg_lo:[1,0,0] neg_hi:[1,0,0]
	v_mfma_f32_16x16x32_bf16 v[202:205], v[6:9], v[66:69], v[206:209]
	v_pk_fma_f32 v[122:123], v[232:233], v[134:135], v[186:187] op_sel_hi:[1,0,1] neg_lo:[1,0,0] neg_hi:[1,0,0]
	v_pk_mul_f32 v[188:189], v[116:117], v[238:239]
	s_waitcnt lgkmcnt(0)
	s_barrier
; DI float red16(float x) { x = red8(x); x += dppf<0x140>(x); return x; }
; DI void scan_task(const Params& p, int l, int b, int h, int dir, int half, char* lds) {
;     ...
;   auto issue_loads = [&](int c) {
;     const int slo = chunk_lo(c);
;     const int s = slo + st_p;
;     const bool hasprev = (s != 0 && s != NCTX), hasnext = (s != NCTX - 1 && s != TB - 1);
;     const bf16_t* pa = p.PA + (size_t)(b * TB + s) * LDPA + hc + c4 * 4;
;     const int op = hasprev ? -LDPA : 0, on = hasnext ? LDPA : 0;
;     mprev = hasprev ? 1.f : 0.f; mnext = hasnext ? 1.f : 0.f;
; #pragma unroll
;     for (int sec = 0; sec < 3; ++sec) {
;       ld[sec][1] = *(const u32x2*)(pa + sec * 384);
;       ld[sec][0] = *(const u32x2*)(pa + sec * 384 + op);
;       ld[sec][2] = *(const u32x2*)(pa + sec * 384 + on);
;     }
;     const size_t trow = (size_t)(b * TB + slo + fr) * 64;
; #pragma unroll
;     ...
;       for (int ii = 0; ii < 16; ++ii) {
;         f32x4 nw = cw, nkk = ckk, nbb = cbb, nkd = ckd, nrr = crr; f32x2 nvv = cvv;
;         if (ii < 15) {
;           ps += inc; pv += inc;
;           nw = *(const f32x4*)(ps + VW * CP); nkk = *(const f32x4*)(ps + VKK * CP); nbb = *(const f32x4*)(ps + VB * CP);
;           nkd = *(const f32x4*)(ps + VKD * CP); nrr = *(const f32x4*)(ps + VR * CP); nvv = *(const f32x2*)pv;
;         }
;         __builtin_amdgcn_sched_barrier(0x7);
;         const f32x2 kk0 = {ckk[0], ckk[1]}, kk1 = {ckk[2], ckk[3]}, w0 = {cw[0], cw[1]}, w1 = {cw[2], cw[3]};
;         const f32x2 b0 = {cbb[0], cbb[1]}, b1 = {cbb[2], cbb[3]}, kd0 = {ckd[0], ckd[1]}, kd1 = {ckd[2], ckd[3]};
;         const f32x2 r0 = {crr[0], crr[1]}, r1 = {crr[2], crr[3]};
;         const f32x2 p0 = S0[0] * kk0 + S0[1] * kk1, p1 = S1[0] * kk0 + S1[1] * kk1;
;         const f32x2 u00 = S0[0] * w0 + kd0 * cvv[0], u01 = S0[1] * w1 + kd1 * cvv[0];
;         const f32x2 u10 = S1[0] * w0 + kd0 * cvv[1], u11 = S1[1] * w1 + kd1 * cvv[1];
;         const float q0 = red16(p0[0] + p0[1]), q1 = red16(p1[0] + p1[1]);
;         S0[0] = u00 - b0 * q0; S0[1] = u01 - b1 * q0;
;         S1[0] = u10 - b0 * q1; S1[1] = u11 - b1 * q1;
;         const f32x2 y0 = S0[0] * r0 + S0[1] * r1, y1 = S1[0] * r0 + S1[1] * r1;
;         *(f32x2*)py = (f32x2){y0[0] + y0[1], y1[0] + y1[1]};
;         py += dir ? -512 : 512;
;         cw = nw; ckk = nkk; cbb = nbb; ckd = nkd; crr = nrr; cvv = nvv;
;       }
	v_pk_mul_f32 v[190:191], v[120:121], v[238:239]
	v_pk_fma_f32 v[188:189], v[118:119], v[240:241], v[188:189]
	v_pk_fma_f32 v[190:191], v[122:123], v[240:241], v[190:191]
	s_nop 0
	v_add_f32_e32 v246, v188, v189
	v_add_f32_e32 v247, v190, v191
	ds_write_b64 v159, v[246:247] offset:54272
	v_mfma_f32_16x16x32_bf16 v[206:209], v[10:13], v[70:73], 0
	ds_read_b128 v[226:229], v244 offset:6256
	ds_read_b128 v[222:225], v244 offset:1904
	ds_read_b128 v[210:213], v97 offset:13056
	ds_read_b128 v[234:237], v244 offset:14960
	ds_read_b128 v[230:233], v244 offset:10608
	ds_read_b128 v[238:241], v244 offset:19312
	ds_read_b128 v[214:217], v97 offset:4352
	ds_read_b64 v[242:243], v245 offset:23664
	v_pk_mul_f32 v[128:129], v[116:117], v[164:165]
	s_nop 1
	v_pk_mul_f32 v[130:131], v[120:121], v[164:165]
	v_pk_fma_f32 v[128:129], v[118:119], v[166:167], v[128:129]
	v_pk_fma_f32 v[130:131], v[122:123], v[166:167], v[130:131]
	v_add_f32_e32 v110, v50, v202
	v_pk_mul_f32 v[136:137], v[172:173], v[180:181] op_sel_hi:[1,0]
	v_pk_mul_f32 v[182:183], v[174:175], v[180:181] op_sel_hi:[1,0]
	v_mul_f32_e32 v110, 0xbfb8aa3b, v110
	v_add_f32_e32 v132, v128, v129
	v_add_f32_e32 v134, v130, v131
	v_pk_mul_f32 v[184:185], v[172:173], v[180:181] op_sel:[0,1]
	v_exp_f32_e32 v110, v110
	v_pk_mul_f32 v[186:187], v[174:175], v[180:181] op_sel:[0,1]
	v_add_f32_dpp v132, v132, v132 quad_perm:[1,0,3,2] row_mask:0xf bank_mask:0xf bound_ctrl:1
	v_add_f32_dpp v134, v134, v134 quad_perm:[1,0,3,2] row_mask:0xf bank_mask:0xf bound_ctrl:1
	s_nop 0
	v_pk_fma_f32 v[136:137], v[116:117], v[160:161], v[136:137]
	v_add_f32_dpp v132, v132, v132 quad_perm:[2,3,0,1] row_mask:0xf bank_mask:0xf bound_ctrl:1
	v_mfma_f32_16x16x32_bf16 v[206:209], v[14:17], v[74:77], v[206:209]
	v_add_f32_dpp v134, v134, v134 quad_perm:[2,3,0,1] row_mask:0xf bank_mask:0xf bound_ctrl:1
	v_pk_fma_f32 v[182:183], v[118:119], v[162:163], v[182:183]
	v_add_f32_dpp v132, v132, v132 row_half_mirror row_mask:0xf bank_mask:0xf bound_ctrl:1
	v_mov_b32_e32 v249, 0
	v_add_f32_dpp v134, v134, v134 row_half_mirror row_mask:0xf bank_mask:0xf bound_ctrl:1
	v_pk_fma_f32 v[184:185], v[120:121], v[160:161], v[184:185]
	v_add_f32_dpp v132, v132, v132 row_mirror row_mask:0xf bank_mask:0xf bound_ctrl:1
	s_nop 0
	v_add_f32_dpp v134, v134, v134 row_mirror row_mask:0xf bank_mask:0xf bound_ctrl:1
	v_pk_fma_f32 v[186:187], v[122:123], v[162:163], v[186:187]
	v_pk_fma_f32 v[116:117], v[168:169], v[132:133], v[136:137] op_sel_hi:[1,0,1] neg_lo:[1,0,0] neg_hi:[1,0,0]
	v_add_u32_e32 v62, s28, v1
	v_pk_fma_f32 v[118:119], v[170:171], v[132:133], v[182:183] op_sel_hi:[1,0,1] neg_lo:[1,0,0] neg_hi:[1,0,0]
	v_pk_fma_f32 v[120:121], v[168:169], v[134:135], v[184:185] op_sel_hi:[1,0,1] neg_lo:[1,0,0] neg_hi:[1,0,0]
	v_readlane_b32 s0, v252, 48
	v_pk_fma_f32 v[122:123], v[170:171], v[134:135], v[186:187] op_sel_hi:[1,0,1] neg_lo:[1,0,0] neg_hi:[1,0,0]
	v_pk_mul_f32 v[188:189], v[116:117], v[176:177]
	v_pk_mul_f32 v[190:191], v[120:121], v[176:177]
	v_and_b32_e32 v64, 0xfffffeff, v62
	v_pk_fma_f32 v[188:189], v[118:119], v[178:179], v[188:189]
	v_pk_fma_f32 v[190:191], v[122:123], v[178:179], v[190:191]
	v_add_f32_e32 v246, v188, v189
	s_nop 0
	v_add_f32_e32 v247, v190, v191
	ds_write_b64 v159, v[246:247] offset:56320
	ds_read_b128 v[164:167], v244 offset:6528
	v_and_b32_e32 v66, 0xfffff7ff, v62
	ds_read_b128 v[160:163], v244 offset:2176
	ds_read_b128 v[172:175], v244 offset:15232
	v_add_u32_e32 v62, s0, v62
	ds_read_b128 v[168:171], v244 offset:10880
	ds_read_b128 v[176:179], v244 offset:19584
	ds_read_b64 v[180:181], v245 offset:23936
	s_movk_i32 s0, 0xb00
	s_waitcnt lgkmcnt(7)
	v_pk_mul_f32 v[128:129], v[116:117], v[226:227]
	v_pk_mul_f32 v[130:131], v[120:121], v[226:227]
	v_mad_i64_i32 v[62:63], s[0:1], v62, s0, v[102:103]
	v_pk_fma_f32 v[128:129], v[118:119], v[228:229], v[128:129]
	v_pk_fma_f32 v[130:131], v[122:123], v[228:229], v[130:131]
	v_cmp_eq_u32_e32 vcc, 0, v64
	v_pk_mul_f32 v[136:137], v[234:235], v[242:243] op_sel_hi:[1,0]
	v_pk_mul_f32 v[182:183], v[236:237], v[242:243] op_sel_hi:[1,0]
	v_add_f32_e32 v132, v128, v129
	v_cmp_eq_u32_e64 s[0:1], s33, v66
	v_add_f32_e32 v134, v130, v131
	v_pk_mul_f32 v[184:185], v[234:235], v[242:243] op_sel:[0,1]
	v_pk_mul_f32 v[186:187], v[236:237], v[242:243] op_sel:[0,1]
	s_nop 0
	v_add_f32_dpp v132, v132, v132 quad_perm:[1,0,3,2] row_mask:0xf bank_mask:0xf bound_ctrl:1
	v_add_f32_dpp v134, v134, v134 quad_perm:[1,0,3,2] row_mask:0xf bank_mask:0xf bound_ctrl:1
	v_pk_fma_f32 v[136:137], v[116:117], v[222:223], v[136:137]
	v_cndmask_b32_e64 v65, -1, 0, vcc
	v_add_f32_dpp v132, v132, v132 quad_perm:[2,3,0,1] row_mask:0xf bank_mask:0xf bound_ctrl:1
	v_add_f32_dpp v134, v134, v134 quad_perm:[2,3,0,1] row_mask:0xf bank_mask:0xf bound_ctrl:1
	v_cndmask_b32_e64 v64, v150, 0, vcc
	v_pk_fma_f32 v[182:183], v[118:119], v[224:225], v[182:183]
	v_add_f32_dpp v132, v132, v132 row_half_mirror row_mask:0xf bank_mask:0xf bound_ctrl:1
	v_add_f32_dpp v134, v134, v134 row_half_mirror row_mask:0xf bank_mask:0xf bound_ctrl:1
	v_cndmask_b32_e64 v248, v151, 0, s[0:1]
	v_pk_fma_f32 v[184:185], v[120:121], v[222:223], v[184:185]
	v_add_f32_dpp v132, v132, v132 row_mirror row_mask:0xf bank_mask:0xf bound_ctrl:1
	v_add_f32_dpp v134, v134, v134 row_mirror row_mask:0xf bank_mask:0xf bound_ctrl:1
	v_lshl_add_u64 v[64:65], v[62:63], 0, v[64:65]
	v_pk_fma_f32 v[186:187], v[122:123], v[224:225], v[186:187]
	v_pk_fma_f32 v[116:117], v[230:231], v[132:133], v[136:137] op_sel_hi:[1,0,1] neg_lo:[1,0,0] neg_hi:[1,0,0]
	v_lshl_add_u64 v[66:67], v[62:63], 0, v[248:249]
	v_pk_fma_f32 v[118:119], v[232:233], v[132:133], v[182:183] op_sel_hi:[1,0,1] neg_lo:[1,0,0] neg_hi:[1,0,0]
	v_pk_fma_f32 v[120:121], v[230:231], v[134:135], v[184:185] op_sel_hi:[1,0,1] neg_lo:[1,0,0] neg_hi:[1,0,0]
	v_pk_fma_f32 v[122:123], v[232:233], v[134:135], v[186:187] op_sel_hi:[1,0,1] neg_lo:[1,0,0] neg_hi:[1,0,0]
	global_load_dwordx2 v[78:79], v[62:63], off
	v_pk_mul_f32 v[188:189], v[116:117], v[238:239]
	v_pk_mul_f32 v[190:191], v[120:121], v[238:239]
	v_pk_fma_f32 v[188:189], v[118:119], v[240:241], v[188:189]
	global_load_dwordx2 v[80:81], v[64:65], off
	v_pk_fma_f32 v[190:191], v[122:123], v[240:241], v[190:191]
	v_add_f32_e32 v246, v188, v189
	v_add_f32_e32 v247, v190, v191
	global_load_dwordx2 v[82:83], v[62:63], off offset:768
	ds_write_b64 v159, v[246:247] offset:58368
	ds_read_b128 v[192:195], v124 offset:52224
	global_load_dwordx2 v[86:87], v[62:63], off offset:1536
	ds_read_b128 v[196:199], v124 offset:52240
	s_mul_i32 s20, s26, 7
	s_add_i32 s20, s20, 4
	global_load_dwordx2 v[84:85], v[66:67], off
	s_add_i32 s20, s20, s27
	s_add_i32 s20, s20, s100
	s_mulk_i32 s20, 0x600
	global_load_dwordx2 v[88:89], v[64:65], off offset:768
	s_waitcnt lgkmcnt(0)
; DI float sigmoidf_(float x) { return __builtin_amdgcn_rcpf(1.f + __expf(-x)); }
; DI void scan_task(const Params& p, int l, int b, int h, int dir, int half, char* lds) {
;     ...
;   auto issue_loads = [&](int c) {
;     const int slo = chunk_lo(c);
;     const int s = slo + st_p;
;     const bool hasprev = (s != 0 && s != NCTX), hasnext = (s != NCTX - 1 && s != TB - 1);
;     const bf16_t* pa = p.PA + (size_t)(b * TB + s) * LDPA + hc + c4 * 4;
;     const int op = hasprev ? -LDPA : 0, on = hasnext ? LDPA : 0;
;     mprev = hasprev ? 1.f : 0.f; mnext = hasnext ? 1.f : 0.f;
; #pragma unroll
;     for (int sec = 0; sec < 3; ++sec) {
;       ld[sec][1] = *(const u32x2*)(pa + sec * 384);
;       ld[sec][0] = *(const u32x2*)(pa + sec * 384 + op);
;       ld[sec][2] = *(const u32x2*)(pa + sec * 384 + on);
;     }
;     const size_t trow = (size_t)(b * TB + slo + fr) * 64;
; #pragma unroll
;     for (int ks = 0; ks < 2; ++ks) { aw[ks] = *(const bf16x8*)(p.TW + trow + ks * 32 + fq * 8); aa[ks] = *(const bf16x8*)(p.TA + trow + ks * 32 + fq * 8); }
;     ...
; #pragma unroll
;       for (int j = 0; j < 4; ++j) {
;         wv[j] = __expf(-LOG_DECAY_SCALE * sigmoidf_(w0[j] + dw[j]));
;         const float a = sigmoidf_(a0[j] + da[j]);
;         kdv[j] = kv[j] * (1.f + (a - 1.f) * kag[j]);
;         bv[j] = kkv[j] * a;
;       }
	v_pk_add_f32 v[192:193], v[192:193], v[194:195]
	global_load_dwordx2 v[90:91], v[66:67], off offset:768
	v_pk_add_f32 v[196:197], v[196:197], v[198:199]
	v_add_u32_e32 v125, s20, v200
	v_pk_add_f32 v[192:193], v[192:193], v[196:197]
	global_load_dwordx2 v[92:93], v[64:65], off offset:1536
	s_nop 1
	v_add_f32_dpp v192, v192, v192 quad_perm:[1,0,3,2] row_mask:0xf bank_mask:0xf bound_ctrl:1
	v_add_f32_dpp v193, v193, v193 quad_perm:[1,0,3,2] row_mask:0xf bank_mask:0xf bound_ctrl:1
	global_load_dwordx2 v[94:95], v[66:67], off offset:1536
	s_nop 0
	v_add_f32_dpp v192, v192, v192 quad_perm:[2,3,0,1] row_mask:0xf bank_mask:0xf bound_ctrl:1
	v_add_f32_dpp v193, v193, v193 quad_perm:[2,3,0,1] row_mask:0xf bank_mask:0xf bound_ctrl:1
	v_add_u32_e32 v62, s28, v127
	global_store_dwordx2 v125, v[192:193], s[98:99]
	ds_read_b128 v[226:229], v244 offset:6800
	v_ashrrev_i32_e32 v63, 31, v62
	ds_read_b128 v[222:225], v244 offset:2448
	ds_read_b128 v[234:237], v244 offset:15504
	ds_read_b128 v[230:233], v244 offset:11152
	v_lshlrev_b64 v[62:63], 7, v[62:63]
	ds_read_b128 v[238:241], v244 offset:19856
	ds_read_b64 v[242:243], v245 offset:24208
	v_lshl_add_u64 v[66:67], v[106:107], 0, v[62:63]
	v_pk_mul_f32 v[128:129], v[116:117], v[164:165]
	v_pk_mul_f32 v[130:131], v[120:121], v[164:165]
	s_nop 0
	v_pk_fma_f32 v[128:129], v[118:119], v[166:167], v[128:129]
	v_pk_fma_f32 v[130:131], v[122:123], v[166:167], v[130:131]
	v_pk_mul_f32 v[136:137], v[172:173], v[180:181] op_sel_hi:[1,0]
	v_lshl_add_u64 v[74:75], v[108:109], 0, v[62:63]
	v_pk_mul_f32 v[182:183], v[174:175], v[180:181] op_sel_hi:[1,0]
	v_add_f32_e32 v132, v128, v129
	v_add_f32_e32 v134, v130, v131
	global_load_dwordx4 v[62:65], v[66:67], off
	v_pk_mul_f32 v[184:185], v[172:173], v[180:181] op_sel:[0,1]
	v_pk_mul_f32 v[186:187], v[174:175], v[180:181] op_sel:[0,1]
	v_add_f32_dpp v132, v132, v132 quad_perm:[1,0,3,2] row_mask:0xf bank_mask:0xf bound_ctrl:1
	s_nop 0
	v_add_f32_dpp v134, v134, v134 quad_perm:[1,0,3,2] row_mask:0xf bank_mask:0xf bound_ctrl:1
	v_pk_fma_f32 v[136:137], v[116:117], v[160:161], v[136:137]
	global_load_dwordx4 v[66:69], v[66:67], off offset:64
	v_add_f32_dpp v132, v132, v132 quad_perm:[2,3,0,1] row_mask:0xf bank_mask:0xf bound_ctrl:1
	v_add_f32_dpp v134, v134, v134 quad_perm:[2,3,0,1] row_mask:0xf bank_mask:0xf bound_ctrl:1
	v_pk_fma_f32 v[182:183], v[118:119], v[162:163], v[182:183]
	s_nop 0
	v_add_f32_dpp v132, v132, v132 row_half_mirror row_mask:0xf bank_mask:0xf bound_ctrl:1
	v_add_f32_dpp v134, v134, v134 row_half_mirror row_mask:0xf bank_mask:0xf bound_ctrl:1
	v_pk_fma_f32 v[184:185], v[120:121], v[160:161], v[184:185]
	global_load_dwordx4 v[70:73], v[74:75], off
	v_add_f32_dpp v132, v132, v132 row_mirror row_mask:0xf bank_mask:0xf bound_ctrl:1
	v_add_f32_dpp v134, v134, v134 row_mirror row_mask:0xf bank_mask:0xf bound_ctrl:1
	v_pk_fma_f32 v[186:187], v[122:123], v[162:163], v[186:187]
	s_nop 0
	v_pk_fma_f32 v[116:117], v[168:169], v[132:133], v[136:137] op_sel_hi:[1,0,1] neg_lo:[1,0,0] neg_hi:[1,0,0]
	v_pk_fma_f32 v[118:119], v[170:171], v[132:133], v[182:183] op_sel_hi:[1,0,1] neg_lo:[1,0,0] neg_hi:[1,0,0]
	global_load_dwordx4 v[74:77], v[74:75], off offset:64
	v_pk_fma_f32 v[120:121], v[168:169], v[134:135], v[184:185] op_sel_hi:[1,0,1] neg_lo:[1,0,0] neg_hi:[1,0,0]
	v_pk_fma_f32 v[122:123], v[170:171], v[134:135], v[186:187] op_sel_hi:[1,0,1] neg_lo:[1,0,0] neg_hi:[1,0,0]
	v_pk_mul_f32 v[188:189], v[116:117], v[176:177]
	v_cndmask_b32_e64 v96, 1.0, 0, vcc
	v_pk_mul_f32 v[190:191], v[120:121], v[176:177]
	v_pk_fma_f32 v[188:189], v[118:119], v[178:179], v[188:189]
	v_pk_fma_f32 v[190:191], v[122:123], v[178:179], v[190:191]
	v_cndmask_b32_e64 v98, 1.0, 0, s[0:1]
	v_add_f32_e32 v246, v188, v189
	v_add_f32_e32 v247, v190, v191
	v_add_f32_e32 v201, v51, v203
	ds_write_b64 v159, v[246:247] offset:52224
	ds_read_b128 v[164:167], v244 offset:7072
	ds_read_b128 v[160:163], v244 offset:2720
	v_mul_f32_e32 v201, 0xbfb8aa3b, v201
	ds_read_b128 v[172:175], v244 offset:15776
	ds_read_b128 v[168:171], v244 offset:11424
	ds_read_b128 v[176:179], v244 offset:20128
	v_exp_f32_e32 v201, v201
	ds_read_b64 v[180:181], v245 offset:24480
	s_waitcnt lgkmcnt(7)
	v_pk_mul_f32 v[128:129], v[116:117], v[226:227]
	v_add_f32_e32 v110, 1.0, v110
	v_pk_mul_f32 v[130:131], v[120:121], v[226:227]
	v_pk_fma_f32 v[128:129], v[118:119], v[228:229], v[128:129]
	v_rcp_f32_e32 v110, v110
	v_pk_fma_f32 v[130:131], v[122:123], v[228:229], v[130:131]
	v_pk_mul_f32 v[136:137], v[234:235], v[242:243] op_sel_hi:[1,0]
	v_pk_mul_f32 v[182:183], v[236:237], v[242:243] op_sel_hi:[1,0]
	s_nop 2
	v_add_f32_e32 v132, v128, v129
	v_add_f32_e32 v134, v130, v131
	v_pk_mul_f32 v[184:185], v[234:235], v[242:243] op_sel:[0,1]
	v_add_f32_e32 v202, v54, v206
	v_pk_mul_f32 v[186:187], v[236:237], v[242:243] op_sel:[0,1]
	v_add_f32_dpp v132, v132, v132 quad_perm:[1,0,3,2] row_mask:0xf bank_mask:0xf bound_ctrl:1
	v_mul_f32_e32 v202, 0xbfb8aa3b, v202
	v_add_f32_dpp v134, v134, v134 quad_perm:[1,0,3,2] row_mask:0xf bank_mask:0xf bound_ctrl:1
	v_pk_fma_f32 v[136:137], v[116:117], v[222:223], v[136:137]
	v_add_f32_dpp v132, v132, v132 quad_perm:[2,3,0,1] row_mask:0xf bank_mask:0xf bound_ctrl:1
	v_exp_f32_e32 v203, v202
	v_add_f32_dpp v134, v134, v134 quad_perm:[2,3,0,1] row_mask:0xf bank_mask:0xf bound_ctrl:1
	v_pk_fma_f32 v[182:183], v[118:119], v[224:225], v[182:183]
	v_add_f32_dpp v132, v132, v132 row_half_mirror row_mask:0xf bank_mask:0xf bound_ctrl:1
	v_add_f32_e32 v201, 1.0, v201
	v_add_f32_dpp v134, v134, v134 row_half_mirror row_mask:0xf bank_mask:0xf bound_ctrl:1
	v_pk_fma_f32 v[184:185], v[120:121], v[222:223], v[184:185]
; DI float sigmoidf_(float x) { return __builtin_amdgcn_rcpf(1.f + __expf(-x)); }
; DI float red16(float x) { x = red8(x); x += dppf<0x140>(x); return x; }
; DI void scan_task(const Params& p, int l, int b, int h, int dir, int half, char* lds) {
;     ...
; #pragma unroll
;       for (int j = 0; j < 4; ++j) {
;         wv[j] = __expf(-LOG_DECAY_SCALE * sigmoidf_(w0[j] + dw[j]));
;         const float a = sigmoidf_(a0[j] + da[j]);
;         kdv[j] = kv[j] * (1.f + (a - 1.f) * kag[j]);
;         bv[j] = kkv[j] * a;
;       }
;     ...
;       for (int ii = 0; ii < 16; ++ii) {
;         f32x4 nw = cw, nkk = ckk, nbb = cbb, nkd = ckd, nrr = crr; f32x2 nvv = cvv;
;         if (ii < 15) {
;           ps += inc; pv += inc;
;           nw = *(const f32x4*)(ps + VW * CP); nkk = *(const f32x4*)(ps + VKK * CP); nbb = *(const f32x4*)(ps + VB * CP);
;           nkd = *(const f32x4*)(ps + VKD * CP); nrr = *(const f32x4*)(ps + VR * CP); nvv = *(const f32x2*)pv;
;         }
;         __builtin_amdgcn_sched_barrier(0x7);
;         const f32x2 kk0 = {ckk[0], ckk[1]}, kk1 = {ckk[2], ckk[3]}, w0 = {cw[0], cw[1]}, w1 = {cw[2], cw[3]};
;         const f32x2 b0 = {cbb[0], cbb[1]}, b1 = {cbb[2], cbb[3]}, kd0 = {ckd[0], ckd[1]}, kd1 = {ckd[2], ckd[3]};
;         const f32x2 r0 = {crr[0], crr[1]}, r1 = {crr[2], crr[3]};
;         const f32x2 p0 = S0[0] * kk0 + S0[1] * kk1, p1 = S1[0] * kk0 + S1[1] * kk1;
;         const f32x2 u00 = S0[0] * w0 + kd0 * cvv[0], u01 = S0[1] * w1 + kd1 * cvv[0];
;         const f32x2 u10 = S1[0] * w0 + kd0 * cvv[1], u11 = S1[1] * w1 + kd1 * cvv[1];
;         const float q0 = red16(p0[0] + p0[1]), q1 = red16(p1[0] + p1[1]);
;         S0[0] = u00 - b0 * q0; S0[1] = u01 - b1 * q0;
;         S1[0] = u10 - b0 * q1; S1[1] = u11 - b1 * q1;
;         const f32x2 y0 = S0[0] * r0 + S0[1] * r1, y1 = S1[0] * r0 + S1[1] * r1;
;         *(f32x2*)py = (f32x2){y0[0] + y0[1], y1[0] + y1[1]};
;         py += dir ? -512 : 512;
;         cw = nw; ckk = nkk; cbb = nbb; ckd = nkd; crr = nrr; cvv = nvv;
;       }
	v_add_f32_dpp v132, v132, v132 row_mirror row_mask:0xf bank_mask:0xf bound_ctrl:1
	v_rcp_f32_e32 v201, v201
	v_add_f32_dpp v134, v134, v134 row_mirror row_mask:0xf bank_mask:0xf bound_ctrl:1
	v_pk_fma_f32 v[186:187], v[122:123], v[224:225], v[186:187]
	v_mul_f32_e32 v110, 0xbf1b459e, v110
	v_pk_fma_f32 v[116:117], v[230:231], v[132:133], v[136:137] op_sel_hi:[1,0,1] neg_lo:[1,0,0] neg_hi:[1,0,0]
	v_pk_fma_f32 v[118:119], v[232:233], v[132:133], v[182:183] op_sel_hi:[1,0,1] neg_lo:[1,0,0] neg_hi:[1,0,0]
	v_pk_fma_f32 v[120:121], v[230:231], v[134:135], v[184:185] op_sel_hi:[1,0,1] neg_lo:[1,0,0] neg_hi:[1,0,0]
	v_mul_f32_e32 v110, 0x3fb8aa3b, v110
	v_pk_fma_f32 v[122:123], v[232:233], v[134:135], v[186:187] op_sel_hi:[1,0,1] neg_lo:[1,0,0] neg_hi:[1,0,0]
	v_pk_mul_f32 v[188:189], v[116:117], v[238:239]
	v_pk_mul_f32 v[190:191], v[120:121], v[238:239]
	v_exp_f32_e32 v202, v110
	v_pk_fma_f32 v[188:189], v[118:119], v[240:241], v[188:189]
	v_pk_fma_f32 v[190:191], v[122:123], v[240:241], v[190:191]
	v_add_f32_e32 v110, 1.0, v203
	v_add_f32_e32 v246, v188, v189
	v_add_f32_e32 v247, v190, v191
	ds_write_b64 v159, v[246:247] offset:54272
	v_rcp_f32_e32 v218, v110
	ds_read_b128 v[226:229], v244 offset:7344
	ds_read_b128 v[222:225], v244 offset:2992
	ds_read_b128 v[234:237], v244 offset:16048
	v_mul_f32_e32 v110, 0xbf1b459e, v201
	ds_read_b128 v[230:233], v244 offset:11696
	ds_read_b128 v[238:241], v244 offset:20400
	ds_read_b64 v[242:243], v245 offset:24752
	v_add_f32_e32 v201, v52, v204
	s_waitcnt lgkmcnt(7)
	v_pk_mul_f32 v[128:129], v[116:117], v[164:165]
	v_mul_f32_e32 v201, 0xbfb8aa3b, v201
	v_pk_mul_f32 v[130:131], v[120:121], v[164:165]
	v_pk_fma_f32 v[128:129], v[118:119], v[166:167], v[128:129]
	v_pk_fma_f32 v[130:131], v[122:123], v[166:167], v[130:131]
	v_exp_f32_e32 v201, v201
	v_pk_mul_f32 v[136:137], v[172:173], v[180:181] op_sel_hi:[1,0]
	v_pk_mul_f32 v[182:183], v[174:175], v[180:181] op_sel_hi:[1,0]
	v_add_f32_e32 v132, v128, v129
	v_add_f32_e32 v203, v55, v207
	v_add_f32_e32 v134, v130, v131
	v_pk_mul_f32 v[184:185], v[172:173], v[180:181] op_sel:[0,1]
	v_mul_f32_e32 v203, 0xbfb8aa3b, v203
	v_pk_mul_f32 v[186:187], v[174:175], v[180:181] op_sel:[0,1]
	v_add_f32_dpp v132, v132, v132 quad_perm:[1,0,3,2] row_mask:0xf bank_mask:0xf bound_ctrl:1
	v_add_f32_dpp v134, v134, v134 quad_perm:[1,0,3,2] row_mask:0xf bank_mask:0xf bound_ctrl:1
	v_exp_f32_e32 v204, v203
	v_pk_fma_f32 v[136:137], v[116:117], v[160:161], v[136:137]
	v_add_f32_dpp v132, v132, v132 quad_perm:[2,3,0,1] row_mask:0xf bank_mask:0xf bound_ctrl:1
	v_add_f32_dpp v134, v134, v134 quad_perm:[2,3,0,1] row_mask:0xf bank_mask:0xf bound_ctrl:1
	v_add_f32_e32 v201, 1.0, v201
	v_pk_fma_f32 v[182:183], v[118:119], v[162:163], v[182:183]
	v_add_f32_dpp v132, v132, v132 row_half_mirror row_mask:0xf bank_mask:0xf bound_ctrl:1
	v_add_f32_dpp v134, v134, v134 row_half_mirror row_mask:0xf bank_mask:0xf bound_ctrl:1
	v_rcp_f32_e32 v201, v201
	v_pk_fma_f32 v[184:185], v[120:121], v[160:161], v[184:185]
	v_add_f32_dpp v132, v132, v132 row_mirror row_mask:0xf bank_mask:0xf bound_ctrl:1
	v_mul_f32_e32 v110, 0x3fb8aa3b, v110
	v_add_f32_dpp v134, v134, v134 row_mirror row_mask:0xf bank_mask:0xf bound_ctrl:1
	v_pk_fma_f32 v[186:187], v[122:123], v[162:163], v[186:187]
	v_pk_fma_f32 v[116:117], v[168:169], v[132:133], v[136:137] op_sel_hi:[1,0,1] neg_lo:[1,0,0] neg_hi:[1,0,0]
	v_exp_f32_e32 v203, v110
	v_pk_fma_f32 v[118:119], v[170:171], v[132:133], v[182:183] op_sel_hi:[1,0,1] neg_lo:[1,0,0] neg_hi:[1,0,0]
	v_pk_fma_f32 v[120:121], v[168:169], v[134:135], v[184:185] op_sel_hi:[1,0,1] neg_lo:[1,0,0] neg_hi:[1,0,0]
	v_pk_fma_f32 v[122:123], v[170:171], v[134:135], v[186:187] op_sel_hi:[1,0,1] neg_lo:[1,0,0] neg_hi:[1,0,0]
	v_add_f32_e32 v110, 1.0, v204
	v_pk_mul_f32 v[188:189], v[116:117], v[176:177]
	v_pk_mul_f32 v[190:191], v[120:121], v[176:177]
	v_rcp_f32_e32 v219, v110
	v_pk_fma_f32 v[188:189], v[118:119], v[178:179], v[188:189]
	v_pk_fma_f32 v[190:191], v[122:123], v[178:179], v[190:191]
	v_add_f32_e32 v246, v188, v189
	v_mul_f32_e32 v110, 0xbf1b459e, v201
	v_add_f32_e32 v247, v190, v191
	ds_write_b64 v159, v[246:247] offset:56320
	ds_read_b128 v[164:167], v244 offset:7616
	v_mul_f32_e32 v110, 0x3fb8aa3b, v110
	ds_read_b128 v[160:163], v244 offset:3264
	ds_read_b128 v[172:175], v244 offset:16320
	ds_read_b128 v[168:171], v244 offset:11968
	v_exp_f32_e32 v204, v110
	ds_read_b128 v[176:179], v244 offset:20672
	ds_read_b64 v[180:181], v245 offset:25024
	v_add_f32_e32 v110, v53, v205
	s_waitcnt lgkmcnt(7)
; DI float sigmoidf_(float x) { return __builtin_amdgcn_rcpf(1.f + __expf(-x)); }
; DI void scan_task(const Params& p, int l, int b, int h, int dir, int half, char* lds) {
;     ...
; #pragma unroll
;       for (int j = 0; j < 4; ++j) {
;         wv[j] = __expf(-LOG_DECAY_SCALE * sigmoidf_(w0[j] + dw[j]));
;         const float a = sigmoidf_(a0[j] + da[j]);
;         kdv[j] = kv[j] * (1.f + (a - 1.f) * kag[j]);
;         bv[j] = kkv[j] * a;
;       }
;       *(f32x4*)(cb + VW * CP + fr * CS + colB) = wv;
;       *(f32x4*)(cb + VKD * CP + fr * CS + colB) = kdv;
;       *(f32x4*)(cb + VB * CP + fr * CS + colB) = bv;
;     ...
;     {
;       const int slo = chunk_lo(c);
;       const float* yp = ybuf + (st_p * 16 + c4) * 32;
;       f32x4 a = *(const f32x4*)(yp + 4 * (c4 & 7));
; #pragma unroll
;       for (int i = 1; i < 8; ++i) a += *(const f32x4*)(yp + 4 * ((i + c4) & 7));
;       *(f32x2*)(p.Y + (size_t)dir * T_TOK * 384 + (size_t)(b * TB + slo + st_p) * 384 + hc + half * 32 + c4 * 2) = (f32x2){a[0] + a[2], a[1] + a[3]};
	v_pk_mul_f32 v[128:129], v[116:117], v[226:227]
	v_pk_mul_f32 v[130:131], v[120:121], v[226:227]
	v_mul_f32_e32 v110, 0xbfb8aa3b, v110
	v_pk_fma_f32 v[128:129], v[118:119], v[228:229], v[128:129]
	v_pk_fma_f32 v[130:131], v[122:123], v[228:229], v[130:131]
	v_pk_mul_f32 v[136:137], v[234:235], v[242:243] op_sel_hi:[1,0]
	v_exp_f32_e32 v110, v110
	v_pk_mul_f32 v[182:183], v[236:237], v[242:243] op_sel_hi:[1,0]
	v_add_f32_e32 v132, v128, v129
	v_add_f32_e32 v134, v130, v131
	v_add_f32_e32 v201, v56, v208
	v_pk_mul_f32 v[184:185], v[234:235], v[242:243] op_sel:[0,1]
	v_pk_mul_f32 v[186:187], v[236:237], v[242:243] op_sel:[0,1]
	v_mul_f32_e32 v201, 0xbfb8aa3b, v201
	v_add_f32_dpp v132, v132, v132 quad_perm:[1,0,3,2] row_mask:0xf bank_mask:0xf bound_ctrl:1
	v_add_f32_dpp v134, v134, v134 quad_perm:[1,0,3,2] row_mask:0xf bank_mask:0xf bound_ctrl:1
	v_pk_fma_f32 v[136:137], v[116:117], v[222:223], v[136:137]
	v_add_f32_e32 v205, v57, v209
	v_add_f32_dpp v132, v132, v132 quad_perm:[2,3,0,1] row_mask:0xf bank_mask:0xf bound_ctrl:1
	v_add_f32_dpp v134, v134, v134 quad_perm:[2,3,0,1] row_mask:0xf bank_mask:0xf bound_ctrl:1
	v_pk_fma_f32 v[182:183], v[118:119], v[224:225], v[182:183]
	v_exp_f32_e32 v201, v201
	v_add_f32_dpp v132, v132, v132 row_half_mirror row_mask:0xf bank_mask:0xf bound_ctrl:1
	v_add_f32_dpp v134, v134, v134 row_half_mirror row_mask:0xf bank_mask:0xf bound_ctrl:1
	v_mul_f32_e32 v205, 0xbfb8aa3b, v205
	v_pk_fma_f32 v[184:185], v[120:121], v[222:223], v[184:185]
	v_add_f32_dpp v132, v132, v132 row_mirror row_mask:0xf bank_mask:0xf bound_ctrl:1
	v_add_f32_dpp v134, v134, v134 row_mirror row_mask:0xf bank_mask:0xf bound_ctrl:1
	v_exp_f32_e32 v205, v205
	v_pk_fma_f32 v[186:187], v[122:123], v[224:225], v[186:187]
	v_pk_fma_f32 v[116:117], v[230:231], v[132:133], v[136:137] op_sel_hi:[1,0,1] neg_lo:[1,0,0] neg_hi:[1,0,0]
	v_pk_fma_f32 v[118:119], v[232:233], v[132:133], v[182:183] op_sel_hi:[1,0,1] neg_lo:[1,0,0] neg_hi:[1,0,0]
	v_add_f32_e32 v110, 1.0, v110
	v_pk_fma_f32 v[120:121], v[230:231], v[134:135], v[184:185] op_sel_hi:[1,0,1] neg_lo:[1,0,0] neg_hi:[1,0,0]
	v_pk_fma_f32 v[122:123], v[232:233], v[134:135], v[186:187] op_sel_hi:[1,0,1] neg_lo:[1,0,0] neg_hi:[1,0,0]
	v_pk_mul_f32 v[188:189], v[116:117], v[238:239]
	v_rcp_f32_e32 v110, v110
	v_pk_mul_f32 v[190:191], v[120:121], v[238:239]
	v_pk_fma_f32 v[188:189], v[118:119], v[240:241], v[188:189]
	v_add_f32_e32 v201, 1.0, v201
	v_pk_fma_f32 v[190:191], v[122:123], v[240:241], v[190:191]
	v_add_f32_e32 v246, v188, v189
	v_add_f32_e32 v247, v190, v191
	v_rcp_f32_e32 v220, v201
	ds_write_b64 v159, v[246:247] offset:58368
	ds_read_b128 v[192:195], v124 offset:52224
	ds_read_b128 v[196:199], v124 offset:52240
	v_add_f32_e32 v201, 1.0, v205
	s_mul_i32 s20, s26, -1
	s_add_i32 s20, s20, 8
	v_rcp_f32_e32 v221, v201
	s_add_i32 s20, s20, s27
	s_add_i32 s20, s20, s100
	s_mulk_i32 s20, 0x600
	v_mul_f32_e32 v110, 0xbf1b459e, v110
	s_waitcnt lgkmcnt(0)
	v_pk_add_f32 v[192:193], v[192:193], v[194:195]
	v_pk_add_f32 v[196:197], v[196:197], v[198:199]
	v_mul_f32_e32 v110, 0x3fb8aa3b, v110
	v_add_u32_e32 v125, s20, v200
	v_pk_add_f32 v[192:193], v[192:193], v[196:197]
	s_nop 1
	v_exp_f32_e32 v205, v110
	v_add_f32_dpp v192, v192, v192 quad_perm:[1,0,3,2] row_mask:0xf bank_mask:0xf bound_ctrl:1
	v_add_f32_dpp v193, v193, v193 quad_perm:[1,0,3,2] row_mask:0xf bank_mask:0xf bound_ctrl:1
	v_pk_add_f32 v[206:207], v[218:219], -1.0 op_sel_hi:[1,0]
	s_nop 0
	v_add_f32_dpp v192, v192, v192 quad_perm:[2,3,0,1] row_mask:0xf bank_mask:0xf bound_ctrl:1
	v_add_f32_dpp v193, v193, v193 quad_perm:[2,3,0,1] row_mask:0xf bank_mask:0xf bound_ctrl:1
	v_pk_add_f32 v[208:209], v[220:221], -1.0 op_sel_hi:[1,0]
	global_store_dwordx2 v125, v[192:193], s[98:99]
	ds_read_b128 v[226:229], v244 offset:7888
	ds_read_b128 v[222:225], v244 offset:3536
	v_pk_fma_f32 v[206:207], v[58:59], v[206:207], 1.0 op_sel_hi:[1,1,0]
	ds_read_b128 v[234:237], v244 offset:16592
	ds_read_b128 v[230:233], v244 offset:12240
	v_pk_fma_f32 v[208:209], v[60:61], v[208:209], 1.0 op_sel_hi:[1,1,0]
	ds_read_b128 v[238:241], v244 offset:20944
	ds_read_b64 v[242:243], v245 offset:25296
	v_pk_mul_f32 v[128:129], v[116:117], v[164:165]
	v_pk_mul_f32 v[130:131], v[120:121], v[164:165]
	v_pk_fma_f32 v[128:129], v[118:119], v[166:167], v[128:129]
	v_pk_mul_f32 v[206:207], v[210:211], v[206:207]
	v_pk_fma_f32 v[130:131], v[122:123], v[166:167], v[130:131]
	v_pk_mul_f32 v[136:137], v[172:173], v[180:181] op_sel_hi:[1,0]
	v_pk_mul_f32 v[182:183], v[174:175], v[180:181] op_sel_hi:[1,0]
	v_pk_mul_f32 v[208:209], v[212:213], v[208:209]
	v_add_f32_e32 v132, v128, v129
	v_add_f32_e32 v134, v130, v131
	v_pk_mul_f32 v[184:185], v[172:173], v[180:181] op_sel:[0,1]
	v_pk_mul_f32 v[186:187], v[174:175], v[180:181] op_sel:[0,1]
	v_add_f32_dpp v132, v132, v132 quad_perm:[1,0,3,2] row_mask:0xf bank_mask:0xf bound_ctrl:1
	v_pk_mul_f32 v[210:211], v[214:215], v[218:219]
	v_add_f32_dpp v134, v134, v134 quad_perm:[1,0,3,2] row_mask:0xf bank_mask:0xf bound_ctrl:1
	v_pk_fma_f32 v[136:137], v[116:117], v[160:161], v[136:137]
	v_add_f32_dpp v132, v132, v132 quad_perm:[2,3,0,1] row_mask:0xf bank_mask:0xf bound_ctrl:1
	v_pk_mul_f32 v[212:213], v[216:217], v[220:221]
	v_add_f32_dpp v134, v134, v134 quad_perm:[2,3,0,1] row_mask:0xf bank_mask:0xf bound_ctrl:1
	v_pk_fma_f32 v[182:183], v[118:119], v[162:163], v[182:183]
	ds_write_b128 v97, v[202:205]
	v_add_f32_dpp v132, v132, v132 row_half_mirror row_mask:0xf bank_mask:0xf bound_ctrl:1
	v_add_f32_dpp v134, v134, v134 row_half_mirror row_mask:0xf bank_mask:0xf bound_ctrl:1
	v_pk_fma_f32 v[184:185], v[120:121], v[160:161], v[184:185]
	ds_write_b128 v97, v[206:209] offset:13056
	v_add_f32_dpp v132, v132, v132 row_mirror row_mask:0xf bank_mask:0xf bound_ctrl:1
	v_add_f32_dpp v134, v134, v134 row_mirror row_mask:0xf bank_mask:0xf bound_ctrl:1
	v_pk_fma_f32 v[186:187], v[122:123], v[162:163], v[186:187]
	ds_write_b128 v97, v[210:213] offset:8704
	v_pk_fma_f32 v[116:117], v[168:169], v[132:133], v[136:137] op_sel_hi:[1,0,1] neg_lo:[1,0,0] neg_hi:[1,0,0]
	v_pk_fma_f32 v[118:119], v[170:171], v[132:133], v[182:183] op_sel_hi:[1,0,1] neg_lo:[1,0,0] neg_hi:[1,0,0]
	v_pk_fma_f32 v[120:121], v[168:169], v[134:135], v[184:185] op_sel_hi:[1,0,1] neg_lo:[1,0,0] neg_hi:[1,0,0]
	s_waitcnt lgkmcnt(0)
	s_barrier
; DI float red16(float x) { x = red8(x); x += dppf<0x140>(x); return x; }
; DI void scan_task(const Params& p, int l, int b, int h, int dir, int half, char* lds) {
;     ...
;     __syncthreads();
;     {
;       const f32x4 rv = *(const f32x4*)(cb + VR * CP + st_p * CS + c4 * 4);
;       const f32x4 kdv = *(const f32x4*)(cb + VKD * CP + st_p * CS + c4 * 4);
;       float bs = rv[0] * kdv[0] * rkg[0] + rv[1] * kdv[1] * rkg[1] + rv[2] * kdv[2] * rkg[2] + rv[3] * kdv[3] * rkg[3];
;       bs = red16(bs);
;       if (c4 == 0 && half == 0) p.BON[(size_t)dir * T_TOK * 6 + (size_t)(b * TB + slo + st_p) * 6 + h] = bs;
;     }
;     ...
;       for (int ii = 0; ii < 16; ++ii) {
;         f32x4 nw = cw, nkk = ckk, nbb = cbb, nkd = ckd, nrr = crr; f32x2 nvv = cvv;
;         if (ii < 15) {
;           ps += inc; pv += inc;
;           nw = *(const f32x4*)(ps + VW * CP); nkk = *(const f32x4*)(ps + VKK * CP); nbb = *(const f32x4*)(ps + VB * CP);
;           nkd = *(const f32x4*)(ps + VKD * CP); nrr = *(const f32x4*)(ps + VR * CP); nvv = *(const f32x2*)pv;
;         }
;         __builtin_amdgcn_sched_barrier(0x7);
;         const f32x2 kk0 = {ckk[0], ckk[1]}, kk1 = {ckk[2], ckk[3]}, w0 = {cw[0], cw[1]}, w1 = {cw[2], cw[3]};
;         const f32x2 b0 = {cbb[0], cbb[1]}, b1 = {cbb[2], cbb[3]}, kd0 = {ckd[0], ckd[1]}, kd1 = {ckd[2], ckd[3]};
;         const f32x2 r0 = {crr[0], crr[1]}, r1 = {crr[2], crr[3]};
;         const f32x2 p0 = S0[0] * kk0 + S0[1] * kk1, p1 = S1[0] * kk0 + S1[1] * kk1;
;         const f32x2 u00 = S0[0] * w0 + kd0 * cvv[0], u01 = S0[1] * w1 + kd1 * cvv[0];
;         const f32x2 u10 = S1[0] * w0 + kd0 * cvv[1], u11 = S1[1] * w1 + kd1 * cvv[1];
;         const float q0 = red16(p0[0] + p0[1]), q1 = red16(p1[0] + p1[1]);
;         S0[0] = u00 - b0 * q0; S0[1] = u01 - b1 * q0;
;         S1[0] = u10 - b0 * q1; S1[1] = u11 - b1 * q1;
;         const f32x2 y0 = S0[0] * r0 + S0[1] * r1, y1 = S1[0] * r0 + S1[1] * r1;
;         *(f32x2*)py = (f32x2){y0[0] + y0[1], y1[0] + y1[1]};
;         py += dir ? -512 : 512;
;         cw = nw; ckk = nkk; cbb = nbb; ckd = nkd; crr = nrr; cvv = nvv;
;       }
	v_pk_fma_f32 v[122:123], v[170:171], v[134:135], v[186:187] op_sel_hi:[1,0,1] neg_lo:[1,0,0] neg_hi:[1,0,0]
	v_pk_mul_f32 v[188:189], v[116:117], v[176:177]
	ds_read_b128 v[202:205], v100 offset:17408
	v_pk_mul_f32 v[190:191], v[120:121], v[176:177]
	v_pk_fma_f32 v[188:189], v[118:119], v[178:179], v[188:189]
	v_pk_fma_f32 v[190:191], v[122:123], v[178:179], v[190:191]
	ds_read_b128 v[206:209], v100 offset:13056
	v_add_f32_e32 v246, v188, v189
	v_add_f32_e32 v247, v190, v191
	ds_write_b64 v159, v[246:247] offset:52224
	s_waitcnt lgkmcnt(1)
	ds_read_b128 v[164:167], v244 offset:8160
	ds_read_b128 v[160:163], v244 offset:3808
	ds_read_b128 v[172:175], v244 offset:16864
	v_mul_f32_e32 v201, v203, v207
	ds_read_b128 v[168:171], v244 offset:12512
	ds_read_b128 v[176:179], v244 offset:21216
	v_mul_f32_e32 v110, v202, v206
	ds_read_b64 v[180:181], v245 offset:25568
	v_pk_mul_f32 v[128:129], v[116:117], v[226:227]
	v_mul_f32_e32 v201, v47, v201
	v_pk_mul_f32 v[130:131], v[120:121], v[226:227]
	v_pk_fma_f32 v[128:129], v[118:119], v[228:229], v[128:129]
	v_pk_fma_f32 v[130:131], v[122:123], v[228:229], v[130:131]
	v_fmac_f32_e32 v201, v46, v110
	v_pk_mul_f32 v[136:137], v[234:235], v[242:243] op_sel_hi:[1,0]
	v_pk_mul_f32 v[182:183], v[236:237], v[242:243] op_sel_hi:[1,0]
	v_mul_f32_e32 v110, v204, v208
	v_add_f32_e32 v132, v128, v129
	v_add_f32_e32 v134, v130, v131
	v_pk_mul_f32 v[184:185], v[234:235], v[242:243] op_sel:[0,1]
	v_fmac_f32_e32 v201, v48, v110
	v_pk_mul_f32 v[186:187], v[236:237], v[242:243] op_sel:[0,1]
	v_add_f32_dpp v132, v132, v132 quad_perm:[1,0,3,2] row_mask:0xf bank_mask:0xf bound_ctrl:1
	v_add_f32_dpp v134, v134, v134 quad_perm:[1,0,3,2] row_mask:0xf bank_mask:0xf bound_ctrl:1
	v_mul_f32_e32 v110, v205, v209
	v_pk_fma_f32 v[136:137], v[116:117], v[222:223], v[136:137]
	v_add_f32_dpp v132, v132, v132 quad_perm:[2,3,0,1] row_mask:0xf bank_mask:0xf bound_ctrl:1
	v_add_f32_dpp v134, v134, v134 quad_perm:[2,3,0,1] row_mask:0xf bank_mask:0xf bound_ctrl:1
	v_fmac_f32_e32 v201, v49, v110
	v_pk_fma_f32 v[182:183], v[118:119], v[224:225], v[182:183]
	v_add_f32_dpp v132, v132, v132 row_half_mirror row_mask:0xf bank_mask:0xf bound_ctrl:1
	s_nop 1
	v_add_f32_dpp v134, v134, v134 row_half_mirror row_mask:0xf bank_mask:0xf bound_ctrl:1
	v_pk_fma_f32 v[184:185], v[120:121], v[222:223], v[184:185]
	v_add_f32_dpp v132, v132, v132 row_mirror row_mask:0xf bank_mask:0xf bound_ctrl:1
	v_add_f32_dpp v110, v201, v201 quad_perm:[1,0,3,2] row_mask:0xf bank_mask:0xf bound_ctrl:1
	v_add_f32_dpp v134, v134, v134 row_mirror row_mask:0xf bank_mask:0xf bound_ctrl:1
	v_pk_fma_f32 v[186:187], v[122:123], v[224:225], v[186:187]
	v_pk_fma_f32 v[116:117], v[230:231], v[132:133], v[136:137] op_sel_hi:[1,0,1] neg_lo:[1,0,0] neg_hi:[1,0,0]
	s_nop 1
	v_pk_fma_f32 v[118:119], v[232:233], v[132:133], v[182:183] op_sel_hi:[1,0,1] neg_lo:[1,0,0] neg_hi:[1,0,0]
	v_pk_fma_f32 v[120:121], v[230:231], v[134:135], v[184:185] op_sel_hi:[1,0,1] neg_lo:[1,0,0] neg_hi:[1,0,0]
	v_add_f32_dpp v110, v110, v110 quad_perm:[2,3,0,1] row_mask:0xf bank_mask:0xf bound_ctrl:1
	v_pk_fma_f32 v[122:123], v[232:233], v[134:135], v[186:187] op_sel_hi:[1,0,1] neg_lo:[1,0,0] neg_hi:[1,0,0]
	v_pk_mul_f32 v[188:189], v[116:117], v[238:239]
	v_pk_mul_f32 v[190:191], v[120:121], v[238:239]
	s_nop 1
	v_pk_fma_f32 v[188:189], v[118:119], v[240:241], v[188:189]
	v_pk_fma_f32 v[190:191], v[122:123], v[240:241], v[190:191]
	v_add_f32_e32 v246, v188, v189
	v_add_f32_dpp v110, v110, v110 row_half_mirror row_mask:0xf bank_mask:0xf bound_ctrl:1
	v_add_f32_e32 v247, v190, v191
	ds_write_b64 v159, v[246:247] offset:54272
	ds_read_b128 v[226:229], v244 offset:8432
	s_nop 1
	ds_read_b128 v[222:225], v244 offset:4080
	ds_read_b128 v[234:237], v244 offset:17136
	v_mov_b32_dpp v201, v110 row_mirror row_mask:0xf bank_mask:0xf bound_ctrl:1
	ds_read_b128 v[230:233], v244 offset:12784
	ds_read_b128 v[238:241], v244 offset:21488
	ds_read_b64 v[242:243], v245 offset:25840
	s_mov_b32 s2, s29
	s_and_saveexec_b64 s[0:1], s[36:37]
	v_add_f32_e32 v110, v110, v201
	v_add_u32_e32 v201, s2, v126
	v_readlane_b32 s2, v252, 50
	v_readlane_b32 s3, v252, 51
	s_nop 1
	v_mad_i64_i32 v[202:203], s[2:3], v201, 24, s[2:3]
	global_store_dword v[202:203], v110, off
	s_or_b64 exec, exec, s[0:1]
	s_nop 1
	s_waitcnt lgkmcnt(7)
; DI float red16(float x) { x = red8(x); x += dppf<0x140>(x); return x; }
; DI void scan_task(const Params& p, int l, int b, int h, int dir, int half, char* lds) {
;     ...
;       for (int ii = 0; ii < 16; ++ii) {
;         f32x4 nw = cw, nkk = ckk, nbb = cbb, nkd = ckd, nrr = crr; f32x2 nvv = cvv;
;         if (ii < 15) {
;           ps += inc; pv += inc;
;           nw = *(const f32x4*)(ps + VW * CP); nkk = *(const f32x4*)(ps + VKK * CP); nbb = *(const f32x4*)(ps + VB * CP);
;           nkd = *(const f32x4*)(ps + VKD * CP); nrr = *(const f32x4*)(ps + VR * CP); nvv = *(const f32x2*)pv;
;         }
;         __builtin_amdgcn_sched_barrier(0x7);
;         const f32x2 kk0 = {ckk[0], ckk[1]}, kk1 = {ckk[2], ckk[3]}, w0 = {cw[0], cw[1]}, w1 = {cw[2], cw[3]};
;         const f32x2 b0 = {cbb[0], cbb[1]}, b1 = {cbb[2], cbb[3]}, kd0 = {ckd[0], ckd[1]}, kd1 = {ckd[2], ckd[3]};
;         const f32x2 r0 = {crr[0], crr[1]}, r1 = {crr[2], crr[3]};
;         const f32x2 p0 = S0[0] * kk0 + S0[1] * kk1, p1 = S1[0] * kk0 + S1[1] * kk1;
;         const f32x2 u00 = S0[0] * w0 + kd0 * cvv[0], u01 = S0[1] * w1 + kd1 * cvv[0];
;         const f32x2 u10 = S1[0] * w0 + kd0 * cvv[1], u11 = S1[1] * w1 + kd1 * cvv[1];
;         const float q0 = red16(p0[0] + p0[1]), q1 = red16(p1[0] + p1[1]);
;         S0[0] = u00 - b0 * q0; S0[1] = u01 - b1 * q0;
;         S1[0] = u10 - b0 * q1; S1[1] = u11 - b1 * q1;
;         const f32x2 y0 = S0[0] * r0 + S0[1] * r1, y1 = S1[0] * r0 + S1[1] * r1;
;         *(f32x2*)py = (f32x2){y0[0] + y0[1], y1[0] + y1[1]};
;         py += dir ? -512 : 512;
;         cw = nw; ckk = nkk; cbb = nbb; ckd = nkd; crr = nrr; cvv = nvv;
;       }
;     }
;     __syncthreads();
;     {
;       const int slo = chunk_lo(c);
;       const float* yp = ybuf + (st_p * 16 + c4) * 32;
;       f32x4 a = *(const f32x4*)(yp + 4 * (c4 & 7));
; #pragma unroll
;       for (int i = 1; i < 8; ++i) a += *(const f32x4*)(yp + 4 * ((i + c4) & 7));
;       *(f32x2*)(p.Y + (size_t)dir * T_TOK * 384 + (size_t)(b * TB + slo + st_p) * 384 + hc + half * 32 + c4 * 2) = (f32x2){a[0] + a[2], a[1] + a[3]};
;     }
;     if (c + 1 < NCH) produce(c + 1);
; template <int KSEL> DI void run_phase(const Params& p, int ph, char* lds) {
;     ...
;       if (KSEL != 11) { if (bid < 192) { scan_task(p, l, bid / 24, (bid % 24) >> 2, (bid >> 1) & 1, bid & 1, lds); break; } if (KSEL == 4) break; }
	v_pk_mul_f32 v[128:129], v[116:117], v[164:165]
	v_pk_mul_f32 v[130:131], v[120:121], v[164:165]
	v_pk_fma_f32 v[128:129], v[118:119], v[166:167], v[128:129]
	v_pk_fma_f32 v[130:131], v[122:123], v[166:167], v[130:131]
	v_pk_mul_f32 v[136:137], v[172:173], v[180:181] op_sel_hi:[1,0]
	v_pk_mul_f32 v[182:183], v[174:175], v[180:181] op_sel_hi:[1,0]
	v_add_f32_e32 v132, v128, v129
	v_add_f32_e32 v134, v130, v131
	v_pk_mul_f32 v[184:185], v[172:173], v[180:181] op_sel:[0,1]
	v_pk_mul_f32 v[186:187], v[174:175], v[180:181] op_sel:[0,1]
	v_add_f32_dpp v132, v132, v132 quad_perm:[1,0,3,2] row_mask:0xf bank_mask:0xf bound_ctrl:1
	v_add_f32_dpp v134, v134, v134 quad_perm:[1,0,3,2] row_mask:0xf bank_mask:0xf bound_ctrl:1
	v_pk_fma_f32 v[136:137], v[116:117], v[160:161], v[136:137]
	v_add_f32_dpp v132, v132, v132 quad_perm:[2,3,0,1] row_mask:0xf bank_mask:0xf bound_ctrl:1
	v_add_f32_dpp v134, v134, v134 quad_perm:[2,3,0,1] row_mask:0xf bank_mask:0xf bound_ctrl:1
	v_pk_fma_f32 v[182:183], v[118:119], v[162:163], v[182:183]
	v_add_f32_dpp v132, v132, v132 row_half_mirror row_mask:0xf bank_mask:0xf bound_ctrl:1
	v_add_f32_dpp v134, v134, v134 row_half_mirror row_mask:0xf bank_mask:0xf bound_ctrl:1
	v_pk_fma_f32 v[184:185], v[120:121], v[160:161], v[184:185]
	v_add_f32_dpp v132, v132, v132 row_mirror row_mask:0xf bank_mask:0xf bound_ctrl:1
	v_add_f32_dpp v134, v134, v134 row_mirror row_mask:0xf bank_mask:0xf bound_ctrl:1
	v_pk_fma_f32 v[186:187], v[122:123], v[162:163], v[186:187]
	v_pk_fma_f32 v[116:117], v[168:169], v[132:133], v[136:137] op_sel_hi:[1,0,1] neg_lo:[1,0,0] neg_hi:[1,0,0]
	v_pk_fma_f32 v[118:119], v[170:171], v[132:133], v[182:183] op_sel_hi:[1,0,1] neg_lo:[1,0,0] neg_hi:[1,0,0]
	v_pk_fma_f32 v[120:121], v[168:169], v[134:135], v[184:185] op_sel_hi:[1,0,1] neg_lo:[1,0,0] neg_hi:[1,0,0]
	v_pk_fma_f32 v[122:123], v[170:171], v[134:135], v[186:187] op_sel_hi:[1,0,1] neg_lo:[1,0,0] neg_hi:[1,0,0]
	v_pk_mul_f32 v[188:189], v[116:117], v[176:177]
	v_pk_mul_f32 v[190:191], v[120:121], v[176:177]
	v_pk_fma_f32 v[188:189], v[118:119], v[178:179], v[188:189]
	v_pk_fma_f32 v[190:191], v[122:123], v[178:179], v[190:191]
	v_add_f32_e32 v246, v188, v189
	v_add_f32_e32 v247, v190, v191
	ds_write_b64 v159, v[246:247] offset:56320
	v_add_u32_e32 v244, s101, v244
	v_add_u32_e32 v245, s101, v245
	ds_read_b128 v[164:167], v244 offset:4352
	ds_read_b128 v[160:163], v244 offset:0
	ds_read_b128 v[172:175], v244 offset:13056
	ds_read_b128 v[168:171], v244 offset:8704
	ds_read_b128 v[176:179], v244 offset:17408
	ds_read_b64 v[180:181], v245 offset:21760
	s_waitcnt lgkmcnt(7)
	v_pk_mul_f32 v[128:129], v[116:117], v[226:227]
	v_pk_mul_f32 v[130:131], v[120:121], v[226:227]
	v_pk_fma_f32 v[128:129], v[118:119], v[228:229], v[128:129]
	v_pk_fma_f32 v[130:131], v[122:123], v[228:229], v[130:131]
	v_pk_mul_f32 v[136:137], v[234:235], v[242:243] op_sel_hi:[1,0]
	v_pk_mul_f32 v[182:183], v[236:237], v[242:243] op_sel_hi:[1,0]
	v_add_f32_e32 v132, v128, v129
	v_add_f32_e32 v134, v130, v131
	v_pk_mul_f32 v[184:185], v[234:235], v[242:243] op_sel:[0,1]
	v_pk_mul_f32 v[186:187], v[236:237], v[242:243] op_sel:[0,1]
	v_add_f32_dpp v132, v132, v132 quad_perm:[1,0,3,2] row_mask:0xf bank_mask:0xf bound_ctrl:1
	v_add_f32_dpp v134, v134, v134 quad_perm:[1,0,3,2] row_mask:0xf bank_mask:0xf bound_ctrl:1
	v_pk_fma_f32 v[136:137], v[116:117], v[222:223], v[136:137]
	v_add_f32_dpp v132, v132, v132 quad_perm:[2,3,0,1] row_mask:0xf bank_mask:0xf bound_ctrl:1
	v_add_f32_dpp v134, v134, v134 quad_perm:[2,3,0,1] row_mask:0xf bank_mask:0xf bound_ctrl:1
	v_pk_fma_f32 v[182:183], v[118:119], v[224:225], v[182:183]
	v_add_f32_dpp v132, v132, v132 row_half_mirror row_mask:0xf bank_mask:0xf bound_ctrl:1
	v_add_f32_dpp v134, v134, v134 row_half_mirror row_mask:0xf bank_mask:0xf bound_ctrl:1
	v_pk_fma_f32 v[184:185], v[120:121], v[222:223], v[184:185]
	v_add_f32_dpp v132, v132, v132 row_mirror row_mask:0xf bank_mask:0xf bound_ctrl:1
	v_add_f32_dpp v134, v134, v134 row_mirror row_mask:0xf bank_mask:0xf bound_ctrl:1
	v_pk_fma_f32 v[186:187], v[122:123], v[224:225], v[186:187]
	v_pk_fma_f32 v[116:117], v[230:231], v[132:133], v[136:137] op_sel_hi:[1,0,1] neg_lo:[1,0,0] neg_hi:[1,0,0]
	v_pk_fma_f32 v[118:119], v[232:233], v[132:133], v[182:183] op_sel_hi:[1,0,1] neg_lo:[1,0,0] neg_hi:[1,0,0]
	v_pk_fma_f32 v[120:121], v[230:231], v[134:135], v[184:185] op_sel_hi:[1,0,1] neg_lo:[1,0,0] neg_hi:[1,0,0]
	v_pk_fma_f32 v[122:123], v[232:233], v[134:135], v[186:187] op_sel_hi:[1,0,1] neg_lo:[1,0,0] neg_hi:[1,0,0]
	v_pk_mul_f32 v[188:189], v[116:117], v[238:239]
	v_pk_mul_f32 v[190:191], v[120:121], v[238:239]
	v_pk_fma_f32 v[188:189], v[118:119], v[240:241], v[188:189]
	v_pk_fma_f32 v[190:191], v[122:123], v[240:241], v[190:191]
	v_add_f32_e32 v246, v188, v189
	v_add_f32_e32 v247, v190, v191
	ds_write_b64 v159, v[246:247] offset:58368
	ds_read_b128 v[192:195], v124 offset:52224
	ds_read_b128 v[196:199], v124 offset:52240
	s_mul_i32 s20, s26, -9
	s_add_i32 s20, s20, 12
	s_add_i32 s20, s20, s27
	s_add_i32 s20, s20, s100
	s_mulk_i32 s20, 0x600
	s_waitcnt lgkmcnt(0)
	v_pk_add_f32 v[192:193], v[192:193], v[194:195]
	v_pk_add_f32 v[196:197], v[196:197], v[198:199]
	v_add_u32_e32 v125, s20, v200
	v_pk_add_f32 v[192:193], v[192:193], v[196:197]
	s_nop 1
	v_add_f32_dpp v192, v192, v192 quad_perm:[1,0,3,2] row_mask:0xf bank_mask:0xf bound_ctrl:1
	v_add_f32_dpp v193, v193, v193 quad_perm:[1,0,3,2] row_mask:0xf bank_mask:0xf bound_ctrl:1
	s_nop 0
	v_add_f32_dpp v192, v192, v192 quad_perm:[2,3,0,1] row_mask:0xf bank_mask:0xf bound_ctrl:1
	v_add_f32_dpp v193, v193, v193 quad_perm:[2,3,0,1] row_mask:0xf bank_mask:0xf bound_ctrl:1
	global_store_dwordx2 v125, v[192:193], s[98:99]
	s_barrier
	v_subrev_u32_e32 v100, s101, v100
	v_subrev_u32_e32 v97, s101, v97
	s_sub_i32 s101, 0, s101
	s_mov_b32 s100, s29
	s_mov_b32 s29, s28
	s_add_i32 s38, s38, 1
	s_cmpk_lg_i32 s38, 0x90
	s_cbranch_scc1 .Lscan_loop
	v_readlane_b32 s49, v250, 7
	s_nop 3
	s_branch .Lscan_joins_queue

; #define LAS __attribute__((address_space(3)))
; template <class Epi>
; DI void gemm_tile(const bf16_t* __restrict__ A, int lda, const bf16_t* __restrict__ Bt, int ldb, int K, int row0, int col0, char* lds, const Epi& epi) {
;   const int tid = opaque_tid(), lane = tid & 63, wid = tid >> 6, wr = wid >> 1, wc = wid & 1, fr = lane & 15, fq = lane >> 4;
;   const bf16_t* ag[4];
;   const bf16_t* bg[4];
; #pragma unroll
;   for (int i = 0; i < 4; ++i) {
;     const int id = i * 256 + tid, r = id >> 3, cp = id & 7, c = cp ^ ((r >> 1) & 7);
;     ag[i] = A + (size_t)(row0 + r) * lda + c * 8;
;     bg[i] = Bt + (size_t)(col0 + r) * ldb + c * 8;
;   }
;   f32x4 acc[4][4];
; #pragma unroll
;   for (int m = 0; m < 4; ++m)
; #pragma unroll
;     for (int n = 0; n < 4; ++n) acc[m][n] = (f32x4){0.f, 0.f, 0.f, 0.f};
;   const int KT = K >> 6;
;   auto stage_a = [&](int kt, int buf) {
;     char* sa = lds + buf * 32768;
; #pragma unroll
;     for (int i = 0; i < 4; ++i)
;       __builtin_amdgcn_global_load_lds((const void __attribute__((address_space(1)))*)(ag[i] + kt * 64), (void LAS*)(sa + (i * 256 + tid) * 16), 16, 0, 0);
;   };
;   auto stage_b = [&](int kt, int buf) {
;     char* sb = lds + buf * 32768 + 16384;
; #pragma unroll
;     for (int i = 0; i < 4; ++i)
;       __builtin_amdgcn_global_load_lds((const void __attribute__((address_space(1)))*)(bg[i] + kt * 64), (void LAS*)(sb + (i * 256 + tid) * 16), 16, 0, 0);
;   };
;   __syncthreads();
;   stage_a(0, 0); stage_b(0, 0);
;   const int swz = fr >> 1;
;   for (int kt = 0; kt < KT; ++kt) {
;     asm volatile("s_waitcnt vmcnt(0)" ::: "memory");
;     __syncthreads();
;     const char* sa = lds + (kt & 1) * 32768 + (wr * 64 + fr) * 128;
;     const char* sb = lds + (kt & 1) * 32768 + 16384 + (wc * 64 + fr) * 128;
; #pragma unroll
;     for (int kk = 0; kk < 2; ++kk) {
;       if (kt + 1 < KT) { if (kk == 0) stage_a(kt + 1, (kt + 1) & 1); else stage_b(kt + 1, (kt + 1) & 1); }
;       bf16x8 a[4], b[4];
;       const int co = ((kk * 4 + fq) ^ swz) * 16;
; #pragma unroll
;       for (int m = 0; m < 4; ++m) a[m] = *(const bf16x8*)(sa + m * 2048 + co);
; #pragma unroll
;       for (int n = 0; n < 4; ++n) b[n] = *(const bf16x8*)(sb + n * 2048 + co);
; template <int KSEL> DI void run_phase(const Params& p, int ph, char* lds) {
;     ...
;           const int t = (int)*slot;
;           if (t >= nq + 864) break;
.LBB0_518:
	s_or_b64 exec, exec, s[0:1]
	s_waitcnt lgkmcnt(0)
	s_barrier
	ds_read_b32 v1, v145
	s_mov_b64 s[0:1], -1
	s_waitcnt lgkmcnt(0)
	v_cmp_le_i32_e32 vcc, s28, v1
	v_readfirstlane_b32 s2, v1
	s_cbranch_vccnz .LBB0_513
	s_cmp_ge_i32 s2, s85
	s_cbranch_scc0 .LBB0_525
	s_sub_i32 s3, s2, s85
	v_readlane_b32 s0, v250, 12
	s_cmp_ge_i32 s2, s0
	s_mov_b64 s[0:1], -1
	s_cbranch_scc0 .LBB0_522
	s_add_i32 s0, s3, 0xfffffe50
	v_mov_b32_e32 v26, v138
	s_mul_hi_i32 s1, s0, 0x55555556
	s_lshr_b32 s20, s1, 31
	v_lshrrev_b32_e32 v27, 4, v26
	v_xor_b32_e32 v2, v27, v26
	s_add_i32 s20, s1, s20
	v_lshlrev_b32_e32 v2, 4, v2
	v_readlane_b32 s4, v253, 54
	s_mul_i32 s1, s20, 3
	v_and_b32_e32 v110, 0x70, v2
	v_readlane_b32 s5, v253, 55
	v_readlane_b32 s6, v253, 56
	v_readlane_b32 s7, v253, 57
	v_readlane_b32 s8, v253, 58
	v_readlane_b32 s9, v253, 59
	v_readlane_b32 s10, v253, 60
	v_readlane_b32 s11, v253, 61
	s_sub_i32 s0, s0, s1
	s_lshl_b32 s1, s0, 7
	v_lshl_add_u64 v[10:11], s[10:11], 0, v[110:111]
	v_readlane_b32 s4, v253, 26
	s_lshl_b32 s0, s20, 7
	v_readlane_b32 s6, v253, 28
	v_readlane_b32 s8, v253, 30
	v_readlane_b32 s9, v253, 31
	v_ashrrev_i32_e32 v4, 3, v26
	v_add_u32_e32 v2, s1, v4
	v_lshl_add_u64 v[16:17], s[8:9], 0, v[110:111]
	v_add_u32_e32 v4, s0, v4
	s_movk_i32 s6, 0xf00
	v_mad_i64_i32 v[6:7], s[20:21], v4, s6, v[16:17]
	v_add_u32_e32 v4, 0x100, v26
	v_ashrrev_i32_e32 v8, 3, v4
	v_add_u32_e32 v4, s1, v8
	v_add_u32_e32 v8, s0, v8
	v_mad_i64_i32 v[12:13], s[20:21], v8, s6, v[16:17]
	v_add_u32_e32 v8, 0x200, v26
	v_add_u32_e32 v24, 0x300, v26
	v_ashrrev_i32_e32 v14, 3, v8
	v_ashrrev_i32_e32 v28, 3, v24
	v_add_u32_e32 v8, s1, v14
	v_add_u32_e32 v24, s1, v28
	v_ashrrev_i32_e32 v3, 31, v2
	v_ashrrev_i32_e32 v5, 31, v4
	v_ashrrev_i32_e32 v9, 31, v8
	v_ashrrev_i32_e32 v25, 31, v24
	v_lshlrev_b64 v[2:3], 9, v[2:3]
	v_lshlrev_b64 v[4:5], 9, v[4:5]
	v_lshlrev_b64 v[8:9], 9, v[8:9]
	v_lshlrev_b64 v[24:25], 9, v[24:25]
	v_lshl_add_u64 v[2:3], v[10:11], 0, v[2:3]
	v_lshl_add_u64 v[4:5], v[10:11], 0, v[4:5]
	v_lshl_add_u64 v[8:9], v[10:11], 0, v[8:9]
	v_lshl_add_u64 v[10:11], v[10:11], 0, v[24:25]
	v_add_u32_e32 v24, s0, v28
	v_lshlrev_b32_e32 v28, 4, v26
	v_add_u32_e32 v29, 0x1000, v28
	v_readfirstlane_b32 s49, v28
	s_mov_b32 m0, s49
	v_readfirstlane_b32 s54, v29
	v_add_u32_e32 v29, 0x2000, v28
	s_barrier
	global_load_lds_dwordx4 v[2:3], off
	s_mov_b32 m0, s54
	v_readfirstlane_b32 s55, v29
	v_add_u32_e32 v29, 0x3000, v28
	global_load_lds_dwordx4 v[4:5], off
	s_mov_b32 m0, s55
	v_readfirstlane_b32 s27, v29
	v_add_u32_e32 v29, 0x4000, v28
	s_mov_b64 s[8:9], 0x600
	global_load_lds_dwordx4 v[8:9], off
	s_mov_b32 m0, s27
	v_readfirstlane_b32 s43, v29
	v_lshl_add_u64 v[18:19], v[6:7], 0, s[8:9]
	global_load_lds_dwordx4 v[10:11], off
	s_mov_b32 m0, s43
	v_add_u32_e32 v14, s0, v14
	global_load_lds_dwordx4 v[18:19], off
	v_add_u32_e32 v18, 0x5000, v28
	v_lshl_add_u64 v[20:21], v[12:13], 0, s[8:9]
	v_readfirstlane_b32 s46, v18
	v_add_u32_e32 v18, 0x6000, v28
	v_mad_i64_i32 v[14:15], s[20:21], v14, s6, v[16:17]
	s_mov_b32 m0, s46
	v_readfirstlane_b32 s47, v18
	v_add_u32_e32 v18, 0x7000, v28
	v_bfe_u32 v1, v26, 6, 1
	v_lshl_add_u64 v[22:23], v[14:15], 0, s[8:9]
	v_mad_i64_i32 v[16:17], s[20:21], v24, s6, v[16:17]
	s_waitcnt vmcnt(0)
	v_and_b32_e32 v67, 15, v26
	v_ashrrev_i32_e32 v68, 7, v26
	v_bfe_u32 v66, v26, 4, 2
	global_load_lds_dwordx4 v[20:21], off
	s_mov_b32 m0, s47
	v_readfirstlane_b32 s48, v18
	v_bfe_u32 v69, v26, 1, 3
	v_add_u32_e32 v26, 0x8000, v28
	v_lshl_add_u64 v[24:25], v[16:17], 0, s[8:9]
	global_load_lds_dwordx4 v[22:23], off
	s_mov_b32 m0, s48
	v_lshlrev_b32_e32 v18, 7, v67
	v_add_u32_e32 v29, 0x9000, v28
	v_readfirstlane_b32 s26, v26
	global_load_lds_dwordx4 v[24:25], off
	v_lshl_or_b32 v104, v68, 13, v18
	v_lshl_or_b32 v110, v1, 13, v18
	v_lshl_add_u64 v[18:19], v[2:3], 0, s[92:93]
	v_add_u32_e32 v30, 0xa000, v28
	s_mov_b32 m0, s26
	v_readfirstlane_b32 s28, v29
	s_waitcnt vmcnt(0)
	s_waitcnt vmcnt(0) lgkmcnt(0)
	s_barrier
	v_add_u32_e32 v105, 0xc000, v28
	v_add_u32_e32 v106, 0xd000, v28
	v_add_u32_e32 v107, 0xe000, v28
	v_add_u32_e32 v108, 0xf000, v28
	v_lshl_add_u64 v[20:21], v[4:5], 0, s[92:93]
	v_add_u32_e32 v28, 0xb000, v28
	global_load_lds_dwordx4 v[18:19], off
	s_mov_b32 m0, s28
	v_readfirstlane_b32 s29, v30
	v_lshl_add_u64 v[22:23], v[8:9], 0, s[92:93]
	global_load_lds_dwordx4 v[20:21], off
	s_mov_b32 m0, s29
	v_readfirstlane_b32 s36, v28
	v_bitop3_b32 v18, v27, v69, 3 bitop3:0x6c
	v_lshl_add_u64 v[24:25], v[10:11], 0, s[92:93]
	global_load_lds_dwordx4 v[22:23], off
	s_mov_b32 m0, s36
	v_lshlrev_b32_e32 v19, 4, v18
	global_load_lds_dwordx4 v[24:25], off
	v_or_b32_e32 v18, v104, v19
	v_or_b32_e32 v19, v110, v19
	ds_read_b128 v[20:23], v18
	ds_read_b128 v[24:27], v18 offset:2048
	ds_read_b128 v[28:31], v18 offset:4096
	ds_read_b128 v[32:35], v18 offset:6144
	ds_read_b128 v[36:39], v19 offset:16384
	ds_read_b128 v[40:43], v19 offset:18432
	ds_read_b128 v[44:47], v19 offset:20480
	ds_read_b128 v[48:51], v19 offset:22528
	v_readlane_b32 s7, v253, 29
	s_mov_b64 s[6:7], 0x680
	v_readfirstlane_b32 s37, v105
	v_lshl_add_u64 v[64:65], v[6:7], 0, s[6:7]
	s_mov_b32 m0, s37
	v_readfirstlane_b32 s38, v106
	v_lshl_add_u64 v[98:99], v[12:13], 0, s[6:7]
	global_load_lds_dwordx4 v[64:65], off
	s_mov_b32 m0, s38
	v_readfirstlane_b32 s39, v107
	v_lshl_add_u64 v[100:101], v[14:15], 0, s[6:7]
	s_waitcnt lgkmcnt(0)
; #define LAS __attribute__((address_space(3)))
; template <class Epi>
; DI void gemm_tile(const bf16_t* __restrict__ A, int lda, const bf16_t* __restrict__ Bt, int ldb, int K, int row0, int col0, char* lds, const Epi& epi) {
;     ...
;   auto stage_a = [&](int kt, int buf) {
;     char* sa = lds + buf * 32768;
; #pragma unroll
;     for (int i = 0; i < 4; ++i)
;       __builtin_amdgcn_global_load_lds((const void __attribute__((address_space(1)))*)(ag[i] + kt * 64), (void LAS*)(sa + (i * 256 + tid) * 16), 16, 0, 0);
;   };
;   auto stage_b = [&](int kt, int buf) {
;     char* sb = lds + buf * 32768 + 16384;
; #pragma unroll
;     for (int i = 0; i < 4; ++i)
;       __builtin_amdgcn_global_load_lds((const void __attribute__((address_space(1)))*)(bg[i] + kt * 64), (void LAS*)(sb + (i * 256 + tid) * 16), 16, 0, 0);
;   };
;   __syncthreads();
;   stage_a(0, 0); stage_b(0, 0);
;   const int swz = fr >> 1;
;   for (int kt = 0; kt < KT; ++kt) {
;     asm volatile("s_waitcnt vmcnt(0)" ::: "memory");
;     __syncthreads();
;     const char* sa = lds + (kt & 1) * 32768 + (wr * 64 + fr) * 128;
;     const char* sb = lds + (kt & 1) * 32768 + 16384 + (wc * 64 + fr) * 128;
; #pragma unroll
;     for (int kk = 0; kk < 2; ++kk) {
;       if (kt + 1 < KT) { if (kk == 0) stage_a(kt + 1, (kt + 1) & 1); else stage_b(kt + 1, (kt + 1) & 1); }
;       bf16x8 a[4], b[4];
;       const int co = ((kk * 4 + fq) ^ swz) * 16;
; #pragma unroll
;       for (int m = 0; m < 4; ++m) a[m] = *(const bf16x8*)(sa + m * 2048 + co);
; #pragma unroll
;       for (int n = 0; n < 4; ++n) b[n] = *(const bf16x8*)(sb + n * 2048 + co);
; #pragma unroll
;       for (int m = 0; m < 4; ++m)
; #pragma unroll
;         for (int n = 0; n < 4; ++n) acc[m][n] = __builtin_amdgcn_mfma_f32_16x16x32_bf16(b[n], a[m], acc[m][n], 0, 0, 0);
	v_mfma_f32_16x16x32_bf16 v[52:55], v[36:39], v[20:23], 0
	global_load_lds_dwordx4 v[98:99], off
	s_mov_b32 m0, s39
	v_mfma_f32_16x16x32_bf16 v[56:59], v[40:43], v[20:23], 0
	v_readfirstlane_b32 s42, v108
	v_lshl_add_u64 v[102:103], v[16:17], 0, s[6:7]
	global_load_lds_dwordx4 v[100:101], off
	v_mfma_f32_16x16x32_bf16 v[60:63], v[44:47], v[20:23], 0
	s_mov_b32 m0, s42
	s_mov_b64 s[6:7], 0x700
	global_load_lds_dwordx4 v[102:103], off
	v_mfma_f32_16x16x32_bf16 v[70:73], v[48:51], v[20:23], 0
	v_bitop3_b32 v20, v66, v69, 4 bitop3:0x36
	v_lshlrev_b32_e32 v21, 4, v20
	v_or_b32_e32 v20, v104, v21
	v_mfma_f32_16x16x32_bf16 v[74:77], v[36:39], v[24:27], 0
	v_or_b32_e32 v21, v110, v21
	v_lshl_add_u64 v[64:65], v[6:7], 0, s[6:7]
	v_lshl_add_u64 v[132:133], v[12:13], 0, s[6:7]
	v_mfma_f32_16x16x32_bf16 v[78:81], v[40:43], v[24:27], 0
	v_lshl_add_u64 v[134:135], v[14:15], 0, s[6:7]
	v_lshl_add_u64 v[136:137], v[16:17], 0, s[6:7]
	s_mov_b64 s[6:7], 0x100
	v_mfma_f32_16x16x32_bf16 v[82:85], v[44:47], v[24:27], 0
	s_mov_b32 m0, s49
	v_lshlrev_b32_e32 v69, 6, v1
	v_lshlrev_b32_e32 v66, 2, v66
	v_mfma_f32_16x16x32_bf16 v[22:25], v[48:51], v[24:27], 0
	v_readlane_b32 s20, v252, 62
	v_readlane_b32 s21, v252, 63
	v_or_b32_e32 v1, s1, v67
	v_mfma_f32_16x16x32_bf16 v[86:89], v[36:39], v[28:31], 0
	s_mov_b32 s8, 0x3b800000
	v_lshl_add_u32 v1, v68, 6, v1
	v_readlane_b32 s5, v253, 27
	v_mfma_f32_16x16x32_bf16 v[90:93], v[40:43], v[28:31], 0
	v_readlane_b32 s12, v253, 62
	v_readlane_b32 s13, v253, 63
	v_readlane_b32 s14, v254, 0
	v_mfma_f32_16x16x32_bf16 v[94:97], v[44:47], v[28:31], 0
	v_readlane_b32 s15, v254, 1
	v_readlane_b32 s16, v254, 2
	v_readlane_b32 s17, v254, 3
	v_mfma_f32_16x16x32_bf16 v[26:29], v[48:51], v[28:31], 0
	v_readlane_b32 s18, v254, 4
	v_readlane_b32 s19, v254, 5
	v_readlane_b32 s10, v253, 32
	v_mfma_f32_16x16x32_bf16 v[36:39], v[36:39], v[32:35], 0
	v_readlane_b32 s11, v253, 33
	s_mov_b64 s[90:91], s[80:81]
	v_readlane_b32 s95, v254, 48
	v_mfma_f32_16x16x32_bf16 v[40:43], v[40:43], v[32:35], 0
	v_mfma_f32_16x16x32_bf16 v[44:47], v[44:47], v[32:35], 0
	v_mfma_f32_16x16x32_bf16 v[30:33], v[48:51], v[32:35], 0
	ds_read_b128 v[48:51], v20
	ds_read_b128 v[98:101], v20 offset:2048
	ds_read_b128 v[102:105], v20 offset:4096
	ds_read_b128 v[106:109], v20 offset:6144
	ds_read_b128 v[116:119], v21 offset:16384
	ds_read_b128 v[120:123], v21 offset:18432
	ds_read_b128 v[124:127], v21 offset:20480
	ds_read_b128 v[128:131], v21 offset:22528
	s_waitcnt vmcnt(0)
	s_waitcnt lgkmcnt(0)
	v_mfma_f32_16x16x32_bf16 v[34:37], v[116:119], v[106:109], v[36:39]
	s_waitcnt vmcnt(0)
	s_barrier
	v_mfma_f32_16x16x32_bf16 v[38:41], v[120:123], v[106:109], v[40:43]
	v_mfma_f32_16x16x32_bf16 v[42:45], v[124:127], v[106:109], v[44:47]
	s_nop 2
	v_lshl_add_u64 v[46:47], v[2:3], 0, s[6:7]
	v_mfma_f32_16x16x32_bf16 v[52:55], v[116:119], v[48:51], v[52:55]
	global_load_lds_dwordx4 v[46:47], off
	s_mov_b32 m0, s54
	v_mfma_f32_16x16x32_bf16 v[56:59], v[120:123], v[48:51], v[56:59]
	v_mfma_f32_16x16x32_bf16 v[60:63], v[124:127], v[48:51], v[60:63]
	v_mfma_f32_16x16x32_bf16 v[48:51], v[128:131], v[48:51], v[70:73]
	v_mfma_f32_16x16x32_bf16 v[70:73], v[116:119], v[98:101], v[74:77]
	v_mfma_f32_16x16x32_bf16 v[74:77], v[120:123], v[98:101], v[78:81]
	v_mfma_f32_16x16x32_bf16 v[78:81], v[124:127], v[98:101], v[82:85]
	v_mfma_f32_16x16x32_bf16 v[82:85], v[116:119], v[102:105], v[86:89]
	v_mfma_f32_16x16x32_bf16 v[86:89], v[120:123], v[102:105], v[90:93]
	v_mfma_f32_16x16x32_bf16 v[90:93], v[124:127], v[102:105], v[94:97]
	s_nop 2
	v_lshl_add_u64 v[94:95], v[4:5], 0, s[6:7]
	v_lshl_add_u64 v[96:97], v[8:9], 0, s[6:7]
	global_load_lds_dwordx4 v[94:95], off
	s_mov_b32 m0, s55
	v_mfma_f32_16x16x32_bf16 v[22:25], v[128:131], v[98:101], v[22:25]
	v_lshl_add_u64 v[98:99], v[10:11], 0, s[6:7]
	global_load_lds_dwordx4 v[96:97], off
	s_mov_b32 m0, s27
	v_mfma_f32_16x16x32_bf16 v[26:29], v[128:131], v[102:105], v[26:29]
	global_load_lds_dwordx4 v[98:99], off
	s_mov_b32 m0, s43
	v_mfma_f32_16x16x32_bf16 v[30:33], v[128:131], v[106:109], v[30:33]
	ds_read_b128 v[94:97], v18 offset:32768
	ds_read_b128 v[98:101], v18 offset:34816
	ds_read_b128 v[102:105], v18 offset:36864
	ds_read_b128 v[106:109], v18 offset:38912
	ds_read_b128 v[116:119], v19 offset:49152
	ds_read_b128 v[120:123], v19 offset:51200
	ds_read_b128 v[124:127], v19 offset:53248
	ds_read_b128 v[128:131], v19 offset:55296
	global_load_lds_dwordx4 v[64:65], off
	s_mov_b32 m0, s46
	s_waitcnt lgkmcnt(0)
	v_mfma_f32_16x16x32_bf16 v[52:55], v[116:119], v[94:97], v[52:55]
	global_load_lds_dwordx4 v[132:133], off
	s_mov_b32 m0, s47
	v_mfma_f32_16x16x32_bf16 v[56:59], v[120:123], v[94:97], v[56:59]
	global_load_lds_dwordx4 v[134:135], off
	s_mov_b32 m0, s48
	v_mfma_f32_16x16x32_bf16 v[60:63], v[124:127], v[94:97], v[60:63]
	global_load_lds_dwordx4 v[136:137], off
	s_mov_b64 s[6:7], 0x780
	v_mfma_f32_16x16x32_bf16 v[46:49], v[128:131], v[94:97], v[48:51]
	s_mov_b32 m0, s26
	v_readlane_b32 s54, v250, 1
	v_readlane_b32 s55, v250, 2
	v_mfma_f32_16x16x32_bf16 v[70:73], v[116:119], v[98:101], v[70:73]
	s_mov_b32 s47, 0x38e38e39
	s_mov_b64 s[26:27], s[72:73]
	v_mfma_f32_16x16x32_bf16 v[74:77], v[120:123], v[98:101], v[74:77]
	v_mfma_f32_16x16x32_bf16 v[78:81], v[124:127], v[98:101], v[78:81]
	v_mfma_f32_16x16x32_bf16 v[22:25], v[128:131], v[98:101], v[22:25]
	v_mfma_f32_16x16x32_bf16 v[82:85], v[116:119], v[102:105], v[82:85]
	v_mfma_f32_16x16x32_bf16 v[86:89], v[120:123], v[102:105], v[86:89]
	v_mfma_f32_16x16x32_bf16 v[90:93], v[124:127], v[102:105], v[90:93]
	v_mfma_f32_16x16x32_bf16 v[26:29], v[128:131], v[102:105], v[26:29]
	v_mfma_f32_16x16x32_bf16 v[34:37], v[116:119], v[106:109], v[34:37]
	v_mfma_f32_16x16x32_bf16 v[38:41], v[120:123], v[106:109], v[38:41]
	v_mfma_f32_16x16x32_bf16 v[42:45], v[124:127], v[106:109], v[42:45]
	v_mfma_f32_16x16x32_bf16 v[30:33], v[128:131], v[106:109], v[30:33]
	ds_read_b128 v[94:97], v20 offset:32768
	ds_read_b128 v[98:101], v20 offset:34816
	ds_read_b128 v[102:105], v20 offset:36864
	ds_read_b128 v[106:109], v20 offset:38912
	ds_read_b128 v[116:119], v21 offset:49152
	ds_read_b128 v[120:123], v21 offset:51200
	ds_read_b128 v[124:127], v21 offset:53248
	ds_read_b128 v[128:131], v21 offset:55296
	s_waitcnt vmcnt(0)
	s_waitcnt vmcnt(0) lgkmcnt(0)
	v_mfma_f32_16x16x32_bf16 v[50:53], v[116:119], v[94:97], v[52:55]
	s_barrier
; template <class Epi>
; DI void gemm_tile(const bf16_t* __restrict__ A, int lda, const bf16_t* __restrict__ Bt, int ldb, int K, int row0, int col0, char* lds, const Epi& epi) {
;     ...
;   for (int kt = 0; kt < KT; ++kt) {
;     asm volatile("s_waitcnt vmcnt(0)" ::: "memory");
;     __syncthreads();
;     const char* sa = lds + (kt & 1) * 32768 + (wr * 64 + fr) * 128;
;     const char* sb = lds + (kt & 1) * 32768 + 16384 + (wc * 64 + fr) * 128;
; #pragma unroll
;     for (int kk = 0; kk < 2; ++kk) {
;       if (kt + 1 < KT) { if (kk == 0) stage_a(kt + 1, (kt + 1) & 1); else stage_b(kt + 1, (kt + 1) & 1); }
;       bf16x8 a[4], b[4];
;       const int co = ((kk * 4 + fq) ^ swz) * 16;
; #pragma unroll
;       for (int m = 0; m < 4; ++m) a[m] = *(const bf16x8*)(sa + m * 2048 + co);
; #pragma unroll
;       for (int n = 0; n < 4; ++n) b[n] = *(const bf16x8*)(sb + n * 2048 + co);
; #pragma unroll
;       for (int m = 0; m < 4; ++m)
; #pragma unroll
;         for (int n = 0; n < 4; ++n) acc[m][n] = __builtin_amdgcn_mfma_f32_16x16x32_bf16(b[n], a[m], acc[m][n], 0, 0, 0);
;   DI void operator()(const f32x4 (&acc)[4][4], int r0, int c0, int fr, int fq) const {
;     ...
;         f32x4 rs = *(const f32x4*)(rstd + col);
	v_mfma_f32_16x16x32_bf16 v[54:57], v[120:123], v[94:97], v[56:59]
	v_mfma_f32_16x16x32_bf16 v[58:61], v[124:127], v[94:97], v[60:63]
	v_mfma_f32_16x16x32_bf16 v[62:65], v[116:119], v[98:101], v[70:73]
	v_mfma_f32_16x16x32_bf16 v[70:73], v[120:123], v[98:101], v[74:77]
	v_mfma_f32_16x16x32_bf16 v[74:77], v[124:127], v[98:101], v[78:81]
	v_mfma_f32_16x16x32_bf16 v[78:81], v[116:119], v[102:105], v[82:85]
	v_mfma_f32_16x16x32_bf16 v[34:37], v[116:119], v[106:109], v[34:37]
	v_lshl_add_u64 v[116:117], v[14:15], 0, s[6:7]
	v_lshl_add_u64 v[118:119], v[16:17], 0, s[6:7]
	v_mfma_f32_16x16x32_bf16 v[38:41], v[120:123], v[106:109], v[38:41]
	v_mfma_f32_16x16x32_bf16 v[42:45], v[124:127], v[106:109], v[42:45]
	v_mfma_f32_16x16x32_bf16 v[30:33], v[128:131], v[106:109], v[30:33]
	v_lshl_add_u64 v[106:107], v[6:7], 0, s[6:7]
	v_lshl_add_u64 v[108:109], v[12:13], 0, s[6:7]
	s_mov_b64 s[6:7], 0x180
	v_lshl_add_u64 v[2:3], v[2:3], 0, s[6:7]
	v_lshl_add_u64 v[4:5], v[4:5], 0, s[6:7]
	global_load_lds_dwordx4 v[2:3], off
	s_mov_b32 m0, s28
	v_lshl_add_u64 v[6:7], v[8:9], 0, s[6:7]
	global_load_lds_dwordx4 v[4:5], off
	s_mov_b32 m0, s29
	v_lshl_add_u64 v[8:9], v[10:11], 0, s[6:7]
	global_load_lds_dwordx4 v[6:7], off
	s_mov_b32 m0, s36
	v_mfma_f32_16x16x32_bf16 v[46:49], v[128:131], v[94:97], v[46:49]
	global_load_lds_dwordx4 v[8:9], off
	s_mov_b32 m0, s37
	v_mfma_f32_16x16x32_bf16 v[22:25], v[128:131], v[98:101], v[22:25]
	s_mov_b32 s6, 0x45800000
	s_mov_b32 s28, s94
	v_mfma_f32_16x16x32_bf16 v[82:85], v[120:123], v[102:105], v[86:89]
	v_mfma_f32_16x16x32_bf16 v[86:89], v[124:127], v[102:105], v[90:93]
	v_mfma_f32_16x16x32_bf16 v[26:29], v[128:131], v[102:105], v[26:29]
	ds_read_b128 v[2:5], v18
	ds_read_b128 v[6:9], v18 offset:2048
	ds_read_b128 v[10:13], v18 offset:4096
	ds_read_b128 v[14:17], v18 offset:6144
	ds_read_b128 v[90:93], v19 offset:16384
	ds_read_b128 v[94:97], v19 offset:18432
	ds_read_b128 v[98:101], v19 offset:20480
	ds_read_b128 v[102:105], v19 offset:22528
	global_load_lds_dwordx4 v[106:107], off
	s_mov_b32 m0, s38
	s_waitcnt lgkmcnt(0)
	v_mfma_f32_16x16x32_bf16 v[50:53], v[90:93], v[2:5], v[50:53]
	global_load_lds_dwordx4 v[108:109], off
	s_mov_b32 m0, s39
	v_mfma_f32_16x16x32_bf16 v[54:57], v[94:97], v[2:5], v[54:57]
	global_load_lds_dwordx4 v[116:117], off
	s_mov_b32 m0, s42
	v_mfma_f32_16x16x32_bf16 v[58:61], v[98:101], v[2:5], v[58:61]
	global_load_lds_dwordx4 v[118:119], off
	v_mfma_f32_16x16x32_bf16 v[2:5], v[102:105], v[2:5], v[46:49]
	v_mfma_f32_16x16x32_bf16 v[46:49], v[90:93], v[6:9], v[62:65]
	v_mfma_f32_16x16x32_bf16 v[62:65], v[94:97], v[6:9], v[70:73]
	v_mfma_f32_16x16x32_bf16 v[70:73], v[98:101], v[6:9], v[74:77]
	v_mfma_f32_16x16x32_bf16 v[6:9], v[102:105], v[6:9], v[22:25]
	v_mfma_f32_16x16x32_bf16 v[22:25], v[90:93], v[10:13], v[78:81]
	v_mfma_f32_16x16x32_bf16 v[74:77], v[94:97], v[10:13], v[82:85]
	v_mfma_f32_16x16x32_bf16 v[78:81], v[98:101], v[10:13], v[86:89]
	v_mfma_f32_16x16x32_bf16 v[10:13], v[102:105], v[10:13], v[26:29]
	v_mfma_f32_16x16x32_bf16 v[26:29], v[90:93], v[14:17], v[34:37]
	v_mfma_f32_16x16x32_bf16 v[34:37], v[94:97], v[14:17], v[38:41]
	v_mfma_f32_16x16x32_bf16 v[38:41], v[98:101], v[14:17], v[42:45]
	v_mfma_f32_16x16x32_bf16 v[14:17], v[102:105], v[14:17], v[30:33]
	s_nop 2
	ds_read_b128 v[30:33], v20
	ds_read_b128 v[42:45], v20 offset:2048
	ds_read_b128 v[82:85], v20 offset:4096
	ds_read_b128 v[86:89], v20 offset:6144
	ds_read_b128 v[90:93], v21 offset:16384
	ds_read_b128 v[94:97], v21 offset:18432
	ds_read_b128 v[98:101], v21 offset:20480
	ds_read_b128 v[102:105], v21 offset:22528
	s_waitcnt vmcnt(0)
	s_waitcnt vmcnt(0) lgkmcnt(0)
	v_mfma_f32_16x16x32_bf16 v[50:53], v[90:93], v[30:33], v[50:53]
	s_barrier
	v_or3_b32 v186, v69, v66, s0
	v_ashrrev_i32_e32 v187, 31, v186
	v_lshl_add_u64 v[186:187], v[186:187], 2, s[20:21]
	global_load_dwordx4 v[168:171], v[186:187], off
	global_load_dwordx4 v[172:175], v[186:187], off offset:64
	global_load_dwordx4 v[176:179], v[186:187], off offset:128
	global_load_dwordx4 v[180:183], v[186:187], off offset:192
	v_mfma_f32_16x16x32_bf16 v[54:57], v[94:97], v[30:33], v[54:57]
	v_mfma_f32_16x16x32_bf16 v[58:61], v[98:101], v[30:33], v[58:61]
	v_mfma_f32_16x16x32_bf16 v[2:5], v[102:105], v[30:33], v[2:5]
	v_mfma_f32_16x16x32_bf16 v[30:33], v[90:93], v[42:45], v[46:49]
	v_mfma_f32_16x16x32_bf16 v[46:49], v[94:97], v[42:45], v[62:65]
	v_mfma_f32_16x16x32_bf16 v[62:65], v[98:101], v[42:45], v[70:73]
	v_mfma_f32_16x16x32_bf16 v[6:9], v[102:105], v[42:45], v[6:9]
	v_mfma_f32_16x16x32_bf16 v[22:25], v[90:93], v[82:85], v[22:25]
	v_mfma_f32_16x16x32_bf16 v[42:45], v[94:97], v[82:85], v[74:77]
	v_mfma_f32_16x16x32_bf16 v[70:73], v[98:101], v[82:85], v[78:81]
	v_mfma_f32_16x16x32_bf16 v[10:13], v[102:105], v[82:85], v[10:13]
	v_mfma_f32_16x16x32_bf16 v[26:29], v[90:93], v[86:89], v[26:29]
	v_mfma_f32_16x16x32_bf16 v[34:37], v[94:97], v[86:89], v[34:37]
	v_mfma_f32_16x16x32_bf16 v[38:41], v[98:101], v[86:89], v[38:41]
	v_mfma_f32_16x16x32_bf16 v[14:17], v[102:105], v[86:89], v[14:17]
	ds_read_b128 v[74:77], v19 offset:55296
	ds_read_b128 v[78:81], v19 offset:53248
	ds_read_b128 v[82:85], v19 offset:51200
	ds_read_b128 v[86:89], v19 offset:49152
	ds_read_b128 v[90:93], v18 offset:38912
	ds_read_b128 v[94:97], v18 offset:36864
	ds_read_b128 v[98:101], v18 offset:34816
	ds_read_b128 v[102:105], v18 offset:32768
	s_waitcnt lgkmcnt(0)
; DI unsigned pk_bf16(float lo, float hi) { f32x2 v = {lo, hi}; bf16v2 b = __builtin_convertvector(v, bf16v2); return __builtin_bit_cast(unsigned, b); }
; template <class Epi>
; DI void gemm_tile(const bf16_t* __restrict__ A, int lda, const bf16_t* __restrict__ Bt, int ldb, int K, int row0, int col0, char* lds, const Epi& epi) {
;     ...
;       for (int m = 0; m < 4; ++m)
; #pragma unroll
;         for (int n = 0; n < 4; ++n) acc[m][n] = __builtin_amdgcn_mfma_f32_16x16x32_bf16(b[n], a[m], acc[m][n], 0, 0, 0);
;   DI void operator()(const f32x4 (&acc)[4][4], int r0, int c0, int fr, int fq) const {
; #pragma unroll
;     for (int m = 0; m < 4; ++m)
; #pragma unroll
;       for (int n = 0; n < 4; ++n) {
;         const int row = r0 + m * 16 + fr, col = c0 + n * 16 + fq * 4;
;         f32x4 rs = *(const f32x4*)(rstd + col);
; #pragma unroll
;         for (int j = 0; j < 4; ++j) rs[j] = rsqrtf(rs[j] * (1.f / 256.f) + EPSF);
;         u32x2 v = {pk_bf16(acc[m][n][0] * rs[0], acc[m][n][1] * rs[1]), pk_bf16(acc[m][n][2] * rs[2], acc[m][n][3] * rs[3])};
;         *(u32x2*)(VT + (size_t)row * T_TOK + col) = v;
;       }
	v_mfma_f32_16x16x32_bf16 v[50:53], v[86:89], v[102:105], v[50:53]
	v_mfma_f32_16x16x32_bf16 v[54:57], v[82:85], v[102:105], v[54:57]
	v_mfma_f32_16x16x32_bf16 v[106:109], v[78:81], v[102:105], v[58:61]
	v_mfma_f32_16x16x32_bf16 v[2:5], v[74:77], v[102:105], v[2:5]
	v_mfma_f32_16x16x32_bf16 v[30:33], v[86:89], v[98:101], v[30:33]
	v_mfma_f32_16x16x32_bf16 v[102:105], v[82:85], v[98:101], v[46:49]
	v_mfma_f32_16x16x32_bf16 v[116:119], v[78:81], v[98:101], v[62:65]
	v_mfma_f32_16x16x32_bf16 v[6:9], v[74:77], v[98:101], v[6:9]
	v_mfma_f32_16x16x32_bf16 v[22:25], v[86:89], v[94:97], v[22:25]
	v_mfma_f32_16x16x32_bf16 v[98:101], v[82:85], v[94:97], v[42:45]
	v_mfma_f32_16x16x32_bf16 v[70:73], v[78:81], v[94:97], v[70:73]
	v_mfma_f32_16x16x32_bf16 v[10:13], v[74:77], v[94:97], v[10:13]
	v_mfma_f32_16x16x32_bf16 v[86:89], v[86:89], v[90:93], v[26:29]
	v_mfma_f32_16x16x32_bf16 v[82:85], v[82:85], v[90:93], v[34:37]
	v_mfma_f32_16x16x32_bf16 v[78:81], v[78:81], v[90:93], v[38:41]
	v_mfma_f32_16x16x32_bf16 v[74:77], v[74:77], v[90:93], v[14:17]
	ds_read_b128 v[90:93], v21 offset:55296
	ds_read_b128 v[94:97], v21 offset:53248
	ds_read_b128 v[120:123], v21 offset:51200
	ds_read_b128 v[14:17], v21 offset:49152
	ds_read_b128 v[124:127], v20 offset:38912
	ds_read_b128 v[128:131], v20 offset:36864
	ds_read_b128 v[26:29], v20 offset:34816
	ds_read_b128 v[18:21], v20 offset:32768
	s_waitcnt lgkmcnt(1)
	v_mfma_f32_16x16x32_bf16 v[46:49], v[14:17], v[26:29], v[30:33]
	v_mfma_f32_16x16x32_bf16 v[30:33], v[14:17], v[128:131], v[22:25]
	v_mfma_f32_16x16x32_bf16 v[22:25], v[94:97], v[128:131], v[70:73]
	s_nop 2
	v_or3_b32 v72, v69, v66, s0
	v_ashrrev_i32_e32 v73, 31, v72
	v_lshl_add_u64 v[70:71], v[72:73], 2, s[20:21]
	s_waitcnt lgkmcnt(0)
	v_mfma_f32_16x16x32_bf16 v[62:65], v[14:17], v[18:21], v[50:53]
	s_mov_b32 s0, 0x358637bd
	v_mov_b64_e32 v[66:67], s[0:1]
	v_mfma_f32_16x16x32_bf16 v[50:53], v[90:93], v[18:21], v[2:5]
	v_mfma_f32_16x16x32_bf16 v[2:5], v[90:93], v[124:127], v[74:77]
	s_nop 2
	v_mfma_f32_16x16x32_bf16 v[34:37], v[90:93], v[26:29], v[6:9]
	s_waitcnt vmcnt(0)
	s_nop 4
	v_mov_b32_e32 v74, v168
	v_mov_b32_e32 v75, v169
	v_mov_b32_e32 v76, v170
	v_mov_b32_e32 v77, v171
	v_pk_fma_f32 v[68:69], v[74:75], s[8:9], v[66:67] op_sel_hi:[1,0,0]
	s_nop 0
	v_mul_f32_e32 v74, 0x4b800000, v68
	v_cmp_gt_f32_e64 s[0:1], s53, v68
	v_cmp_gt_f32_e32 vcc, s53, v69
	v_mfma_f32_16x16x32_bf16 v[6:9], v[94:97], v[124:127], v[78:81]
	v_cndmask_b32_e64 v68, v68, v74, s[0:1]
	v_mul_f32_e32 v74, 0x4b800000, v69
	v_cndmask_b32_e32 v69, v69, v74, vcc
	v_rsq_f32_e32 v68, v68
	v_rsq_f32_e32 v69, v69
	v_mfma_f32_16x16x32_bf16 v[58:61], v[120:123], v[18:21], v[54:57]
	v_mul_f32_e64 v74, v68, s6
	v_mul_f32_e64 v75, v69, s6
	v_cndmask_b32_e32 v69, v69, v75, vcc
	v_cndmask_b32_e64 v68, v68, v74, s[0:1]
	v_pk_mul_f32 v[62:63], v[62:63], v[68:69]
	v_pk_fma_f32 v[68:69], v[76:77], s[8:9], v[66:67] op_sel_hi:[1,0,0]
	v_cvt_pk_bf16_f32 v62, v62, v63
	v_mul_f32_e32 v63, 0x4b800000, v68
	v_cmp_gt_f32_e64 s[0:1], s53, v68
	v_cmp_gt_f32_e32 vcc, s53, v69
	v_mfma_f32_16x16x32_bf16 v[54:57], v[94:97], v[18:21], v[106:109]
	v_cndmask_b32_e64 v63, v68, v63, s[0:1]
	v_rsq_f32_e32 v68, v63
	v_mul_f32_e32 v63, 0x4b800000, v69
	v_cndmask_b32_e32 v63, v69, v63, vcc
	v_rsq_f32_e32 v69, v63
	v_mfma_f32_16x16x32_bf16 v[42:45], v[120:123], v[26:29], v[102:105]
	v_mul_f32_e64 v74, v68, s6
	v_mul_f32_e64 v75, v69, s6
	v_cndmask_b32_e32 v69, v69, v75, vcc
	v_cndmask_b32_e64 v68, v68, v74, s[0:1]
	v_pk_mul_f32 v[64:65], v[64:65], v[68:69]
	v_mov_b64_e32 v[68:69], s[4:5]
	s_mov_b32 s4, 0x9000
	v_cvt_pk_bf16_f32 v63, v64, v65
	v_mad_i64_i32 v[74:75], s[0:1], v1, s4, v[68:69]
	v_lshlrev_b64 v[64:65], 1, v[72:73]
	v_lshl_add_u64 v[74:75], v[74:75], 0, v[64:65]
	global_store_dwordx2 v[74:75], v[62:63], off
	v_or_b32_e32 v62, 16, v72
	v_ashrrev_i32_e32 v63, 31, v62
	v_lshl_add_u64 v[62:63], v[62:63], 2, s[20:21]
	v_mfma_f32_16x16x32_bf16 v[38:41], v[94:97], v[26:29], v[116:119]
	s_nop 4
	v_mov_b32_e32 v76, v172
	v_mov_b32_e32 v77, v173
	v_mov_b32_e32 v78, v174
	v_mov_b32_e32 v79, v175
	v_pk_fma_f32 v[76:77], v[76:77], s[8:9], v[66:67] op_sel_hi:[1,0,0]
	s_nop 0
	v_mul_f32_e32 v73, 0x4b800000, v76
	v_cmp_gt_f32_e64 s[0:1], s53, v76
	v_cmp_gt_f32_e32 vcc, s53, v77
	v_mfma_f32_16x16x32_bf16 v[26:29], v[120:123], v[128:131], v[98:101]
	v_cndmask_b32_e64 v73, v76, v73, s[0:1]
	v_rsq_f32_e32 v76, v73
	v_mul_f32_e32 v73, 0x4b800000, v77
	v_cndmask_b32_e32 v73, v77, v73, vcc
	v_rsq_f32_e32 v77, v73
	v_mfma_f32_16x16x32_bf16 v[18:21], v[90:93], v[128:131], v[10:13]
	v_mul_f32_e64 v80, v76, s6
	v_mul_f32_e64 v81, v77, s6
	v_cndmask_b32_e32 v77, v77, v81, vcc
	v_cndmask_b32_e64 v76, v76, v80, s[0:1]
	v_pk_mul_f32 v[58:59], v[58:59], v[76:77]
	v_pk_fma_f32 v[76:77], v[78:79], s[8:9], v[66:67] op_sel_hi:[1,0,0]
	v_cvt_pk_bf16_f32 v58, v58, v59
	v_mul_f32_e32 v59, 0x4b800000, v76
	v_cmp_gt_f32_e64 s[0:1], s53, v76
	v_cmp_gt_f32_e32 vcc, s53, v77
	v_mfma_f32_16x16x32_bf16 v[14:17], v[14:17], v[124:127], v[86:89]
	v_cndmask_b32_e64 v59, v76, v59, s[0:1]
	v_rsq_f32_e32 v76, v59
	v_mul_f32_e32 v59, 0x4b800000, v77
	v_cndmask_b32_e32 v59, v77, v59, vcc
	v_rsq_f32_e32 v77, v59
	v_mfma_f32_16x16x32_bf16 v[10:13], v[120:123], v[124:127], v[82:85]
	v_mul_f32_e64 v78, v76, s6
	v_mul_f32_e64 v79, v77, s6
	v_cndmask_b32_e32 v77, v77, v79, vcc
	v_cndmask_b32_e64 v76, v76, v78, s[0:1]
	v_pk_mul_f32 v[60:61], v[60:61], v[76:77]
	s_nop 0
	v_cvt_pk_bf16_f32 v59, v60, v61
	global_store_dwordx2 v[74:75], v[58:59], off offset:32
	v_or_b32_e32 v58, 32, v72
	v_ashrrev_i32_e32 v59, 31, v58
	v_lshl_add_u64 v[58:59], v[58:59], 2, s[20:21]
	s_nop 4
; DI unsigned pk_bf16(float lo, float hi) { f32x2 v = {lo, hi}; bf16v2 b = __builtin_convertvector(v, bf16v2); return __builtin_bit_cast(unsigned, b); }
;   DI void operator()(const f32x4 (&acc)[4][4], int r0, int c0, int fr, int fq) const {
;     ...
;       for (int n = 0; n < 4; ++n) {
;         const int row = r0 + m * 16 + fr, col = c0 + n * 16 + fq * 4;
;         f32x4 rs = *(const f32x4*)(rstd + col);
; #pragma unroll
;         for (int j = 0; j < 4; ++j) rs[j] = rsqrtf(rs[j] * (1.f / 256.f) + EPSF);
;         u32x2 v = {pk_bf16(acc[m][n][0] * rs[0], acc[m][n][1] * rs[1]), pk_bf16(acc[m][n][2] * rs[2], acc[m][n][3] * rs[3])};
;         *(u32x2*)(VT + (size_t)row * T_TOK + col) = v;
	v_mov_b32_e32 v76, v176
	v_mov_b32_e32 v77, v177
	v_mov_b32_e32 v78, v178
	v_mov_b32_e32 v79, v179
	v_pk_fma_f32 v[60:61], v[76:77], s[8:9], v[66:67] op_sel_hi:[1,0,0]
	s_nop 0
	v_mul_f32_e32 v73, 0x4b800000, v60
	v_cmp_gt_f32_e64 s[0:1], s53, v60
	v_cmp_gt_f32_e32 vcc, s53, v61
	s_nop 0
	v_cndmask_b32_e64 v60, v60, v73, s[0:1]
	v_mul_f32_e32 v73, 0x4b800000, v61
	v_cndmask_b32_e32 v61, v61, v73, vcc
	v_rsq_f32_e32 v60, v60
	v_rsq_f32_e32 v61, v61
	s_nop 0
	v_pk_mul_f32 v[76:77], v[60:61], s[6:7] op_sel_hi:[1,0]
	s_nop 0
	v_cndmask_b32_e32 v61, v61, v77, vcc
	v_cndmask_b32_e64 v60, v60, v76, s[0:1]
	v_pk_mul_f32 v[54:55], v[54:55], v[60:61]
	v_pk_fma_f32 v[60:61], v[78:79], s[8:9], v[66:67] op_sel_hi:[1,0,0]
	v_cvt_pk_bf16_f32 v54, v54, v55
	v_mul_f32_e32 v55, 0x4b800000, v60
	v_cmp_gt_f32_e64 s[0:1], s53, v60
	v_cmp_gt_f32_e32 vcc, s53, v61
	s_nop 0
	v_cndmask_b32_e64 v55, v60, v55, s[0:1]
	v_rsq_f32_e32 v60, v55
	v_mul_f32_e32 v55, 0x4b800000, v61
	v_cndmask_b32_e32 v55, v61, v55, vcc
	v_rsq_f32_e32 v61, v55
	s_nop 0
	v_pk_mul_f32 v[76:77], v[60:61], s[6:7] op_sel_hi:[1,0]
	s_nop 0
	v_cndmask_b32_e32 v61, v61, v77, vcc
	v_cndmask_b32_e64 v60, v60, v76, s[0:1]
	v_pk_mul_f32 v[56:57], v[56:57], v[60:61]
	s_nop 0
	v_cvt_pk_bf16_f32 v55, v56, v57
	global_store_dwordx2 v[74:75], v[54:55], off offset:64
	v_or_b32_e32 v54, 48, v72
	v_ashrrev_i32_e32 v55, 31, v54
	v_lshl_add_u64 v[54:55], v[54:55], 2, s[20:21]
	s_nop 4
	v_mov_b32_e32 v76, v180
	v_mov_b32_e32 v77, v181
	v_mov_b32_e32 v78, v182
	v_mov_b32_e32 v79, v183
	v_pk_fma_f32 v[56:57], v[76:77], s[8:9], v[66:67] op_sel_hi:[1,0,0]
	s_nop 0
	v_mul_f32_e32 v60, 0x4b800000, v56
	v_cmp_gt_f32_e64 s[0:1], s53, v56
	v_cmp_gt_f32_e32 vcc, s53, v57
	s_nop 0
	v_cndmask_b32_e64 v56, v56, v60, s[0:1]
	v_mul_f32_e32 v60, 0x4b800000, v57
	v_cndmask_b32_e32 v57, v57, v60, vcc
	v_rsq_f32_e32 v56, v56
	v_rsq_f32_e32 v57, v57
	s_nop 0
	v_pk_mul_f32 v[60:61], v[56:57], s[6:7] op_sel_hi:[1,0]
	s_nop 0
	v_cndmask_b32_e32 v57, v57, v61, vcc
	v_cndmask_b32_e64 v56, v56, v60, s[0:1]
	v_pk_mul_f32 v[50:51], v[50:51], v[56:57]
	v_pk_fma_f32 v[56:57], v[78:79], s[8:9], v[66:67] op_sel_hi:[1,0,0]
	v_cvt_pk_bf16_f32 v50, v50, v51
	v_mul_f32_e32 v51, 0x4b800000, v56
	v_cmp_gt_f32_e64 s[0:1], s53, v56
	v_cmp_gt_f32_e32 vcc, s53, v57
	s_nop 0
	v_cndmask_b32_e64 v51, v56, v51, s[0:1]
	v_rsq_f32_e32 v56, v51
	v_mul_f32_e32 v51, 0x4b800000, v57
	v_cndmask_b32_e32 v51, v57, v51, vcc
	v_rsq_f32_e32 v57, v51
	s_nop 0
	v_pk_mul_f32 v[60:61], v[56:57], s[6:7] op_sel_hi:[1,0]
	s_nop 0
	v_cndmask_b32_e32 v57, v57, v61, vcc
	v_cndmask_b32_e64 v56, v56, v60, s[0:1]
	v_pk_mul_f32 v[52:53], v[52:53], v[56:57]
	v_or_b32_e32 v60, 16, v1
	v_cvt_pk_bf16_f32 v51, v52, v53
	global_store_dwordx2 v[74:75], v[50:51], off offset:96
	s_nop 4
	v_mov_b32_e32 v50, v168
	v_mov_b32_e32 v51, v169
	v_mov_b32_e32 v52, v170
	v_mov_b32_e32 v53, v171
	v_pk_fma_f32 v[50:51], v[50:51], s[8:9], v[66:67] op_sel_hi:[1,0,0]
	s_nop 0
	v_mul_f32_e32 v56, 0x4b800000, v50
	v_cmp_gt_f32_e64 s[0:1], s53, v50
	v_cmp_gt_f32_e32 vcc, s53, v51
	s_nop 0
	v_cndmask_b32_e64 v50, v50, v56, s[0:1]
	v_mul_f32_e32 v56, 0x4b800000, v51
	v_cndmask_b32_e32 v51, v51, v56, vcc
	v_rsq_f32_e32 v50, v50
	v_rsq_f32_e32 v51, v51
	s_nop 0
	v_pk_mul_f32 v[56:57], v[50:51], s[6:7] op_sel_hi:[1,0]
	s_nop 0
	v_cndmask_b32_e32 v51, v51, v57, vcc
	v_cndmask_b32_e64 v50, v50, v56, s[0:1]
	v_pk_mul_f32 v[46:47], v[46:47], v[50:51]
	s_nop 0
	v_cvt_pk_bf16_f32 v50, v46, v47
	v_pk_fma_f32 v[46:47], v[52:53], s[8:9], v[66:67] op_sel_hi:[1,0,0]
	s_nop 0
	v_mul_f32_e32 v51, 0x4b800000, v46
	v_cmp_gt_f32_e64 s[0:1], s53, v46
	v_cmp_gt_f32_e32 vcc, s53, v47
	s_nop 0
	v_cndmask_b32_e64 v46, v46, v51, s[0:1]
	v_mul_f32_e32 v51, 0x4b800000, v47
	v_cndmask_b32_e32 v47, v47, v51, vcc
	v_rsq_f32_e32 v46, v46
	v_rsq_f32_e32 v47, v47
	s_nop 0
	v_pk_mul_f32 v[52:53], v[46:47], s[6:7] op_sel_hi:[1,0]
	s_nop 0
	v_cndmask_b32_e32 v47, v47, v53, vcc
	v_cndmask_b32_e64 v46, v46, v52, s[0:1]
	v_pk_mul_f32 v[46:47], v[48:49], v[46:47]
	s_nop 0
	v_cvt_pk_bf16_f32 v51, v46, v47
	v_mad_i64_i32 v[46:47], s[0:1], v60, s4, v[68:69]
	v_lshl_add_u64 v[46:47], v[46:47], 0, v[64:65]
	global_store_dwordx2 v[46:47], v[50:51], off
	s_nop 4
	v_mov_b32_e32 v48, v172
	v_mov_b32_e32 v49, v173
	v_mov_b32_e32 v50, v174
	v_mov_b32_e32 v51, v175
	v_pk_fma_f32 v[48:49], v[48:49], s[8:9], v[66:67] op_sel_hi:[1,0,0]
	s_nop 0
	v_mul_f32_e32 v52, 0x4b800000, v48
	v_cmp_gt_f32_e64 s[0:1], s53, v48
	v_cmp_gt_f32_e32 vcc, s53, v49
	s_nop 0
	v_cndmask_b32_e64 v48, v48, v52, s[0:1]
	v_mul_f32_e32 v52, 0x4b800000, v49
	v_cndmask_b32_e32 v49, v49, v52, vcc
	v_rsq_f32_e32 v48, v48
	v_rsq_f32_e32 v49, v49
	s_nop 0
	v_pk_mul_f32 v[52:53], v[48:49], s[6:7] op_sel_hi:[1,0]
	s_nop 0
	v_cndmask_b32_e32 v49, v49, v53, vcc
	v_cndmask_b32_e64 v48, v48, v52, s[0:1]
	v_pk_mul_f32 v[42:43], v[42:43], v[48:49]
	v_pk_fma_f32 v[48:49], v[50:51], s[8:9], v[66:67] op_sel_hi:[1,0,0]
	v_cvt_pk_bf16_f32 v42, v42, v43
	v_mul_f32_e32 v43, 0x4b800000, v48
	v_cmp_gt_f32_e64 s[0:1], s53, v48
	v_cmp_gt_f32_e32 vcc, s53, v49
	s_nop 0
	v_cndmask_b32_e64 v43, v48, v43, s[0:1]
	v_rsq_f32_e32 v48, v43
	v_mul_f32_e32 v43, 0x4b800000, v49
	v_cndmask_b32_e32 v43, v49, v43, vcc
	v_rsq_f32_e32 v49, v43
	s_nop 0
	v_pk_mul_f32 v[50:51], v[48:49], s[6:7] op_sel_hi:[1,0]
	s_nop 0
	v_cndmask_b32_e32 v49, v49, v51, vcc
	v_cndmask_b32_e64 v48, v48, v50, s[0:1]
	v_pk_mul_f32 v[44:45], v[44:45], v[48:49]
	s_nop 0
	v_cvt_pk_bf16_f32 v43, v44, v45
	global_store_dwordx2 v[46:47], v[42:43], off offset:32
	s_nop 4
	v_mov_b32_e32 v42, v176
	v_mov_b32_e32 v43, v177
	v_mov_b32_e32 v44, v178
; DI unsigned pk_bf16(float lo, float hi) { f32x2 v = {lo, hi}; bf16v2 b = __builtin_convertvector(v, bf16v2); return __builtin_bit_cast(unsigned, b); }
;   DI void operator()(const f32x4 (&acc)[4][4], int r0, int c0, int fr, int fq) const {
;     ...
;       for (int n = 0; n < 4; ++n) {
;         const int row = r0 + m * 16 + fr, col = c0 + n * 16 + fq * 4;
;         f32x4 rs = *(const f32x4*)(rstd + col);
; #pragma unroll
;         for (int j = 0; j < 4; ++j) rs[j] = rsqrtf(rs[j] * (1.f / 256.f) + EPSF);
;         u32x2 v = {pk_bf16(acc[m][n][0] * rs[0], acc[m][n][1] * rs[1]), pk_bf16(acc[m][n][2] * rs[2], acc[m][n][3] * rs[3])};
;         *(u32x2*)(VT + (size_t)row * T_TOK + col) = v;
	v_mov_b32_e32 v45, v179
	v_pk_fma_f32 v[42:43], v[42:43], s[8:9], v[66:67] op_sel_hi:[1,0,0]
	s_nop 0
	v_mul_f32_e32 v48, 0x4b800000, v42
	v_cmp_gt_f32_e64 s[0:1], s53, v42
	v_cmp_gt_f32_e32 vcc, s53, v43
	s_nop 0
	v_cndmask_b32_e64 v42, v42, v48, s[0:1]
	v_mul_f32_e32 v48, 0x4b800000, v43
	v_cndmask_b32_e32 v43, v43, v48, vcc
	v_rsq_f32_e32 v42, v42
	v_rsq_f32_e32 v43, v43
	s_nop 0
	v_pk_mul_f32 v[48:49], v[42:43], s[6:7] op_sel_hi:[1,0]
	s_nop 0
	v_cndmask_b32_e32 v43, v43, v49, vcc
	v_cndmask_b32_e64 v42, v42, v48, s[0:1]
	v_pk_mul_f32 v[38:39], v[38:39], v[42:43]
	v_pk_fma_f32 v[42:43], v[44:45], s[8:9], v[66:67] op_sel_hi:[1,0,0]
	v_cvt_pk_bf16_f32 v38, v38, v39
	v_mul_f32_e32 v39, 0x4b800000, v42
	v_cmp_gt_f32_e64 s[0:1], s53, v42
	v_cmp_gt_f32_e32 vcc, s53, v43
	s_nop 0
	v_cndmask_b32_e64 v39, v42, v39, s[0:1]
	v_rsq_f32_e32 v42, v39
	v_mul_f32_e32 v39, 0x4b800000, v43
	v_cndmask_b32_e32 v39, v43, v39, vcc
	v_rsq_f32_e32 v43, v39
	s_nop 0
	v_pk_mul_f32 v[44:45], v[42:43], s[6:7] op_sel_hi:[1,0]
	s_nop 0
	v_cndmask_b32_e32 v43, v43, v45, vcc
	v_cndmask_b32_e64 v42, v42, v44, s[0:1]
	v_pk_mul_f32 v[40:41], v[40:41], v[42:43]
	s_nop 0
	v_cvt_pk_bf16_f32 v39, v40, v41
	global_store_dwordx2 v[46:47], v[38:39], off offset:64
	s_nop 4
	v_mov_b32_e32 v38, v180
	v_mov_b32_e32 v39, v181
	v_mov_b32_e32 v40, v182
	v_mov_b32_e32 v41, v183
	v_pk_fma_f32 v[38:39], v[38:39], s[8:9], v[66:67] op_sel_hi:[1,0,0]
	s_nop 0
	v_mul_f32_e32 v42, 0x4b800000, v38
	v_cmp_gt_f32_e64 s[0:1], s53, v38
	v_cmp_gt_f32_e32 vcc, s53, v39
	s_nop 0
	v_cndmask_b32_e64 v38, v38, v42, s[0:1]
	v_mul_f32_e32 v42, 0x4b800000, v39
	v_cndmask_b32_e32 v39, v39, v42, vcc
	v_rsq_f32_e32 v38, v38
	v_rsq_f32_e32 v39, v39
	s_nop 0
	v_pk_mul_f32 v[42:43], v[38:39], s[6:7] op_sel_hi:[1,0]
	s_nop 0
	v_cndmask_b32_e32 v39, v39, v43, vcc
	v_cndmask_b32_e64 v38, v38, v42, s[0:1]
	v_pk_mul_f32 v[34:35], v[34:35], v[38:39]
	v_pk_fma_f32 v[38:39], v[40:41], s[8:9], v[66:67] op_sel_hi:[1,0,0]
	v_cvt_pk_bf16_f32 v34, v34, v35
	v_mul_f32_e32 v35, 0x4b800000, v38
	v_cmp_gt_f32_e64 s[0:1], s53, v38
	v_cmp_gt_f32_e32 vcc, s53, v39
	s_nop 0
	v_cndmask_b32_e64 v35, v38, v35, s[0:1]
	v_rsq_f32_e32 v38, v35
	v_mul_f32_e32 v35, 0x4b800000, v39
	v_cndmask_b32_e32 v35, v39, v35, vcc
	v_rsq_f32_e32 v39, v35
	s_nop 0
	v_pk_mul_f32 v[40:41], v[38:39], s[6:7] op_sel_hi:[1,0]
	s_nop 0
	v_cndmask_b32_e32 v39, v39, v41, vcc
	v_cndmask_b32_e64 v38, v38, v40, s[0:1]
	v_pk_mul_f32 v[36:37], v[36:37], v[38:39]
	v_or_b32_e32 v40, 32, v1
	v_cvt_pk_bf16_f32 v35, v36, v37
	global_store_dwordx2 v[46:47], v[34:35], off offset:96
	v_or_b32_e32 v1, 48, v1
	s_nop 4
	v_mov_b32_e32 v34, v168
	v_mov_b32_e32 v35, v169
	v_mov_b32_e32 v36, v170
	v_mov_b32_e32 v37, v171
	v_pk_fma_f32 v[34:35], v[34:35], s[8:9], v[66:67] op_sel_hi:[1,0,0]
	s_nop 0
	v_mul_f32_e32 v38, 0x4b800000, v34
	v_cmp_gt_f32_e64 s[0:1], s53, v34
	v_cmp_gt_f32_e32 vcc, s53, v35
	s_nop 0
	v_cndmask_b32_e64 v34, v34, v38, s[0:1]
	v_mul_f32_e32 v38, 0x4b800000, v35
	v_cndmask_b32_e32 v35, v35, v38, vcc
	v_rsq_f32_e32 v34, v34
	v_rsq_f32_e32 v35, v35
	s_nop 0
	v_pk_mul_f32 v[38:39], v[34:35], s[6:7] op_sel_hi:[1,0]
	s_nop 0
	v_cndmask_b32_e32 v35, v35, v39, vcc
	v_cndmask_b32_e64 v34, v34, v38, s[0:1]
	v_pk_mul_f32 v[30:31], v[30:31], v[34:35]
	s_nop 0
	v_cvt_pk_bf16_f32 v34, v30, v31
	v_pk_fma_f32 v[30:31], v[36:37], s[8:9], v[66:67] op_sel_hi:[1,0,0]
	s_nop 0
	v_mul_f32_e32 v35, 0x4b800000, v30
	v_cmp_gt_f32_e64 s[0:1], s53, v30
	v_cmp_gt_f32_e32 vcc, s53, v31
	s_nop 0
	v_cndmask_b32_e64 v30, v30, v35, s[0:1]
	v_mul_f32_e32 v35, 0x4b800000, v31
	v_cndmask_b32_e32 v31, v31, v35, vcc
	v_rsq_f32_e32 v30, v30
	v_rsq_f32_e32 v31, v31
	s_nop 0
	v_pk_mul_f32 v[36:37], v[30:31], s[6:7] op_sel_hi:[1,0]
	s_nop 0
	v_cndmask_b32_e32 v31, v31, v37, vcc
	v_cndmask_b32_e64 v30, v30, v36, s[0:1]
	v_pk_mul_f32 v[30:31], v[32:33], v[30:31]
	s_nop 0
	v_cvt_pk_bf16_f32 v35, v30, v31
	v_mad_i64_i32 v[30:31], s[0:1], v40, s4, v[68:69]
	v_lshl_add_u64 v[30:31], v[30:31], 0, v[64:65]
	global_store_dwordx2 v[30:31], v[34:35], off
	s_nop 4
	v_mov_b32_e32 v32, v172
	v_mov_b32_e32 v33, v173
	v_mov_b32_e32 v34, v174
	v_mov_b32_e32 v35, v175
	v_pk_fma_f32 v[32:33], v[32:33], s[8:9], v[66:67] op_sel_hi:[1,0,0]
	s_nop 0
	v_mul_f32_e32 v36, 0x4b800000, v32
	v_cmp_gt_f32_e64 s[0:1], s53, v32
	v_cmp_gt_f32_e32 vcc, s53, v33
	s_nop 0
	v_cndmask_b32_e64 v32, v32, v36, s[0:1]
	v_mul_f32_e32 v36, 0x4b800000, v33
	v_cndmask_b32_e32 v33, v33, v36, vcc
	v_rsq_f32_e32 v32, v32
	v_rsq_f32_e32 v33, v33
	s_nop 0
	v_pk_mul_f32 v[36:37], v[32:33], s[6:7] op_sel_hi:[1,0]
	s_nop 0
	v_cndmask_b32_e32 v33, v33, v37, vcc
	v_cndmask_b32_e64 v32, v32, v36, s[0:1]
	v_pk_mul_f32 v[26:27], v[26:27], v[32:33]
	v_pk_fma_f32 v[32:33], v[34:35], s[8:9], v[66:67] op_sel_hi:[1,0,0]
	v_cvt_pk_bf16_f32 v26, v26, v27
	v_mul_f32_e32 v27, 0x4b800000, v32
	v_cmp_gt_f32_e64 s[0:1], s53, v32
	v_cmp_gt_f32_e32 vcc, s53, v33
	s_nop 0
	v_cndmask_b32_e64 v27, v32, v27, s[0:1]
	v_rsq_f32_e32 v32, v27
	v_mul_f32_e32 v27, 0x4b800000, v33
	v_cndmask_b32_e32 v27, v33, v27, vcc
	v_rsq_f32_e32 v33, v27
	s_nop 0
	v_pk_mul_f32 v[34:35], v[32:33], s[6:7] op_sel_hi:[1,0]
	s_nop 0
	v_cndmask_b32_e32 v33, v33, v35, vcc
	v_cndmask_b32_e64 v32, v32, v34, s[0:1]
	v_pk_mul_f32 v[28:29], v[28:29], v[32:33]
	s_nop 0
	v_cvt_pk_bf16_f32 v27, v28, v29
	global_store_dwordx2 v[30:31], v[26:27], off offset:32
	s_nop 4
	v_mov_b32_e32 v26, v176
	v_mov_b32_e32 v27, v177
	v_mov_b32_e32 v28, v178
	v_mov_b32_e32 v29, v179
	v_pk_fma_f32 v[26:27], v[26:27], s[8:9], v[66:67] op_sel_hi:[1,0,0]
	s_nop 0
	v_mul_f32_e32 v32, 0x4b800000, v26
	v_cmp_gt_f32_e64 s[0:1], s53, v26
; DI unsigned pk_bf16(float lo, float hi) { f32x2 v = {lo, hi}; bf16v2 b = __builtin_convertvector(v, bf16v2); return __builtin_bit_cast(unsigned, b); }
;   DI void operator()(const f32x4 (&acc)[4][4], int r0, int c0, int fr, int fq) const {
;     ...
;       for (int n = 0; n < 4; ++n) {
;         const int row = r0 + m * 16 + fr, col = c0 + n * 16 + fq * 4;
;         f32x4 rs = *(const f32x4*)(rstd + col);
; #pragma unroll
;         for (int j = 0; j < 4; ++j) rs[j] = rsqrtf(rs[j] * (1.f / 256.f) + EPSF);
;         u32x2 v = {pk_bf16(acc[m][n][0] * rs[0], acc[m][n][1] * rs[1]), pk_bf16(acc[m][n][2] * rs[2], acc[m][n][3] * rs[3])};
;         *(u32x2*)(VT + (size_t)row * T_TOK + col) = v;
	v_cmp_gt_f32_e32 vcc, s53, v27
	s_nop 0
	v_cndmask_b32_e64 v26, v26, v32, s[0:1]
	v_mul_f32_e32 v32, 0x4b800000, v27
	v_cndmask_b32_e32 v27, v27, v32, vcc
	v_rsq_f32_e32 v26, v26
	v_rsq_f32_e32 v27, v27
	s_nop 0
	v_pk_mul_f32 v[32:33], v[26:27], s[6:7] op_sel_hi:[1,0]
	s_nop 0
	v_cndmask_b32_e32 v27, v27, v33, vcc
	v_cndmask_b32_e64 v26, v26, v32, s[0:1]
	v_pk_mul_f32 v[22:23], v[22:23], v[26:27]
	v_pk_fma_f32 v[26:27], v[28:29], s[8:9], v[66:67] op_sel_hi:[1,0,0]
	v_cvt_pk_bf16_f32 v22, v22, v23
	v_mul_f32_e32 v23, 0x4b800000, v26
	v_cmp_gt_f32_e64 s[0:1], s53, v26
	v_cmp_gt_f32_e32 vcc, s53, v27
	s_nop 0
	v_cndmask_b32_e64 v23, v26, v23, s[0:1]
	v_rsq_f32_e32 v26, v23
	v_mul_f32_e32 v23, 0x4b800000, v27
	v_cndmask_b32_e32 v23, v27, v23, vcc
	v_rsq_f32_e32 v27, v23
	s_nop 0
	v_pk_mul_f32 v[28:29], v[26:27], s[6:7] op_sel_hi:[1,0]
	s_nop 0
	v_cndmask_b32_e32 v27, v27, v29, vcc
	v_cndmask_b32_e64 v26, v26, v28, s[0:1]
	v_pk_mul_f32 v[24:25], v[24:25], v[26:27]
	s_nop 0
	v_cvt_pk_bf16_f32 v23, v24, v25
	global_store_dwordx2 v[30:31], v[22:23], off offset:64
	s_nop 4
	v_mov_b32_e32 v22, v180
	v_mov_b32_e32 v23, v181
	v_mov_b32_e32 v24, v182
	v_mov_b32_e32 v25, v183
	v_pk_fma_f32 v[22:23], v[22:23], s[8:9], v[66:67] op_sel_hi:[1,0,0]
	s_nop 0
	v_mul_f32_e32 v26, 0x4b800000, v22
	v_cmp_gt_f32_e64 s[0:1], s53, v22
	v_cmp_gt_f32_e32 vcc, s53, v23
	s_nop 0
	v_cndmask_b32_e64 v22, v22, v26, s[0:1]
	v_mul_f32_e32 v26, 0x4b800000, v23
	v_cndmask_b32_e32 v23, v23, v26, vcc
	v_rsq_f32_e32 v22, v22
	v_rsq_f32_e32 v23, v23
	s_nop 0
	v_pk_mul_f32 v[26:27], v[22:23], s[6:7] op_sel_hi:[1,0]
	s_nop 0
	v_cndmask_b32_e32 v23, v23, v27, vcc
	v_cndmask_b32_e64 v22, v22, v26, s[0:1]
	v_pk_mul_f32 v[18:19], v[18:19], v[22:23]
	v_pk_fma_f32 v[22:23], v[24:25], s[8:9], v[66:67] op_sel_hi:[1,0,0]
	v_cvt_pk_bf16_f32 v18, v18, v19
	v_mul_f32_e32 v19, 0x4b800000, v22
	v_cmp_gt_f32_e64 s[0:1], s53, v22
	v_cmp_gt_f32_e32 vcc, s53, v23
	s_nop 0
	v_cndmask_b32_e64 v19, v22, v19, s[0:1]
	v_rsq_f32_e32 v22, v19
	v_mul_f32_e32 v19, 0x4b800000, v23
	v_cndmask_b32_e32 v19, v23, v19, vcc
	v_rsq_f32_e32 v23, v19
	s_nop 0
	v_pk_mul_f32 v[24:25], v[22:23], s[6:7] op_sel_hi:[1,0]
	s_nop 0
	v_cndmask_b32_e32 v23, v23, v25, vcc
	v_cndmask_b32_e64 v22, v22, v24, s[0:1]
	v_pk_mul_f32 v[20:21], v[20:21], v[22:23]
	s_nop 0
	v_cvt_pk_bf16_f32 v19, v20, v21
	global_store_dwordx2 v[30:31], v[18:19], off offset:96
	s_nop 4
	v_mov_b32_e32 v18, v168
	v_mov_b32_e32 v19, v169
	v_mov_b32_e32 v20, v170
	v_mov_b32_e32 v21, v171
	v_pk_fma_f32 v[18:19], v[18:19], s[8:9], v[66:67] op_sel_hi:[1,0,0]
	s_nop 0
	v_mul_f32_e32 v22, 0x4b800000, v18
	v_cmp_gt_f32_e64 s[0:1], s53, v18
	v_cmp_gt_f32_e32 vcc, s53, v19
	s_nop 0
	v_cndmask_b32_e64 v18, v18, v22, s[0:1]
	v_mul_f32_e32 v22, 0x4b800000, v19
	v_cndmask_b32_e32 v19, v19, v22, vcc
	v_rsq_f32_e32 v18, v18
	v_rsq_f32_e32 v19, v19
	s_nop 0
	v_pk_mul_f32 v[22:23], v[18:19], s[6:7] op_sel_hi:[1,0]
	s_nop 0
	v_cndmask_b32_e32 v19, v19, v23, vcc
	v_cndmask_b32_e64 v18, v18, v22, s[0:1]
	v_pk_mul_f32 v[14:15], v[14:15], v[18:19]
	s_nop 0
	v_cvt_pk_bf16_f32 v18, v14, v15
	v_pk_fma_f32 v[14:15], v[20:21], s[8:9], v[66:67] op_sel_hi:[1,0,0]
	s_nop 0
	v_mul_f32_e32 v19, 0x4b800000, v14
	v_cmp_gt_f32_e64 s[0:1], s53, v14
	v_cmp_gt_f32_e32 vcc, s53, v15
	s_nop 0
	v_cndmask_b32_e64 v14, v14, v19, s[0:1]
	v_mul_f32_e32 v19, 0x4b800000, v15
	v_cndmask_b32_e32 v15, v15, v19, vcc
	v_rsq_f32_e32 v14, v14
	v_rsq_f32_e32 v15, v15
	s_nop 0
	v_pk_mul_f32 v[20:21], v[14:15], s[6:7] op_sel_hi:[1,0]
	s_nop 0
	v_cndmask_b32_e32 v15, v15, v21, vcc
	v_cndmask_b32_e64 v14, v14, v20, s[0:1]
	v_pk_mul_f32 v[14:15], v[16:17], v[14:15]
	s_nop 0
	v_cvt_pk_bf16_f32 v19, v14, v15
	v_mad_i64_i32 v[14:15], s[0:1], v1, s4, v[68:69]
	v_lshl_add_u64 v[14:15], v[14:15], 0, v[64:65]
	global_store_dwordx2 v[14:15], v[18:19], off
	s_nop 4
	v_mov_b32_e32 v16, v172
	v_mov_b32_e32 v17, v173
	v_mov_b32_e32 v18, v174
	v_mov_b32_e32 v19, v175
	v_pk_fma_f32 v[16:17], v[16:17], s[8:9], v[66:67] op_sel_hi:[1,0,0]
	s_nop 0
	v_mul_f32_e32 v1, 0x4b800000, v16
	v_cmp_gt_f32_e64 s[0:1], s53, v16
	v_cmp_gt_f32_e32 vcc, s53, v17
	s_nop 0
	v_cndmask_b32_e64 v1, v16, v1, s[0:1]
	v_rsq_f32_e32 v16, v1
	v_mul_f32_e32 v1, 0x4b800000, v17
	v_cndmask_b32_e32 v1, v17, v1, vcc
	v_rsq_f32_e32 v17, v1
	s_nop 0
	v_pk_mul_f32 v[20:21], v[16:17], s[6:7] op_sel_hi:[1,0]
	s_nop 0
	v_cndmask_b32_e32 v17, v17, v21, vcc
	v_cndmask_b32_e64 v16, v16, v20, s[0:1]
	v_pk_mul_f32 v[10:11], v[10:11], v[16:17]
	v_pk_fma_f32 v[16:17], v[18:19], s[8:9], v[66:67] op_sel_hi:[1,0,0]
	v_cvt_pk_bf16_f32 v10, v10, v11
	v_mul_f32_e32 v1, 0x4b800000, v16
	v_cmp_gt_f32_e64 s[0:1], s53, v16
	v_cmp_gt_f32_e32 vcc, s53, v17
	s_nop 0
	v_cndmask_b32_e64 v1, v16, v1, s[0:1]
	v_rsq_f32_e32 v16, v1
	v_mul_f32_e32 v1, 0x4b800000, v17
	v_cndmask_b32_e32 v1, v17, v1, vcc
	v_rsq_f32_e32 v17, v1
	s_nop 0
	v_pk_mul_f32 v[18:19], v[16:17], s[6:7] op_sel_hi:[1,0]
	s_nop 0
	v_cndmask_b32_e32 v17, v17, v19, vcc
	v_cndmask_b32_e64 v16, v16, v18, s[0:1]
	v_pk_mul_f32 v[12:13], v[12:13], v[16:17]
	s_nop 0
	v_cvt_pk_bf16_f32 v11, v12, v13
	global_store_dwordx2 v[14:15], v[10:11], off offset:32
	s_nop 4
	v_mov_b32_e32 v10, v176
	v_mov_b32_e32 v11, v177
	v_mov_b32_e32 v12, v178
	v_mov_b32_e32 v13, v179
	v_pk_fma_f32 v[10:11], v[10:11], s[8:9], v[66:67] op_sel_hi:[1,0,0]
	s_nop 0
	v_mul_f32_e32 v1, 0x4b800000, v10
	v_cmp_gt_f32_e64 s[0:1], s53, v10
	v_cmp_gt_f32_e32 vcc, s53, v11
	s_nop 0
	v_cndmask_b32_e64 v1, v10, v1, s[0:1]
	v_rsq_f32_e32 v10, v1
	v_mul_f32_e32 v1, 0x4b800000, v11
	v_cndmask_b32_e32 v1, v11, v1, vcc
	v_rsq_f32_e32 v11, v1
	s_nop 0
; #define LAS __attribute__((address_space(3)))
; DI unsigned pk_bf16(float lo, float hi) { f32x2 v = {lo, hi}; bf16v2 b = __builtin_convertvector(v, bf16v2); return __builtin_bit_cast(unsigned, b); }
; DI int opaque_tid() { int t = threadIdx.x; asm volatile("" : "+v"(t)); return t; }
; template <class Epi>
; DI void gemm_tile(const bf16_t* __restrict__ A, int lda, const bf16_t* __restrict__ Bt, int ldb, int K, int row0, int col0, char* lds, const Epi& epi) {
;   const int tid = opaque_tid(), lane = tid & 63, wid = tid >> 6, wr = wid >> 1, wc = wid & 1, fr = lane & 15, fq = lane >> 4;
;   const bf16_t* ag[4];
;   const bf16_t* bg[4];
; #pragma unroll
;   for (int i = 0; i < 4; ++i) {
;     const int id = i * 256 + tid, r = id >> 3, cp = id & 7, c = cp ^ ((r >> 1) & 7);
;     ag[i] = A + (size_t)(row0 + r) * lda + c * 8;
;     bg[i] = Bt + (size_t)(col0 + r) * ldb + c * 8;
;   }
;   f32x4 acc[4][4];
; #pragma unroll
;   for (int m = 0; m < 4; ++m)
; #pragma unroll
;     for (int n = 0; n < 4; ++n) acc[m][n] = (f32x4){0.f, 0.f, 0.f, 0.f};
;   const int KT = K >> 6;
;   auto stage_a = [&](int kt, int buf) {
;     char* sa = lds + buf * 32768;
; #pragma unroll
;     for (int i = 0; i < 4; ++i)
;       __builtin_amdgcn_global_load_lds((const void __attribute__((address_space(1)))*)(ag[i] + kt * 64), (void LAS*)(sa + (i * 256 + tid) * 16), 16, 0, 0);
;   };
;   auto stage_b = [&](int kt, int buf) {
;     char* sb = lds + buf * 32768 + 16384;
; #pragma unroll
;     for (int i = 0; i < 4; ++i)
;       __builtin_amdgcn_global_load_lds((const void __attribute__((address_space(1)))*)(bg[i] + kt * 64), (void LAS*)(sb + (i * 256 + tid) * 16), 16, 0, 0);
;   };
;   __syncthreads();
;   stage_a(0, 0); stage_b(0, 0);
;   DI void operator()(const f32x4 (&acc)[4][4], int r0, int c0, int fr, int fq) const {
;     ...
;       for (int n = 0; n < 4; ++n) {
;         const int row = r0 + m * 16 + fr, col = c0 + n * 16 + fq * 4;
;         f32x4 rs = *(const f32x4*)(rstd + col);
; #pragma unroll
;         for (int j = 0; j < 4; ++j) rs[j] = rsqrtf(rs[j] * (1.f / 256.f) + EPSF);
;         u32x2 v = {pk_bf16(acc[m][n][0] * rs[0], acc[m][n][1] * rs[1]), pk_bf16(acc[m][n][2] * rs[2], acc[m][n][3] * rs[3])};
;         *(u32x2*)(VT + (size_t)row * T_TOK + col) = v;
	v_pk_mul_f32 v[16:17], v[10:11], s[6:7] op_sel_hi:[1,0]
	s_nop 0
	v_cndmask_b32_e32 v11, v11, v17, vcc
	v_cndmask_b32_e64 v10, v10, v16, s[0:1]
	v_pk_mul_f32 v[6:7], v[6:7], v[10:11]
	v_pk_fma_f32 v[10:11], v[12:13], s[8:9], v[66:67] op_sel_hi:[1,0,0]
	v_cvt_pk_bf16_f32 v6, v6, v7
	v_mul_f32_e32 v1, 0x4b800000, v10
	v_cmp_gt_f32_e64 s[0:1], s53, v10
	v_cmp_gt_f32_e32 vcc, s53, v11
	s_nop 0
	v_cndmask_b32_e64 v1, v10, v1, s[0:1]
	v_rsq_f32_e32 v10, v1
	v_mul_f32_e32 v1, 0x4b800000, v11
	v_cndmask_b32_e32 v1, v11, v1, vcc
	v_rsq_f32_e32 v11, v1
	s_nop 0
	v_pk_mul_f32 v[12:13], v[10:11], s[6:7] op_sel_hi:[1,0]
	s_nop 0
	v_cndmask_b32_e32 v11, v11, v13, vcc
	v_cndmask_b32_e64 v10, v10, v12, s[0:1]
	v_pk_mul_f32 v[8:9], v[8:9], v[10:11]
	s_nop 0
	v_cvt_pk_bf16_f32 v7, v8, v9
	global_store_dwordx2 v[14:15], v[6:7], off offset:64
	s_nop 4
	v_mov_b32_e32 v6, v180
	v_mov_b32_e32 v7, v181
	v_mov_b32_e32 v8, v182
	v_mov_b32_e32 v9, v183
	v_pk_fma_f32 v[6:7], v[6:7], s[8:9], v[66:67] op_sel_hi:[1,0,0]
	s_nop 0
	v_mul_f32_e32 v1, 0x4b800000, v6
	v_cmp_gt_f32_e64 s[0:1], s53, v6
	v_cmp_gt_f32_e32 vcc, s53, v7
	s_nop 0
	v_cndmask_b32_e64 v1, v6, v1, s[0:1]
	v_rsq_f32_e32 v6, v1
	v_mul_f32_e32 v1, 0x4b800000, v7
	v_cndmask_b32_e32 v1, v7, v1, vcc
	v_rsq_f32_e32 v7, v1
	s_nop 0
	v_pk_mul_f32 v[10:11], v[6:7], s[6:7] op_sel_hi:[1,0]
	s_nop 0
	v_cndmask_b32_e32 v7, v7, v11, vcc
	v_cndmask_b32_e64 v6, v6, v10, s[0:1]
	v_pk_mul_f32 v[2:3], v[2:3], v[6:7]
	v_pk_fma_f32 v[6:7], v[8:9], s[8:9], v[66:67] op_sel_hi:[1,0,0]
	v_cvt_pk_bf16_f32 v2, v2, v3
	v_mul_f32_e32 v1, 0x4b800000, v6
	v_cmp_gt_f32_e64 s[0:1], s53, v6
	v_cmp_gt_f32_e32 vcc, s53, v7
	s_nop 0
	v_cndmask_b32_e64 v1, v6, v1, s[0:1]
	v_rsq_f32_e32 v6, v1
	v_mul_f32_e32 v1, 0x4b800000, v7
	v_cndmask_b32_e32 v1, v7, v1, vcc
	v_rsq_f32_e32 v7, v1
	s_nop 0
	v_pk_mul_f32 v[8:9], v[6:7], s[6:7] op_sel_hi:[1,0]
	s_nop 0
	v_cndmask_b32_e32 v7, v7, v9, vcc
	v_cndmask_b32_e64 v6, v6, v8, s[0:1]
	v_pk_mul_f32 v[4:5], v[4:5], v[6:7]
	s_mov_b64 s[0:1], 0
	v_cvt_pk_bf16_f32 v3, v4, v5
	global_store_dwordx2 v[14:15], v[2:3], off offset:96
.LBB0_522:
	s_andn2_b64 vcc, exec, s[0:1]
	s_cbranch_vccnz .LBB0_524
	s_mul_hi_i32 s0, s3, 0x55555556
	s_lshr_b32 s1, s0, 31
	v_mov_b32_e32 v28, v138
	s_add_i32 s1, s0, s1
	s_lshl_b32 s0, s1, 7
	v_lshrrev_b32_e32 v29, 4, v28
	s_mul_i32 s1, s1, 3
	v_xor_b32_e32 v2, v29, v28
	s_sub_i32 s1, s3, s1
	v_lshlrev_b32_e32 v2, 4, v2
	v_readlane_b32 s4, v253, 26
	s_lshl_b32 s1, s1, 7
	v_and_b32_e32 v110, 0x70, v2
	v_readlane_b32 s5, v253, 27
	v_readlane_b32 s6, v253, 28
	v_readlane_b32 s7, v253, 29
	v_readlane_b32 s8, v253, 30
	v_readlane_b32 s9, v253, 31
	v_readlane_b32 s10, v253, 32
	v_readlane_b32 s11, v253, 33
	v_ashrrev_i32_e32 v4, 3, v28
	v_lshl_add_u64 v[10:11], s[8:9], 0, v[110:111]
	v_readlane_b32 s4, v253, 54
	v_add_u32_e32 v2, s0, v4
	v_add_u32_e32 v4, s1, v4
	v_readlane_b32 s8, v253, 58
	v_readlane_b32 s9, v253, 59
	v_ashrrev_i32_e32 v5, 31, v4
	v_lshlrev_b64 v[4:5], 9, v[4:5]
	v_lshl_add_u64 v[16:17], s[8:9], 0, v[110:111]
	v_lshl_add_u64 v[8:9], v[16:17], 0, v[4:5]
	v_add_u32_e32 v4, 0x100, v28
	v_ashrrev_i32_e32 v6, 3, v4
	v_add_u32_e32 v4, s0, v6
	v_add_u32_e32 v6, s1, v6
	v_ashrrev_i32_e32 v7, 31, v6
	v_lshlrev_b64 v[6:7], 9, v[6:7]
	v_lshl_add_u64 v[12:13], v[16:17], 0, v[6:7]
	v_add_u32_e32 v6, 0x200, v28
	v_add_u32_e32 v24, 0x300, v28
	v_ashrrev_i32_e32 v14, 3, v6
	v_ashrrev_i32_e32 v26, 3, v24
	v_add_u32_e32 v6, s0, v14
	v_add_u32_e32 v14, s1, v14
	v_add_u32_e32 v24, s0, v26
	v_add_u32_e32 v26, s1, v26
	v_ashrrev_i32_e32 v15, 31, v14
	v_ashrrev_i32_e32 v27, 31, v26
	v_lshlrev_b64 v[14:15], 9, v[14:15]
	v_lshlrev_b64 v[26:27], 9, v[26:27]
	v_readlane_b32 s5, v253, 55
	s_movk_i32 s3, 0xf00
	v_lshl_add_u64 v[14:15], v[16:17], 0, v[14:15]
	v_lshl_add_u64 v[16:17], v[16:17], 0, v[26:27]
	v_lshlrev_b32_e32 v26, 4, v28
	v_mad_i64_i32 v[2:3], s[20:21], v2, s3, v[10:11]
	s_mov_b64 s[4:5], 0x600
	v_readfirstlane_b32 s48, v26
	v_lshl_add_u64 v[18:19], v[2:3], 0, s[4:5]
	s_mov_b32 m0, s48
	s_barrier
	global_load_lds_dwordx4 v[18:19], off
	v_add_u32_e32 v18, 0x1000, v26
	v_mad_i64_i32 v[4:5], s[20:21], v4, s3, v[10:11]
	v_readfirstlane_b32 s49, v18
	v_add_u32_e32 v18, 0x2000, v26
	v_lshl_add_u64 v[20:21], v[4:5], 0, s[4:5]
	v_mad_i64_i32 v[6:7], s[20:21], v6, s3, v[10:11]
	s_mov_b32 m0, s49
	v_readfirstlane_b32 s54, v18
	v_add_u32_e32 v18, 0x3000, v26
	v_lshl_add_u64 v[22:23], v[6:7], 0, s[4:5]
	v_mad_i64_i32 v[10:11], s[20:21], v24, s3, v[10:11]
	global_load_lds_dwordx4 v[20:21], off
	s_mov_b32 m0, s54
	v_readfirstlane_b32 s27, v18
	v_add_u32_e32 v18, 0x4000, v26
	v_lshl_add_u64 v[24:25], v[10:11], 0, s[4:5]
	global_load_lds_dwordx4 v[22:23], off
	s_mov_b32 m0, s27
	v_readfirstlane_b32 s42, v18
	v_add_u32_e32 v18, 0x5000, v26
	global_load_lds_dwordx4 v[24:25], off
	s_mov_b32 m0, s42
	v_readfirstlane_b32 s43, v18
	v_add_u32_e32 v18, 0x6000, v26
	global_load_lds_dwordx4 v[8:9], off
	s_mov_b32 m0, s43
	v_readfirstlane_b32 s46, v18
	v_add_u32_e32 v18, 0x7000, v26
	s_waitcnt vmcnt(0)
	v_and_b32_e32 v66, 15, v28
	global_load_lds_dwordx4 v[12:13], off
	s_mov_b32 m0, s46
	v_readfirstlane_b32 s47, v18
	v_add_u32_e32 v27, 0x8000, v26
	v_bfe_u32 v1, v28, 6, 1
	v_ashrrev_i32_e32 v67, 7, v28
	v_bfe_u32 v75, v28, 4, 2
	global_load_lds_dwordx4 v[14:15], off
	s_mov_b32 m0, s47
	v_bfe_u32 v74, v28, 1, 3
	v_lshlrev_b32_e32 v18, 7, v66
	s_mov_b64 s[4:5], 0x680
	v_add_u32_e32 v28, 0x9000, v26
	v_readfirstlane_b32 s3, v27
	global_load_lds_dwordx4 v[16:17], off
	v_lshl_or_b32 v104, v67, 13, v18
	v_lshl_or_b32 v108, v1, 13, v18
	v_lshl_add_u64 v[18:19], v[2:3], 0, s[4:5]
	v_add_u32_e32 v30, 0xa000, v26
	s_mov_b32 m0, s3
	v_readfirstlane_b32 s26, v28
	s_waitcnt vmcnt(0)
	s_waitcnt vmcnt(0) lgkmcnt(0)
	s_barrier
; template <class Epi>
; DI void gemm_tile(const bf16_t* __restrict__ A, int lda, const bf16_t* __restrict__ Bt, int ldb, int K, int row0, int col0, char* lds, const Epi& epi) {
;     ...
;   for (int kt = 0; kt < KT; ++kt) {
;     asm volatile("s_waitcnt vmcnt(0)" ::: "memory");
;     __syncthreads();
;     const char* sa = lds + (kt & 1) * 32768 + (wr * 64 + fr) * 128;
;     const char* sb = lds + (kt & 1) * 32768 + 16384 + (wc * 64 + fr) * 128;
; #pragma unroll
;     for (int kk = 0; kk < 2; ++kk) {
;       if (kt + 1 < KT) { if (kk == 0) stage_a(kt + 1, (kt + 1) & 1); else stage_b(kt + 1, (kt + 1) & 1); }
;       bf16x8 a[4], b[4];
;       const int co = ((kk * 4 + fq) ^ swz) * 16;
; #pragma unroll
;       for (int m = 0; m < 4; ++m) a[m] = *(const bf16x8*)(sa + m * 2048 + co);
; #pragma unroll
;       for (int n = 0; n < 4; ++n) b[n] = *(const bf16x8*)(sb + n * 2048 + co);
; #pragma unroll
;       for (int m = 0; m < 4; ++m)
; #pragma unroll
;         for (int n = 0; n < 4; ++n) acc[m][n] = __builtin_amdgcn_mfma_f32_16x16x32_bf16(b[n], a[m], acc[m][n], 0, 0, 0);
;     }
	v_add_u32_e32 v105, 0xc000, v26
	v_add_u32_e32 v106, 0xd000, v26
	v_add_u32_e32 v107, 0xe000, v26
	v_add_u32_e32 v109, 0xf000, v26
	v_lshl_add_u64 v[20:21], v[4:5], 0, s[4:5]
	v_add_u32_e32 v26, 0xb000, v26
	global_load_lds_dwordx4 v[18:19], off
	s_mov_b32 m0, s26
	v_readfirstlane_b32 s28, v30
	v_lshl_add_u64 v[22:23], v[6:7], 0, s[4:5]
	global_load_lds_dwordx4 v[20:21], off
	s_mov_b32 m0, s28
	v_readfirstlane_b32 s29, v26
	v_bitop3_b32 v18, v29, v74, 3 bitop3:0x6c
	v_lshl_add_u64 v[24:25], v[10:11], 0, s[4:5]
	global_load_lds_dwordx4 v[22:23], off
	s_mov_b32 m0, s29
	v_lshlrev_b32_e32 v19, 4, v18
	global_load_lds_dwordx4 v[24:25], off
	v_or_b32_e32 v18, v104, v19
	v_or_b32_e32 v19, v108, v19
	ds_read_b128 v[20:23], v18
	ds_read_b128 v[24:27], v18 offset:2048
	ds_read_b128 v[28:31], v18 offset:4096
	ds_read_b128 v[32:35], v18 offset:6144
	ds_read_b128 v[36:39], v19 offset:16384
	ds_read_b128 v[40:43], v19 offset:18432
	ds_read_b128 v[44:47], v19 offset:20480
	ds_read_b128 v[48:51], v19 offset:22528
	v_readfirstlane_b32 s36, v105
	v_lshl_add_u64 v[64:65], v[8:9], 0, s[92:93]
	s_mov_b32 m0, s36
	v_readfirstlane_b32 s37, v106
	v_lshl_add_u64 v[72:73], v[12:13], 0, s[92:93]
	global_load_lds_dwordx4 v[64:65], off
	s_mov_b32 m0, s37
	v_readfirstlane_b32 s38, v107
	v_lshl_add_u64 v[100:101], v[14:15], 0, s[92:93]
	s_waitcnt lgkmcnt(0)
	v_mfma_f32_16x16x32_bf16 v[52:55], v[36:39], v[20:23], 0
	global_load_lds_dwordx4 v[72:73], off
	s_mov_b32 m0, s38
	v_mfma_f32_16x16x32_bf16 v[56:59], v[40:43], v[20:23], 0
	v_readfirstlane_b32 s39, v109
	v_lshl_add_u64 v[102:103], v[16:17], 0, s[92:93]
	global_load_lds_dwordx4 v[100:101], off
	v_mfma_f32_16x16x32_bf16 v[60:63], v[44:47], v[20:23], 0
	s_mov_b32 m0, s39
	s_mov_b64 s[4:5], 0x100
	global_load_lds_dwordx4 v[102:103], off
	v_mfma_f32_16x16x32_bf16 v[68:71], v[48:51], v[20:23], 0
	v_bitop3_b32 v20, v75, v74, 4 bitop3:0x36
	v_lshlrev_b32_e32 v21, 4, v20
	v_or_b32_e32 v20, v104, v21
	v_mfma_f32_16x16x32_bf16 v[76:79], v[36:39], v[24:27], 0
	v_or_b32_e32 v21, v108, v21
	v_lshl_add_u64 v[64:65], v[8:9], 0, s[4:5]
	v_lshl_add_u64 v[72:73], v[12:13], 0, s[4:5]
	v_mfma_f32_16x16x32_bf16 v[80:83], v[40:43], v[24:27], 0
	v_lshl_add_u64 v[108:109], v[14:15], 0, s[4:5]
	v_lshl_add_u64 v[136:137], v[16:17], 0, s[4:5]
	s_mov_b64 s[4:5], 0x700
	v_mfma_f32_16x16x32_bf16 v[84:87], v[44:47], v[24:27], 0
	s_mov_b32 m0, s48
	v_or_b32_e32 v66, s0, v66
	v_lshl_add_u32 v66, v67, 6, v66
	v_mfma_f32_16x16x32_bf16 v[22:25], v[48:51], v[24:27], 0
	v_xor_b32_e32 v67, 16, v147
	v_readlane_b32 s20, v252, 62
	v_readlane_b32 s21, v252, 63
	v_mfma_f32_16x16x32_bf16 v[88:91], v[36:39], v[28:31], 0
	v_readlane_b32 s6, v253, 56
	v_readlane_b32 s7, v253, 57
	v_readlane_b32 s10, v253, 60
	v_mfma_f32_16x16x32_bf16 v[92:95], v[40:43], v[28:31], 0
	v_readlane_b32 s11, v253, 61
	v_readlane_b32 s12, v253, 62
	v_readlane_b32 s13, v253, 63
	v_mfma_f32_16x16x32_bf16 v[96:99], v[44:47], v[28:31], 0
	v_readlane_b32 s14, v254, 0
	v_readlane_b32 s15, v254, 1
	v_readlane_b32 s16, v254, 2
	v_mfma_f32_16x16x32_bf16 v[26:29], v[48:51], v[28:31], 0
	v_readlane_b32 s17, v254, 3
	v_readlane_b32 s18, v254, 4
	v_readlane_b32 s19, v254, 5
	v_mfma_f32_16x16x32_bf16 v[36:39], v[36:39], v[32:35], 0
	v_lshl_or_b32 v1, v1, 6, s1
	v_ashrrev_i32_e32 v1, 6, v1
	v_lshlrev_b32_e32 v110, 3, v75
	v_mfma_f32_16x16x32_bf16 v[40:43], v[40:43], v[32:35], 0
	s_mov_b64 s[90:91], s[80:81]
	v_readlane_b32 s95, v254, 48
	v_mfma_f32_16x16x32_bf16 v[44:47], v[44:47], v[32:35], 0
	v_mfma_f32_16x16x32_bf16 v[30:33], v[48:51], v[32:35], 0
	ds_read_b128 v[48:51], v20
	ds_read_b128 v[100:103], v20 offset:2048
	ds_read_b128 v[104:107], v20 offset:4096
	ds_read_b128 v[116:119], v20 offset:6144
	ds_read_b128 v[120:123], v21 offset:16384
	ds_read_b128 v[124:127], v21 offset:18432
	ds_read_b128 v[128:131], v21 offset:20480
	ds_read_b128 v[132:135], v21 offset:22528
	s_waitcnt vmcnt(0)
	s_waitcnt lgkmcnt(0)
	v_mfma_f32_16x16x32_bf16 v[34:37], v[120:123], v[116:119], v[36:39]
	s_waitcnt vmcnt(0)
	s_barrier
	v_mfma_f32_16x16x32_bf16 v[38:41], v[124:127], v[116:119], v[40:43]
	v_mfma_f32_16x16x32_bf16 v[42:45], v[128:131], v[116:119], v[44:47]
	s_nop 2
	v_lshl_add_u64 v[46:47], v[2:3], 0, s[4:5]
	v_mfma_f32_16x16x32_bf16 v[52:55], v[120:123], v[48:51], v[52:55]
	global_load_lds_dwordx4 v[46:47], off
	s_mov_b32 m0, s49
	v_mfma_f32_16x16x32_bf16 v[56:59], v[124:127], v[48:51], v[56:59]
	v_mfma_f32_16x16x32_bf16 v[60:63], v[128:131], v[48:51], v[60:63]
	v_mfma_f32_16x16x32_bf16 v[48:51], v[132:135], v[48:51], v[68:71]
	v_mfma_f32_16x16x32_bf16 v[68:71], v[120:123], v[100:103], v[76:79]
	v_mfma_f32_16x16x32_bf16 v[76:79], v[124:127], v[100:103], v[80:83]
	v_mfma_f32_16x16x32_bf16 v[80:83], v[128:131], v[100:103], v[84:87]
	v_mfma_f32_16x16x32_bf16 v[84:87], v[120:123], v[104:107], v[88:91]
	v_mfma_f32_16x16x32_bf16 v[88:91], v[124:127], v[104:107], v[92:95]
	v_mfma_f32_16x16x32_bf16 v[92:95], v[128:131], v[104:107], v[96:99]
	s_nop 2
	v_lshl_add_u64 v[96:97], v[4:5], 0, s[4:5]
	v_lshl_add_u64 v[98:99], v[6:7], 0, s[4:5]
	global_load_lds_dwordx4 v[96:97], off
	s_mov_b32 m0, s54
	v_mfma_f32_16x16x32_bf16 v[22:25], v[132:135], v[100:103], v[22:25]
	v_lshl_add_u64 v[100:101], v[10:11], 0, s[4:5]
	global_load_lds_dwordx4 v[98:99], off
	s_mov_b32 m0, s27
	v_mfma_f32_16x16x32_bf16 v[26:29], v[132:135], v[104:107], v[26:29]
	global_load_lds_dwordx4 v[100:101], off
	s_mov_b32 m0, s42
	v_mfma_f32_16x16x32_bf16 v[30:33], v[132:135], v[116:119], v[30:33]
	ds_read_b128 v[96:99], v18 offset:32768
	ds_read_b128 v[100:103], v18 offset:34816
	ds_read_b128 v[104:107], v18 offset:36864
	ds_read_b128 v[116:119], v18 offset:38912
	ds_read_b128 v[120:123], v19 offset:49152
	ds_read_b128 v[124:127], v19 offset:51200
	ds_read_b128 v[128:131], v19 offset:53248
	ds_read_b128 v[132:135], v19 offset:55296
	global_load_lds_dwordx4 v[64:65], off
	s_mov_b32 m0, s43
	s_waitcnt lgkmcnt(0)
; template <class Epi>
; DI void gemm_tile(const bf16_t* __restrict__ A, int lda, const bf16_t* __restrict__ Bt, int ldb, int K, int row0, int col0, char* lds, const Epi& epi) {
;     ...
;   for (int kt = 0; kt < KT; ++kt) {
;     asm volatile("s_waitcnt vmcnt(0)" ::: "memory");
;     __syncthreads();
;     const char* sa = lds + (kt & 1) * 32768 + (wr * 64 + fr) * 128;
;     const char* sb = lds + (kt & 1) * 32768 + 16384 + (wc * 64 + fr) * 128;
; #pragma unroll
;     for (int kk = 0; kk < 2; ++kk) {
;       if (kt + 1 < KT) { if (kk == 0) stage_a(kt + 1, (kt + 1) & 1); else stage_b(kt + 1, (kt + 1) & 1); }
;       bf16x8 a[4], b[4];
;       const int co = ((kk * 4 + fq) ^ swz) * 16;
; #pragma unroll
;       for (int m = 0; m < 4; ++m) a[m] = *(const bf16x8*)(sa + m * 2048 + co);
; #pragma unroll
;       for (int n = 0; n < 4; ++n) b[n] = *(const bf16x8*)(sb + n * 2048 + co);
; #pragma unroll
;       for (int m = 0; m < 4; ++m)
; #pragma unroll
;         for (int n = 0; n < 4; ++n) acc[m][n] = __builtin_amdgcn_mfma_f32_16x16x32_bf16(b[n], a[m], acc[m][n], 0, 0, 0);
;     }
	v_mfma_f32_16x16x32_bf16 v[52:55], v[120:123], v[96:99], v[52:55]
	global_load_lds_dwordx4 v[72:73], off
	s_mov_b32 m0, s46
	v_mfma_f32_16x16x32_bf16 v[56:59], v[124:127], v[96:99], v[56:59]
	global_load_lds_dwordx4 v[108:109], off
	s_mov_b32 m0, s47
	v_mfma_f32_16x16x32_bf16 v[60:63], v[128:131], v[96:99], v[60:63]
	global_load_lds_dwordx4 v[136:137], off
	s_mov_b64 s[4:5], 0x180
	v_mfma_f32_16x16x32_bf16 v[46:49], v[132:135], v[96:99], v[48:51]
	v_lshl_add_u64 v[72:73], v[8:9], 0, s[4:5]
	v_lshl_add_u64 v[108:109], v[12:13], 0, s[4:5]
	s_mov_b32 m0, s3
	v_mfma_f32_16x16x32_bf16 v[68:71], v[120:123], v[100:103], v[68:71]
	s_mov_b32 s47, 0x38e38e39
	s_movk_i32 s3, 0x900
	v_readlane_b32 s54, v250, 1
	v_mfma_f32_16x16x32_bf16 v[76:79], v[124:127], v[100:103], v[76:79]
	v_readlane_b32 s55, v250, 2
	v_mfma_f32_16x16x32_bf16 v[80:83], v[128:131], v[100:103], v[80:83]
	v_mfma_f32_16x16x32_bf16 v[22:25], v[132:135], v[100:103], v[22:25]
	v_mfma_f32_16x16x32_bf16 v[84:87], v[120:123], v[104:107], v[84:87]
	v_mfma_f32_16x16x32_bf16 v[88:91], v[124:127], v[104:107], v[88:91]
	v_mfma_f32_16x16x32_bf16 v[92:95], v[128:131], v[104:107], v[92:95]
	v_mfma_f32_16x16x32_bf16 v[26:29], v[132:135], v[104:107], v[26:29]
	v_mfma_f32_16x16x32_bf16 v[34:37], v[120:123], v[116:119], v[34:37]
	v_mfma_f32_16x16x32_bf16 v[38:41], v[124:127], v[116:119], v[38:41]
	v_mfma_f32_16x16x32_bf16 v[42:45], v[128:131], v[116:119], v[42:45]
	v_mfma_f32_16x16x32_bf16 v[30:33], v[132:135], v[116:119], v[30:33]
	ds_read_b128 v[96:99], v20 offset:32768
	ds_read_b128 v[100:103], v20 offset:34816
	ds_read_b128 v[104:107], v20 offset:36864
	ds_read_b128 v[116:119], v20 offset:38912
	ds_read_b128 v[120:123], v21 offset:49152
	ds_read_b128 v[124:127], v21 offset:51200
	ds_read_b128 v[128:131], v21 offset:53248
	ds_read_b128 v[132:135], v21 offset:55296
	s_waitcnt vmcnt(0)
	s_waitcnt vmcnt(0) lgkmcnt(0)
	v_mfma_f32_16x16x32_bf16 v[34:37], v[120:123], v[116:119], v[34:37]
	s_barrier
	v_mfma_f32_16x16x32_bf16 v[38:41], v[124:127], v[116:119], v[38:41]
	v_mfma_f32_16x16x32_bf16 v[42:45], v[128:131], v[116:119], v[42:45]
	v_mfma_f32_16x16x32_bf16 v[30:33], v[132:135], v[116:119], v[30:33]
	v_lshl_add_u64 v[116:117], v[14:15], 0, s[4:5]
	v_lshl_add_u64 v[118:119], v[16:17], 0, s[4:5]
	s_mov_b64 s[4:5], 0x780
	v_lshl_add_u64 v[2:3], v[2:3], 0, s[4:5]
	v_lshl_add_u64 v[4:5], v[4:5], 0, s[4:5]
	global_load_lds_dwordx4 v[2:3], off
	s_mov_b32 m0, s26
	v_lshl_add_u64 v[6:7], v[6:7], 0, s[4:5]
	global_load_lds_dwordx4 v[4:5], off
	s_mov_b32 m0, s28
	v_lshl_add_u64 v[8:9], v[10:11], 0, s[4:5]
	global_load_lds_dwordx4 v[6:7], off
	s_mov_b32 m0, s29
	v_mfma_f32_16x16x32_bf16 v[50:53], v[120:123], v[96:99], v[52:55]
	global_load_lds_dwordx4 v[8:9], off
	s_mov_b32 m0, s36
	v_mfma_f32_16x16x32_bf16 v[54:57], v[124:127], v[96:99], v[56:59]
	v_readlane_b32 s4, v253, 36
	v_readlane_b32 s18, v253, 50
	v_readlane_b32 s19, v253, 51
	v_mfma_f32_16x16x32_bf16 v[58:61], v[128:131], v[96:99], v[60:63]
	s_movk_i32 s4, 0xc0
	s_mov_b64 s[26:27], s[72:73]
	s_mov_b32 s28, s94
	v_mfma_f32_16x16x32_bf16 v[46:49], v[132:135], v[96:99], v[46:49]
	v_readlane_b32 s5, v253, 37
	v_readlane_b32 s6, v253, 38
	v_readlane_b32 s7, v253, 39
	v_mfma_f32_16x16x32_bf16 v[62:65], v[120:123], v[100:103], v[68:71]
	v_readlane_b32 s8, v253, 40
	v_readlane_b32 s9, v253, 41
	v_readlane_b32 s10, v253, 42
	v_mfma_f32_16x16x32_bf16 v[68:71], v[124:127], v[100:103], v[76:79]
	v_readlane_b32 s11, v253, 43
	v_readlane_b32 s12, v253, 44
	v_readlane_b32 s13, v253, 45
	v_mfma_f32_16x16x32_bf16 v[76:79], v[128:131], v[100:103], v[80:83]
	v_readlane_b32 s14, v253, 46
	v_readlane_b32 s15, v253, 47
	v_readlane_b32 s16, v253, 48
	v_mfma_f32_16x16x32_bf16 v[22:25], v[132:135], v[100:103], v[22:25]
	v_readlane_b32 s17, v253, 49
	v_mfma_f32_16x16x32_bf16 v[80:83], v[120:123], v[104:107], v[84:87]
	v_mfma_f32_16x16x32_bf16 v[84:87], v[124:127], v[104:107], v[88:91]
	v_mfma_f32_16x16x32_bf16 v[88:91], v[128:131], v[104:107], v[92:95]
	v_mfma_f32_16x16x32_bf16 v[26:29], v[132:135], v[104:107], v[26:29]
	ds_read_b128 v[2:5], v18
	ds_read_b128 v[6:9], v18 offset:2048
	ds_read_b128 v[10:13], v18 offset:4096
	ds_read_b128 v[14:17], v18 offset:6144
	ds_read_b128 v[92:95], v19 offset:16384
	ds_read_b128 v[96:99], v19 offset:18432
	ds_read_b128 v[100:103], v19 offset:20480
	ds_read_b128 v[104:107], v19 offset:22528
	global_load_lds_dwordx4 v[72:73], off
	s_mov_b32 m0, s37
	s_waitcnt lgkmcnt(0)
	v_mfma_f32_16x16x32_bf16 v[50:53], v[92:95], v[2:5], v[50:53]
	global_load_lds_dwordx4 v[108:109], off
	s_mov_b32 m0, s38
	v_mfma_f32_16x16x32_bf16 v[54:57], v[96:99], v[2:5], v[54:57]
	global_load_lds_dwordx4 v[116:117], off
	s_mov_b32 m0, s39
	v_mfma_f32_16x16x32_bf16 v[58:61], v[100:103], v[2:5], v[58:61]
	global_load_lds_dwordx4 v[118:119], off
	v_mfma_f32_16x16x32_bf16 v[2:5], v[104:107], v[2:5], v[46:49]
	v_mfma_f32_16x16x32_bf16 v[46:49], v[92:95], v[6:9], v[62:65]
	v_mfma_f32_16x16x32_bf16 v[62:65], v[96:99], v[6:9], v[68:71]
	v_mfma_f32_16x16x32_bf16 v[68:71], v[100:103], v[6:9], v[76:79]
	v_mfma_f32_16x16x32_bf16 v[6:9], v[104:107], v[6:9], v[22:25]
	v_mfma_f32_16x16x32_bf16 v[22:25], v[92:95], v[10:13], v[80:83]
	v_mfma_f32_16x16x32_bf16 v[76:79], v[96:99], v[10:13], v[84:87]
	v_mfma_f32_16x16x32_bf16 v[80:83], v[100:103], v[10:13], v[88:91]
	v_mfma_f32_16x16x32_bf16 v[10:13], v[104:107], v[10:13], v[26:29]
	v_mfma_f32_16x16x32_bf16 v[26:29], v[92:95], v[14:17], v[34:37]
	v_mfma_f32_16x16x32_bf16 v[34:37], v[96:99], v[14:17], v[38:41]
	v_mfma_f32_16x16x32_bf16 v[38:41], v[100:103], v[14:17], v[42:45]
	v_mfma_f32_16x16x32_bf16 v[14:17], v[104:107], v[14:17], v[30:33]
	s_nop 2
	ds_read_b128 v[30:33], v20
	ds_read_b128 v[42:45], v20 offset:2048
	ds_read_b128 v[84:87], v20 offset:4096
	ds_read_b128 v[88:91], v20 offset:6144
	ds_read_b128 v[92:95], v21 offset:16384
	ds_read_b128 v[96:99], v21 offset:18432
	ds_read_b128 v[100:103], v21 offset:20480
	ds_read_b128 v[104:107], v21 offset:22528
	s_waitcnt vmcnt(0)
	s_waitcnt vmcnt(0) lgkmcnt(0)
	v_mfma_f32_16x16x32_bf16 v[50:53], v[92:95], v[30:33], v[50:53]
	s_barrier
; template <class Epi>
; DI void gemm_tile(const bf16_t* __restrict__ A, int lda, const bf16_t* __restrict__ Bt, int ldb, int K, int row0, int col0, char* lds, const Epi& epi) {
;     ...
;       for (int m = 0; m < 4; ++m) a[m] = *(const bf16x8*)(sa + m * 2048 + co);
; #pragma unroll
;       for (int n = 0; n < 4; ++n) b[n] = *(const bf16x8*)(sb + n * 2048 + co);
; #pragma unroll
;       for (int m = 0; m < 4; ++m)
; #pragma unroll
;         for (int n = 0; n < 4; ++n) acc[m][n] = __builtin_amdgcn_mfma_f32_16x16x32_bf16(b[n], a[m], acc[m][n], 0, 0, 0);
;   DI void operator()(const f32x4 (&acc)[4][4], int r0, int c0, int fr, int fq) const {
;     ...
; #pragma unroll
;     for (int m = 0; m < 4; ++m) {
;       const int row = r0 + m * 16 + fr; const float rs = rsqrtf(rstd[row] * (1.f / 256.f) + EPSF);
;       float ss = 0.f;
; #pragma unroll
;       for (int n = 0; n < 4; ++n)
; #pragma unroll
;         for (int j = 0; j < 4; ++j) { float v = acc[m][n][j] * rs; ss += v * v; }
;       ss += __shfl_xor(ss, 16); ss += __shfl_xor(ss, 32);
;       const float inv = rsqrtf(ss * (1.f / 64.f) + EPSF) * rs;
	v_mov_b32_e32 v186, v66
	v_ashrrev_i32_e32 v187, 31, v66
	v_lshl_add_u64 v[186:187], v[186:187], 2, s[20:21]
	global_load_dword v164, v[186:187], off
	global_load_dword v165, v[186:187], off offset:64
	global_load_dword v166, v[186:187], off offset:128
	global_load_dword v167, v[186:187], off offset:192
	v_lshlrev_b32_e32 v184, 4, v75
	global_load_dwordx4 v[168:171], v184, s[44:45]
	global_load_dwordx4 v[172:175], v184, s[44:45] offset:64
	global_load_dwordx4 v[176:179], v184, s[44:45] offset:128
	global_load_dwordx4 v[180:183], v184, s[44:45] offset:192
	v_mfma_f32_16x16x32_bf16 v[54:57], v[96:99], v[30:33], v[54:57]
	v_mfma_f32_16x16x32_bf16 v[58:61], v[100:103], v[30:33], v[58:61]
	v_mfma_f32_16x16x32_bf16 v[2:5], v[104:107], v[30:33], v[2:5]
	v_mfma_f32_16x16x32_bf16 v[30:33], v[92:95], v[42:45], v[46:49]
	v_mfma_f32_16x16x32_bf16 v[46:49], v[96:99], v[42:45], v[62:65]
	v_mfma_f32_16x16x32_bf16 v[62:65], v[100:103], v[42:45], v[68:71]
	v_mfma_f32_16x16x32_bf16 v[6:9], v[104:107], v[42:45], v[6:9]
	v_mfma_f32_16x16x32_bf16 v[22:25], v[92:95], v[84:87], v[22:25]
	v_mfma_f32_16x16x32_bf16 v[42:45], v[96:99], v[84:87], v[76:79]
	v_mfma_f32_16x16x32_bf16 v[68:71], v[100:103], v[84:87], v[80:83]
	v_mfma_f32_16x16x32_bf16 v[10:13], v[104:107], v[84:87], v[10:13]
	v_mfma_f32_16x16x32_bf16 v[26:29], v[92:95], v[88:91], v[26:29]
	v_mfma_f32_16x16x32_bf16 v[34:37], v[96:99], v[88:91], v[34:37]
	v_mfma_f32_16x16x32_bf16 v[38:41], v[100:103], v[88:91], v[38:41]
	v_mfma_f32_16x16x32_bf16 v[14:17], v[104:107], v[88:91], v[14:17]
	ds_read_b128 v[76:79], v19 offset:55296
	ds_read_b128 v[80:83], v19 offset:53248
	ds_read_b128 v[84:87], v19 offset:51200
	ds_read_b128 v[88:91], v19 offset:49152
	ds_read_b128 v[92:95], v18 offset:38912
	ds_read_b128 v[96:99], v18 offset:36864
	ds_read_b128 v[100:103], v18 offset:34816
	ds_read_b128 v[104:107], v18 offset:32768
	s_waitcnt lgkmcnt(0)
	v_mfma_f32_16x16x32_bf16 v[50:53], v[88:91], v[104:107], v[50:53]
	v_mfma_f32_16x16x32_bf16 v[54:57], v[84:87], v[104:107], v[54:57]
	v_mfma_f32_16x16x32_bf16 v[116:119], v[80:83], v[104:107], v[58:61]
	v_mfma_f32_16x16x32_bf16 v[2:5], v[76:79], v[104:107], v[2:5]
	v_mfma_f32_16x16x32_bf16 v[30:33], v[88:91], v[100:103], v[30:33]
	v_mfma_f32_16x16x32_bf16 v[104:107], v[84:87], v[100:103], v[46:49]
	v_mfma_f32_16x16x32_bf16 v[120:123], v[80:83], v[100:103], v[62:65]
	v_mfma_f32_16x16x32_bf16 v[6:9], v[76:79], v[100:103], v[6:9]
	v_mfma_f32_16x16x32_bf16 v[22:25], v[88:91], v[96:99], v[22:25]
	v_mfma_f32_16x16x32_bf16 v[100:103], v[84:87], v[96:99], v[42:45]
	v_mfma_f32_16x16x32_bf16 v[68:71], v[80:83], v[96:99], v[68:71]
	v_mfma_f32_16x16x32_bf16 v[10:13], v[76:79], v[96:99], v[10:13]
	v_mfma_f32_16x16x32_bf16 v[88:91], v[88:91], v[92:95], v[26:29]
	v_mfma_f32_16x16x32_bf16 v[84:87], v[84:87], v[92:95], v[34:37]
	v_mfma_f32_16x16x32_bf16 v[80:83], v[80:83], v[92:95], v[38:41]
	v_mfma_f32_16x16x32_bf16 v[76:79], v[76:79], v[92:95], v[14:17]
	ds_read_b128 v[92:95], v21 offset:55296
	ds_read_b128 v[96:99], v21 offset:53248
	ds_read_b128 v[124:127], v21 offset:51200
	ds_read_b128 v[14:17], v21 offset:49152
	ds_read_b128 v[128:131], v20 offset:38912
	ds_read_b128 v[132:135], v20 offset:36864
	ds_read_b128 v[26:29], v20 offset:34816
	ds_read_b128 v[18:21], v20 offset:32768
	s_waitcnt lgkmcnt(1)
	v_mfma_f32_16x16x32_bf16 v[46:49], v[14:17], v[26:29], v[30:33]
	v_mfma_f32_16x16x32_bf16 v[30:33], v[14:17], v[132:135], v[22:25]
	v_mfma_f32_16x16x32_bf16 v[22:25], v[96:99], v[132:135], v[68:71]
	s_nop 2
	v_and_b32_e32 v68, 64, v147
	v_add_u32_e32 v68, 64, v68
	v_cmp_lt_i32_e32 vcc, v67, v68
	s_waitcnt lgkmcnt(0)
	v_mfma_f32_16x16x32_bf16 v[62:65], v[14:17], v[18:21], v[50:53]
	v_cndmask_b32_e32 v67, v147, v67, vcc
	v_lshlrev_b32_e32 v71, 2, v67
	v_xor_b32_e32 v67, 32, v147
	v_cmp_lt_i32_e32 vcc, v67, v68
	v_mfma_f32_16x16x32_bf16 v[58:61], v[124:127], v[18:21], v[54:57]
	s_nop 0
	v_cndmask_b32_e32 v67, v147, v67, vcc
	v_lshlrev_b32_e32 v74, 2, v67
	v_ashrrev_i32_e32 v67, 31, v66
	v_lshl_add_u64 v[68:69], v[66:67], 2, s[20:21]
	v_mfma_f32_16x16x32_bf16 v[54:57], v[96:99], v[18:21], v[116:119]
	s_waitcnt vmcnt(0)
	v_mov_b32_e32 v67, v164
	v_fmamk_f32 v67, v67, 0x3b800000, v143
	v_cmp_gt_f32_e32 vcc, s53, v67
	v_mul_f32_e32 v68, 0x4b800000, v67
	v_mfma_f32_16x16x32_bf16 v[50:53], v[92:95], v[18:21], v[2:5]
	v_cndmask_b32_e32 v67, v67, v68, vcc
	v_rsq_f32_e32 v67, v67
	v_mfma_f32_16x16x32_bf16 v[2:5], v[92:95], v[128:131], v[76:79]
	v_mul_f32_e32 v68, 0x45800000, v67
	v_cndmask_b32_e32 v68, v67, v68, vcc
	v_mul_f32_e32 v69, v63, v68
	v_mul_f32_e32 v67, v62, v68
	v_mul_f32_e32 v69, v69, v69
	v_fmac_f32_e32 v69, v67, v67
	v_mul_f32_e32 v67, v64, v68
	v_fmac_f32_e32 v69, v67, v67
	v_mul_f32_e32 v67, v65, v68
	v_fmac_f32_e32 v69, v67, v67
	v_mul_f32_e32 v67, v58, v68
	v_fmac_f32_e32 v69, v67, v67
	v_mul_f32_e32 v67, v59, v68
	v_fmac_f32_e32 v69, v67, v67
	v_mul_f32_e32 v67, v60, v68
	v_fmac_f32_e32 v69, v67, v67
	v_mul_f32_e32 v67, v61, v68
	v_fmac_f32_e32 v69, v67, v67
	v_pk_mul_f32 v[72:73], v[54:55], v[68:69] op_sel_hi:[1,0]
	v_mfma_f32_16x16x32_bf16 v[42:45], v[124:127], v[26:29], v[104:107]
	v_mul_f32_e64 v72, v72, v72
	v_mul_f32_e64 v73, v73, v73
	v_add_f32_e32 v67, v72, v69
	v_add_f32_e32 v67, v73, v67
	v_pk_mul_f32 v[72:73], v[56:57], v[68:69] op_sel_hi:[1,0]
	v_mfma_f32_16x16x32_bf16 v[38:41], v[96:99], v[26:29], v[120:123]
	v_mul_f32_e64 v72, v72, v72
	v_mul_f32_e64 v73, v73, v73
	v_add_f32_e32 v67, v72, v67
	v_add_f32_e32 v67, v73, v67
	v_pk_mul_f32 v[72:73], v[50:51], v[68:69] op_sel_hi:[1,0]
	v_mfma_f32_16x16x32_bf16 v[34:37], v[92:95], v[26:29], v[6:9]
	v_mul_f32_e64 v72, v72, v72
	v_mul_f32_e64 v73, v73, v73
	v_add_f32_e32 v67, v72, v67
	v_add_f32_e32 v67, v73, v67
	v_pk_mul_f32 v[72:73], v[52:53], v[68:69] op_sel_hi:[1,0]
	v_mfma_f32_16x16x32_bf16 v[26:29], v[124:127], v[132:135], v[100:103]
	v_mul_f32_e64 v72, v72, v72
	v_mul_f32_e64 v73, v73, v73
	v_add_f32_e32 v67, v72, v67
	v_add_f32_e32 v67, v73, v67
	ds_bpermute_b32 v69, v71, v67
	v_mfma_f32_16x16x32_bf16 v[18:21], v[92:95], v[132:135], v[10:13]
	s_waitcnt lgkmcnt(0)
; DI unsigned pk_bf16(float lo, float hi) { f32x2 v = {lo, hi}; bf16v2 b = __builtin_convertvector(v, bf16v2); return __builtin_bit_cast(unsigned, b); }
;   DI void operator()(const f32x4 (&acc)[4][4], int r0, int c0, int fr, int fq) const {
;     ...
; #pragma unroll
;     for (int m = 0; m < 4; ++m) {
;       const int row = r0 + m * 16 + fr; const float rs = rsqrtf(rstd[row] * (1.f / 256.f) + EPSF);
;       float ss = 0.f;
; #pragma unroll
;       for (int n = 0; n < 4; ++n)
; #pragma unroll
;         for (int j = 0; j < 4; ++j) { float v = acc[m][n][j] * rs; ss += v * v; }
;       ss += __shfl_xor(ss, 16); ss += __shfl_xor(ss, 32);
;       const float inv = rsqrtf(ss * (1.f / 64.f) + EPSF) * rs;
;       const int b = row / TB, s = row % TB;
;       bf16_t* dst = Kt + ((size_t)(b * 6 + h) * TB + s) * 96;
; #pragma unroll
;       for (int n = 0; n < 4; ++n) {
;         const int d = n * 16 + fq * 4; f32x4 g = *(const f32x4*)(gk + d);
;         u32x2 v = {pk_bf16(acc[m][n][0] * inv * g[0], acc[m][n][1] * inv * g[1]), pk_bf16(acc[m][n][2] * inv * g[2], acc[m][n][3] * inv * g[3])};
;         *(u32x2*)(dst + d) = v;
;       }
	v_add_f32_e32 v67, v67, v69
	ds_bpermute_b32 v69, v74, v67
	v_mfma_f32_16x16x32_bf16 v[14:17], v[14:17], v[128:131], v[88:91]
	s_waitcnt lgkmcnt(0)
	v_add_f32_e32 v67, v67, v69
	v_fmamk_f32 v67, v67, 0x3c800000, v143
	v_cmp_gt_f32_e32 vcc, s53, v67
	v_mul_f32_e32 v69, 0x4b800000, v67
	v_mfma_f32_16x16x32_bf16 v[10:13], v[124:127], v[128:131], v[84:87]
	v_cndmask_b32_e32 v67, v67, v69, vcc
	v_rsq_f32_e32 v67, v67
	v_mfma_f32_16x16x32_bf16 v[6:9], v[96:99], v[128:131], v[80:83]
	v_mul_f32_e32 v69, 0x45800000, v67
	v_cndmask_b32_e32 v67, v67, v69, vcc
	v_mul_f32_e32 v70, v68, v67
	v_mul_hi_i32 v67, v66, s47
	v_lshrrev_b32_e32 v68, 31, v67
	v_ashrrev_i32_e32 v67, 9, v67
	v_add_u32_e32 v67, v67, v68
	v_mul_i32_i24_e32 v68, 0x900, v67
	v_sub_u32_e32 v68, v66, v68
	v_mad_i32_i24 v67, v67, 6, v1
	v_ashrrev_i32_e32 v69, 31, v68
	v_mad_i64_i32 v[76:77], s[0:1], v67, s3, v[68:69]
	v_mov_b64_e32 v[68:69], s[18:19]
	v_mad_u64_u32 v[72:73], s[0:1], v76, s4, v[68:69]
	v_lshlrev_b32_e32 v67, 4, v75
	v_mad_i32_i24 v73, v77, s4, v73
	v_pk_mul_f32 v[62:63], v[62:63], v[70:71] op_sel_hi:[1,0]
	v_pk_mul_f32 v[64:65], v[64:65], v[70:71] op_sel_hi:[1,0]
	v_lshl_add_u64 v[72:73], v[72:73], 0, v[110:111]
	v_pk_mul_f32 v[58:59], v[58:59], v[70:71] op_sel_hi:[1,0]
	v_pk_mul_f32 v[60:61], v[60:61], v[70:71] op_sel_hi:[1,0]
	v_pk_mul_f32 v[54:55], v[54:55], v[70:71] op_sel_hi:[1,0]
	v_pk_mul_f32 v[56:57], v[56:57], v[70:71] op_sel_hi:[1,0]
	v_pk_mul_f32 v[50:51], v[50:51], v[70:71] op_sel_hi:[1,0]
	v_pk_mul_f32 v[52:53], v[52:53], v[70:71] op_sel_hi:[1,0]
	v_pk_mul_f32 v[62:63], v[168:169], v[62:63]
	v_pk_mul_f32 v[64:65], v[170:171], v[64:65]
	v_cvt_pk_bf16_f32 v62, v62, v63
	v_cvt_pk_bf16_f32 v63, v64, v65
	global_store_dwordx2 v[72:73], v[62:63], off
	v_pk_mul_f32 v[58:59], v[172:173], v[58:59]
	v_pk_mul_f32 v[60:61], v[174:175], v[60:61]
	v_cvt_pk_bf16_f32 v58, v58, v59
	v_cvt_pk_bf16_f32 v59, v60, v61
	global_store_dwordx2 v[72:73], v[58:59], off offset:32
	v_pk_mul_f32 v[54:55], v[176:177], v[54:55]
	v_pk_mul_f32 v[56:57], v[178:179], v[56:57]
	v_cvt_pk_bf16_f32 v54, v54, v55
	v_cvt_pk_bf16_f32 v55, v56, v57
	global_store_dwordx2 v[72:73], v[54:55], off offset:64
	v_pk_mul_f32 v[50:51], v[180:181], v[50:51]
	v_pk_mul_f32 v[52:53], v[182:183], v[52:53]
	v_cvt_pk_bf16_f32 v50, v50, v51
	v_cvt_pk_bf16_f32 v51, v52, v53
	v_or_b32_e32 v52, 16, v66
	v_ashrrev_i32_e32 v53, 31, v52
	global_store_dwordx2 v[72:73], v[50:51], off offset:96
	v_lshl_add_u64 v[50:51], v[52:53], 2, s[20:21]
	v_mov_b32_e32 v50, v165
	v_fmamk_f32 v50, v50, 0x3b800000, v143
	v_cmp_gt_f32_e32 vcc, s53, v50
	v_mul_f32_e32 v51, 0x4b800000, v50
	s_nop 0
	v_cndmask_b32_e32 v50, v50, v51, vcc
	v_rsq_f32_e32 v50, v50
	s_nop 0
	v_mul_f32_e32 v51, 0x45800000, v50
	v_cndmask_b32_e32 v50, v50, v51, vcc
	v_mul_f32_e32 v53, v47, v50
	v_mul_f32_e32 v51, v46, v50
	v_mul_f32_e32 v53, v53, v53
	v_fmac_f32_e32 v53, v51, v51
	v_mul_f32_e32 v51, v48, v50
	v_fmac_f32_e32 v53, v51, v51
	v_mul_f32_e32 v51, v49, v50
	v_fmac_f32_e32 v53, v51, v51
	v_mul_f32_e32 v51, v42, v50
	v_fmac_f32_e32 v53, v51, v51
	v_mul_f32_e32 v51, v43, v50
	v_fmac_f32_e32 v53, v51, v51
	v_mul_f32_e32 v51, v44, v50
	v_fmac_f32_e32 v53, v51, v51
	v_mul_f32_e32 v51, v45, v50
	v_pk_mul_f32 v[54:55], v[38:39], v[50:51] op_sel_hi:[1,0]
	v_fmac_f32_e32 v53, v51, v51
	v_pk_mul_f32 v[54:55], v[54:55], v[54:55]
	s_nop 0
	v_add_f32_e32 v51, v54, v53
	v_add_f32_e32 v51, v55, v51
	v_pk_mul_f32 v[54:55], v[40:41], v[50:51] op_sel_hi:[1,0]
	s_nop 0
	v_pk_mul_f32 v[54:55], v[54:55], v[54:55]
	s_nop 0
	v_add_f32_e32 v51, v54, v51
	v_add_f32_e32 v51, v55, v51
	v_pk_mul_f32 v[54:55], v[34:35], v[50:51] op_sel_hi:[1,0]
	s_nop 0
	v_pk_mul_f32 v[54:55], v[54:55], v[54:55]
	s_nop 0
	v_add_f32_e32 v51, v54, v51
	v_add_f32_e32 v51, v55, v51
	v_pk_mul_f32 v[54:55], v[36:37], v[50:51] op_sel_hi:[1,0]
	s_nop 0
	v_pk_mul_f32 v[54:55], v[54:55], v[54:55]
	s_nop 0
	v_add_f32_e32 v51, v54, v51
	v_add_f32_e32 v51, v55, v51
	ds_bpermute_b32 v53, v71, v51
	s_waitcnt lgkmcnt(0)
	v_add_f32_e32 v51, v51, v53
	ds_bpermute_b32 v53, v74, v51
	s_waitcnt lgkmcnt(0)
	v_add_f32_e32 v51, v51, v53
	v_fmamk_f32 v51, v51, 0x3c800000, v143
	v_cmp_gt_f32_e32 vcc, s53, v51
	v_mul_f32_e32 v53, 0x4b800000, v51
	s_nop 0
	v_cndmask_b32_e32 v51, v51, v53, vcc
	v_rsq_f32_e32 v51, v51
	s_nop 0
	v_mul_f32_e32 v53, 0x45800000, v51
	v_cndmask_b32_e32 v51, v51, v53, vcc
	v_mul_f32_e32 v50, v50, v51
	v_mul_hi_i32 v51, v52, s47
	v_lshrrev_b32_e32 v53, 31, v51
	v_ashrrev_i32_e32 v51, 9, v51
	v_add_u32_e32 v51, v51, v53
	v_mul_i32_i24_e32 v53, 0x900, v51
	v_sub_u32_e32 v52, v52, v53
	v_mad_i32_i24 v51, v51, 6, v1
	v_ashrrev_i32_e32 v53, 31, v52
	v_mad_i64_i32 v[54:55], s[0:1], v51, s3, v[52:53]
	v_mad_u64_u32 v[52:53], s[0:1], v54, s4, v[68:69]
	v_mad_i32_i24 v53, v55, s4, v53
	v_pk_mul_f32 v[46:47], v[46:47], v[50:51] op_sel_hi:[1,0]
	v_pk_mul_f32 v[48:49], v[48:49], v[50:51] op_sel_hi:[1,0]
	v_lshl_add_u64 v[52:53], v[52:53], 0, v[110:111]
	v_pk_mul_f32 v[42:43], v[42:43], v[50:51] op_sel_hi:[1,0]
	v_pk_mul_f32 v[44:45], v[44:45], v[50:51] op_sel_hi:[1,0]
	v_pk_mul_f32 v[38:39], v[38:39], v[50:51] op_sel_hi:[1,0]
	v_pk_mul_f32 v[40:41], v[40:41], v[50:51] op_sel_hi:[1,0]
	v_pk_mul_f32 v[34:35], v[34:35], v[50:51] op_sel_hi:[1,0]
	v_pk_mul_f32 v[36:37], v[36:37], v[50:51] op_sel_hi:[1,0]
	v_pk_mul_f32 v[46:47], v[168:169], v[46:47]
	v_pk_mul_f32 v[48:49], v[170:171], v[48:49]
	v_cvt_pk_bf16_f32 v46, v46, v47
	v_cvt_pk_bf16_f32 v47, v48, v49
	global_store_dwordx2 v[52:53], v[46:47], off
	v_pk_mul_f32 v[42:43], v[172:173], v[42:43]
	v_pk_mul_f32 v[44:45], v[174:175], v[44:45]
	v_cvt_pk_bf16_f32 v42, v42, v43
; DI unsigned pk_bf16(float lo, float hi) { f32x2 v = {lo, hi}; bf16v2 b = __builtin_convertvector(v, bf16v2); return __builtin_bit_cast(unsigned, b); }
;   DI void operator()(const f32x4 (&acc)[4][4], int r0, int c0, int fr, int fq) const {
;     ...
; #pragma unroll
;     for (int m = 0; m < 4; ++m) {
;       const int row = r0 + m * 16 + fr; const float rs = rsqrtf(rstd[row] * (1.f / 256.f) + EPSF);
;       float ss = 0.f;
; #pragma unroll
;       for (int n = 0; n < 4; ++n)
; #pragma unroll
;         for (int j = 0; j < 4; ++j) { float v = acc[m][n][j] * rs; ss += v * v; }
;       ss += __shfl_xor(ss, 16); ss += __shfl_xor(ss, 32);
;       const float inv = rsqrtf(ss * (1.f / 64.f) + EPSF) * rs;
;       const int b = row / TB, s = row % TB;
;       bf16_t* dst = Kt + ((size_t)(b * 6 + h) * TB + s) * 96;
; #pragma unroll
;       for (int n = 0; n < 4; ++n) {
;         const int d = n * 16 + fq * 4; f32x4 g = *(const f32x4*)(gk + d);
;         u32x2 v = {pk_bf16(acc[m][n][0] * inv * g[0], acc[m][n][1] * inv * g[1]), pk_bf16(acc[m][n][2] * inv * g[2], acc[m][n][3] * inv * g[3])};
;         *(u32x2*)(dst + d) = v;
;       }
	v_cvt_pk_bf16_f32 v43, v44, v45
	global_store_dwordx2 v[52:53], v[42:43], off offset:32
	v_pk_mul_f32 v[38:39], v[176:177], v[38:39]
	v_pk_mul_f32 v[40:41], v[178:179], v[40:41]
	v_cvt_pk_bf16_f32 v38, v38, v39
	v_cvt_pk_bf16_f32 v39, v40, v41
	global_store_dwordx2 v[52:53], v[38:39], off offset:64
	v_pk_mul_f32 v[34:35], v[180:181], v[34:35]
	v_pk_mul_f32 v[36:37], v[182:183], v[36:37]
	v_cvt_pk_bf16_f32 v34, v34, v35
	v_cvt_pk_bf16_f32 v35, v36, v37
	v_or_b32_e32 v36, 32, v66
	v_ashrrev_i32_e32 v37, 31, v36
	global_store_dwordx2 v[52:53], v[34:35], off offset:96
	v_lshl_add_u64 v[34:35], v[36:37], 2, s[20:21]
	v_mov_b32_e32 v34, v166
	v_fmamk_f32 v34, v34, 0x3b800000, v143
	v_cmp_gt_f32_e32 vcc, s53, v34
	v_mul_f32_e32 v35, 0x4b800000, v34
	s_nop 0
	v_cndmask_b32_e32 v34, v34, v35, vcc
	v_rsq_f32_e32 v34, v34
	s_nop 0
	v_mul_f32_e32 v35, 0x45800000, v34
	v_cndmask_b32_e32 v34, v34, v35, vcc
	v_mul_f32_e32 v37, v31, v34
	v_mul_f32_e32 v35, v30, v34
	v_mul_f32_e32 v37, v37, v37
	v_fmac_f32_e32 v37, v35, v35
	v_mul_f32_e32 v35, v32, v34
	v_fmac_f32_e32 v37, v35, v35
	v_mul_f32_e32 v35, v33, v34
	v_fmac_f32_e32 v37, v35, v35
	v_mul_f32_e32 v35, v26, v34
	v_fmac_f32_e32 v37, v35, v35
	v_mul_f32_e32 v35, v27, v34
	v_fmac_f32_e32 v37, v35, v35
	v_mul_f32_e32 v35, v28, v34
	v_fmac_f32_e32 v37, v35, v35
	v_mul_f32_e32 v35, v29, v34
	v_pk_mul_f32 v[38:39], v[22:23], v[34:35] op_sel_hi:[1,0]
	v_fmac_f32_e32 v37, v35, v35
	v_pk_mul_f32 v[38:39], v[38:39], v[38:39]
	s_nop 0
	v_add_f32_e32 v35, v38, v37
	v_add_f32_e32 v35, v39, v35
	v_pk_mul_f32 v[38:39], v[24:25], v[34:35] op_sel_hi:[1,0]
	s_nop 0
	v_pk_mul_f32 v[38:39], v[38:39], v[38:39]
	s_nop 0
	v_add_f32_e32 v35, v38, v35
	v_add_f32_e32 v35, v39, v35
	v_pk_mul_f32 v[38:39], v[18:19], v[34:35] op_sel_hi:[1,0]
	s_nop 0
	v_pk_mul_f32 v[38:39], v[38:39], v[38:39]
	s_nop 0
	v_add_f32_e32 v35, v38, v35
	v_add_f32_e32 v35, v39, v35
	v_pk_mul_f32 v[38:39], v[20:21], v[34:35] op_sel_hi:[1,0]
	s_nop 0
	v_pk_mul_f32 v[38:39], v[38:39], v[38:39]
	s_nop 0
	v_add_f32_e32 v35, v38, v35
	v_add_f32_e32 v35, v39, v35
	ds_bpermute_b32 v37, v71, v35
	s_waitcnt lgkmcnt(0)
	v_add_f32_e32 v35, v35, v37
	ds_bpermute_b32 v37, v74, v35
	s_waitcnt lgkmcnt(0)
; DI unsigned pk_bf16(float lo, float hi) { f32x2 v = {lo, hi}; bf16v2 b = __builtin_convertvector(v, bf16v2); return __builtin_bit_cast(unsigned, b); }
;   DI void operator()(const f32x4 (&acc)[4][4], int r0, int c0, int fr, int fq) const {
;     ...
; #pragma unroll
;     for (int m = 0; m < 4; ++m) {
;       const int row = r0 + m * 16 + fr; const float rs = rsqrtf(rstd[row] * (1.f / 256.f) + EPSF);
;       float ss = 0.f;
; #pragma unroll
;       for (int n = 0; n < 4; ++n)
; #pragma unroll
;         for (int j = 0; j < 4; ++j) { float v = acc[m][n][j] * rs; ss += v * v; }
;       ss += __shfl_xor(ss, 16); ss += __shfl_xor(ss, 32);
;       const float inv = rsqrtf(ss * (1.f / 64.f) + EPSF) * rs;
;       const int b = row / TB, s = row % TB;
;       bf16_t* dst = Kt + ((size_t)(b * 6 + h) * TB + s) * 96;
; #pragma unroll
;       for (int n = 0; n < 4; ++n) {
;         const int d = n * 16 + fq * 4; f32x4 g = *(const f32x4*)(gk + d);
;         u32x2 v = {pk_bf16(acc[m][n][0] * inv * g[0], acc[m][n][1] * inv * g[1]), pk_bf16(acc[m][n][2] * inv * g[2], acc[m][n][3] * inv * g[3])};
;         *(u32x2*)(dst + d) = v;
;       }
	v_add_f32_e32 v35, v35, v37
	v_fmamk_f32 v35, v35, 0x3c800000, v143
	v_cmp_gt_f32_e32 vcc, s53, v35
	v_mul_f32_e32 v37, 0x4b800000, v35
	s_nop 0
	v_cndmask_b32_e32 v35, v35, v37, vcc
	v_rsq_f32_e32 v35, v35
	s_nop 0
	v_mul_f32_e32 v37, 0x45800000, v35
	v_cndmask_b32_e32 v35, v35, v37, vcc
	v_mul_f32_e32 v34, v34, v35
	v_mul_hi_i32 v35, v36, s47
	v_lshrrev_b32_e32 v37, 31, v35
	v_ashrrev_i32_e32 v35, 9, v35
	v_add_u32_e32 v35, v35, v37
	v_mul_i32_i24_e32 v37, 0x900, v35
	v_sub_u32_e32 v36, v36, v37
	v_mad_i32_i24 v35, v35, 6, v1
	v_ashrrev_i32_e32 v37, 31, v36
	v_mad_i64_i32 v[38:39], s[0:1], v35, s3, v[36:37]
	v_mad_u64_u32 v[36:37], s[0:1], v38, s4, v[68:69]
	v_mad_i32_i24 v37, v39, s4, v37
	v_pk_mul_f32 v[30:31], v[30:31], v[34:35] op_sel_hi:[1,0]
	v_pk_mul_f32 v[32:33], v[32:33], v[34:35] op_sel_hi:[1,0]
	v_lshl_add_u64 v[36:37], v[36:37], 0, v[110:111]
	v_pk_mul_f32 v[26:27], v[26:27], v[34:35] op_sel_hi:[1,0]
	v_pk_mul_f32 v[28:29], v[28:29], v[34:35] op_sel_hi:[1,0]
	v_pk_mul_f32 v[22:23], v[22:23], v[34:35] op_sel_hi:[1,0]
	v_pk_mul_f32 v[24:25], v[24:25], v[34:35] op_sel_hi:[1,0]
	v_pk_mul_f32 v[18:19], v[18:19], v[34:35] op_sel_hi:[1,0]
	v_pk_mul_f32 v[20:21], v[20:21], v[34:35] op_sel_hi:[1,0]
	v_pk_mul_f32 v[30:31], v[168:169], v[30:31]
	v_pk_mul_f32 v[32:33], v[170:171], v[32:33]
	v_cvt_pk_bf16_f32 v30, v30, v31
	v_cvt_pk_bf16_f32 v31, v32, v33
	global_store_dwordx2 v[36:37], v[30:31], off
	v_pk_mul_f32 v[26:27], v[172:173], v[26:27]
	v_pk_mul_f32 v[28:29], v[174:175], v[28:29]
	v_cvt_pk_bf16_f32 v26, v26, v27
	v_cvt_pk_bf16_f32 v27, v28, v29
	global_store_dwordx2 v[36:37], v[26:27], off offset:32
	v_pk_mul_f32 v[22:23], v[176:177], v[22:23]
	v_pk_mul_f32 v[24:25], v[178:179], v[24:25]
	v_cvt_pk_bf16_f32 v22, v22, v23
	v_cvt_pk_bf16_f32 v23, v24, v25
	global_store_dwordx2 v[36:37], v[22:23], off offset:64
	v_pk_mul_f32 v[18:19], v[180:181], v[18:19]
	v_pk_mul_f32 v[20:21], v[182:183], v[20:21]
	v_cvt_pk_bf16_f32 v18, v18, v19
	v_cvt_pk_bf16_f32 v19, v20, v21
	v_or_b32_e32 v20, 48, v66
	v_ashrrev_i32_e32 v21, 31, v20
	global_store_dwordx2 v[36:37], v[18:19], off offset:96
	v_lshl_add_u64 v[18:19], v[20:21], 2, s[20:21]
	v_mov_b32_e32 v18, v167
	v_fmamk_f32 v18, v18, 0x3b800000, v143
	v_cmp_gt_f32_e32 vcc, s53, v18
	v_mul_f32_e32 v19, 0x4b800000, v18
	s_nop 0
	v_cndmask_b32_e32 v18, v18, v19, vcc
	v_rsq_f32_e32 v18, v18
	s_nop 0
	v_mul_f32_e32 v19, 0x45800000, v18
	v_cndmask_b32_e32 v18, v18, v19, vcc
	v_mul_f32_e32 v21, v15, v18
	v_mul_f32_e32 v19, v14, v18
	v_mul_f32_e32 v21, v21, v21
	v_fmac_f32_e32 v21, v19, v19
	v_mul_f32_e32 v19, v16, v18
	v_fmac_f32_e32 v21, v19, v19
	v_mul_f32_e32 v19, v17, v18
	v_fmac_f32_e32 v21, v19, v19
	v_mul_f32_e32 v19, v10, v18
	v_fmac_f32_e32 v21, v19, v19
	v_mul_f32_e32 v19, v11, v18
	v_fmac_f32_e32 v21, v19, v19
	v_mul_f32_e32 v19, v12, v18
	v_fmac_f32_e32 v21, v19, v19
	v_mul_f32_e32 v19, v13, v18
	v_pk_mul_f32 v[22:23], v[6:7], v[18:19] op_sel_hi:[1,0]
	v_fmac_f32_e32 v21, v19, v19
	v_pk_mul_f32 v[22:23], v[22:23], v[22:23]
	s_nop 0
	v_add_f32_e32 v19, v22, v21
	v_add_f32_e32 v19, v23, v19
	v_pk_mul_f32 v[22:23], v[8:9], v[18:19] op_sel_hi:[1,0]
	s_nop 0
	v_pk_mul_f32 v[22:23], v[22:23], v[22:23]
	s_nop 0
	v_add_f32_e32 v19, v22, v19
	v_add_f32_e32 v19, v23, v19
	v_pk_mul_f32 v[22:23], v[2:3], v[18:19] op_sel_hi:[1,0]
	s_nop 0
	v_pk_mul_f32 v[22:23], v[22:23], v[22:23]
	s_nop 0
	v_add_f32_e32 v19, v22, v19
	v_add_f32_e32 v19, v23, v19
	v_pk_mul_f32 v[22:23], v[4:5], v[18:19] op_sel_hi:[1,0]
	s_nop 0
	v_pk_mul_f32 v[22:23], v[22:23], v[22:23]
	s_nop 0
	v_add_f32_e32 v19, v22, v19
	v_add_f32_e32 v19, v23, v19
	ds_bpermute_b32 v21, v71, v19
	s_waitcnt lgkmcnt(0)
	v_add_f32_e32 v19, v19, v21
	ds_bpermute_b32 v21, v74, v19
	s_waitcnt lgkmcnt(0)
	v_add_f32_e32 v19, v19, v21
	v_fmamk_f32 v19, v19, 0x3c800000, v143
	v_cmp_gt_f32_e32 vcc, s53, v19
	v_mul_f32_e32 v21, 0x4b800000, v19
	s_nop 0
	v_cndmask_b32_e32 v19, v19, v21, vcc
	v_rsq_f32_e32 v19, v19
	s_nop 0
	v_mul_f32_e32 v21, 0x45800000, v19
	v_cndmask_b32_e32 v19, v19, v21, vcc
	v_mul_f32_e32 v18, v18, v19
	v_mul_hi_i32 v19, v20, s47
	v_lshrrev_b32_e32 v21, 31, v19
	v_ashrrev_i32_e32 v19, 9, v19
	v_add_u32_e32 v19, v19, v21
	v_mul_i32_i24_e32 v21, 0x900, v19
	v_sub_u32_e32 v20, v20, v21
	v_mad_i32_i24 v1, v19, 6, v1
	v_ashrrev_i32_e32 v21, 31, v20
	v_mad_i64_i32 v[22:23], s[0:1], v1, s3, v[20:21]
	v_mad_u64_u32 v[20:21], s[0:1], v22, s4, v[68:69]
	v_mad_i32_i24 v21, v23, s4, v21
	v_pk_mul_f32 v[14:15], v[14:15], v[18:19] op_sel_hi:[1,0]
	v_pk_mul_f32 v[16:17], v[16:17], v[18:19] op_sel_hi:[1,0]
	v_lshl_add_u64 v[20:21], v[20:21], 0, v[110:111]
	v_pk_mul_f32 v[10:11], v[10:11], v[18:19] op_sel_hi:[1,0]
	v_pk_mul_f32 v[12:13], v[12:13], v[18:19] op_sel_hi:[1,0]
	v_pk_mul_f32 v[6:7], v[6:7], v[18:19] op_sel_hi:[1,0]
	v_pk_mul_f32 v[8:9], v[8:9], v[18:19] op_sel_hi:[1,0]
	v_pk_mul_f32 v[2:3], v[2:3], v[18:19] op_sel_hi:[1,0]
	v_pk_mul_f32 v[4:5], v[4:5], v[18:19] op_sel_hi:[1,0]
	v_pk_mul_f32 v[14:15], v[168:169], v[14:15]
	v_pk_mul_f32 v[16:17], v[170:171], v[16:17]
	v_cvt_pk_bf16_f32 v14, v14, v15
	v_cvt_pk_bf16_f32 v15, v16, v17
	global_store_dwordx2 v[20:21], v[14:15], off
	v_pk_mul_f32 v[10:11], v[172:173], v[10:11]
	v_pk_mul_f32 v[12:13], v[174:175], v[12:13]
	v_cvt_pk_bf16_f32 v10, v10, v11
	v_cvt_pk_bf16_f32 v11, v12, v13
	global_store_dwordx2 v[20:21], v[10:11], off offset:32
	v_pk_mul_f32 v[6:7], v[176:177], v[6:7]
	v_pk_mul_f32 v[8:9], v[178:179], v[8:9]
	v_cvt_pk_bf16_f32 v6, v6, v7
	v_cvt_pk_bf16_f32 v7, v8, v9
	global_store_dwordx2 v[20:21], v[6:7], off offset:64
	v_pk_mul_f32 v[2:3], v[180:181], v[2:3]
	v_pk_mul_f32 v[4:5], v[182:183], v[4:5]
	v_cvt_pk_bf16_f32 v2, v2, v3
	v_cvt_pk_bf16_f32 v3, v4, v5
	global_store_dwordx2 v[20:21], v[2:3], off offset:96

; DI unsigned pk_bf16(float lo, float hi) { f32x2 v = {lo, hi}; bf16v2 b = __builtin_convertvector(v, bf16v2); return __builtin_bit_cast(unsigned, b); }
;   DI void operator()(const f32x4 (&acc)[4][4], int r0, int c0, int fr, int fq) const {
;     ...
;       const int h = c0 >> 6;
; #pragma unroll
;       for (int m = 0; m < 4; ++m) {
;         const int row = r0 + m * 16 + fr; const float rs = rsqrtf(rstd[row] * (1.f / 768.f) + EPSF);
;         float ss = 0.f;
; #pragma unroll
;         for (int n = 0; n < 4; ++n)
; #pragma unroll
;           for (int j = 0; j < 4; ++j) { float v = acc[m][n][j] * rs; ss += v * v; }
;         ss += __shfl_xor(ss, 16); ss += __shfl_xor(ss, 32);
;         const float inv = rsqrtf(ss * (1.f / 64.f) + EPSF) * rs * QSCALE;
;         const int b = row / TB, s = row % TB;
;         bf16_t* dst = Q + ((size_t)(b * 6 + h) * TB + s) * 96;
; #pragma unroll
;         for (int n = 0; n < 4; ++n) {
;           const int d = n * 16 + fq * 4; f32x4 g = *(const f32x4*)(gn + d);
;           u32x2 v = {pk_bf16(acc[m][n][0] * inv * g[0], acc[m][n][1] * inv * g[1]), pk_bf16(acc[m][n][2] * inv * g[2], acc[m][n][3] * inv * g[3])};
;           *(u32x2*)(dst + d) = v;
;         }
;       }
.LBB0_659:
	s_andn2_saveexec_b64 s[0:1], s[54:55]
	s_cbranch_execz .LBB0_510
	v_and_b32_e32 v67, 64, v147
	v_xor_b32_e32 v66, 16, v147
	v_add_u32_e32 v67, 64, v67
	v_cmp_lt_i32_e32 vcc, v66, v67
	v_ashrrev_i32_e32 v71, 31, v70
	global_load_dwordx4 v[80:83], v110, s[40:41]
	v_cndmask_b32_e32 v66, v147, v66, vcc
	v_lshlrev_b32_e32 v78, 2, v66
	v_xor_b32_e32 v66, 32, v147
	v_cmp_lt_i32_e32 vcc, v66, v67
	v_ashrrev_i32_e32 v1, 6, v75
	v_readlane_b32 s4, v253, 36
	v_cndmask_b32_e32 v66, v147, v66, vcc
	v_lshlrev_b32_e32 v79, 2, v66
	v_lshl_add_u64 v[66:67], v[70:71], 2, s[60:61]
	global_load_dword v68, v[66:67], off
	global_load_dword v165, v[66:67], off offset:64
	global_load_dword v166, v[66:67], off offset:128
	global_load_dword v167, v[66:67], off offset:192
	global_load_dwordx4 v[168:171], v110, s[40:41]
	global_load_dwordx4 v[172:175], v110, s[40:41] offset:64
	global_load_dwordx4 v[176:179], v110, s[40:41] offset:128
	global_load_dwordx4 v[180:183], v110, s[40:41] offset:192
	s_movk_i32 s20, 0x900
	v_readlane_b32 s16, v253, 48
	v_readlane_b32 s17, v253, 49
	s_movk_i32 s4, 0xc0
	v_readlane_b32 s5, v253, 37
	v_readlane_b32 s6, v253, 38
	v_readlane_b32 s7, v253, 39
	v_readlane_b32 s8, v253, 40
	v_readlane_b32 s9, v253, 41
	v_readlane_b32 s10, v253, 42
	v_readlane_b32 s11, v253, 43
	v_readlane_b32 s12, v253, 44
	v_readlane_b32 s13, v253, 45
	v_readlane_b32 s14, v253, 46
	v_readlane_b32 s15, v253, 47
	v_readlane_b32 s18, v253, 50
	v_readlane_b32 s19, v253, 51
	s_waitcnt vmcnt(0)
	v_fmamk_f32 v68, v68, 0x3aaaaaab, v143
	v_cmp_gt_f32_e32 vcc, s53, v68
	v_mul_f32_e32 v69, 0x4b800000, v68
	s_nop 0
	v_cndmask_b32_e32 v68, v68, v69, vcc
	v_rsq_f32_e32 v68, v68
	s_nop 0
	v_mul_f32_e32 v69, 0x45800000, v68
	v_cndmask_b32_e32 v68, v68, v69, vcc
	v_mul_f32_e32 v71, v63, v68
	v_mul_f32_e32 v69, v62, v68
	v_mul_f32_e32 v71, v71, v71
	v_fmac_f32_e32 v71, v69, v69
	v_mul_f32_e32 v69, v64, v68
	v_fmac_f32_e32 v71, v69, v69
	v_mul_f32_e32 v69, v65, v68
	v_fmac_f32_e32 v71, v69, v69
	v_mul_f32_e32 v69, v58, v68
	v_fmac_f32_e32 v71, v69, v69
	v_mul_f32_e32 v69, v59, v68
	v_fmac_f32_e32 v71, v69, v69
	v_mul_f32_e32 v69, v60, v68
	v_fmac_f32_e32 v71, v69, v69
	v_mul_f32_e32 v69, v61, v68
	v_pk_mul_f32 v[74:75], v[54:55], v[68:69] op_sel_hi:[1,0]
	v_fmac_f32_e32 v71, v69, v69
	v_pk_mul_f32 v[74:75], v[74:75], v[74:75]
	s_nop 0
	v_add_f32_e32 v69, v74, v71
	v_add_f32_e32 v69, v75, v69
	v_pk_mul_f32 v[74:75], v[56:57], v[68:69] op_sel_hi:[1,0]
	s_nop 0
	v_pk_mul_f32 v[74:75], v[74:75], v[74:75]
	s_nop 0
	v_add_f32_e32 v69, v74, v69
	v_add_f32_e32 v69, v75, v69
	v_pk_mul_f32 v[74:75], v[50:51], v[68:69] op_sel_hi:[1,0]
	s_nop 0
	v_pk_mul_f32 v[74:75], v[74:75], v[74:75]
	s_nop 0
	v_add_f32_e32 v69, v74, v69
	v_add_f32_e32 v69, v75, v69
	v_pk_mul_f32 v[74:75], v[52:53], v[68:69] op_sel_hi:[1,0]
	s_nop 0
	v_pk_mul_f32 v[74:75], v[74:75], v[74:75]
	s_nop 0
	v_add_f32_e32 v69, v74, v69
	v_add_f32_e32 v69, v75, v69
	ds_bpermute_b32 v71, v78, v69
	s_waitcnt lgkmcnt(0)
	v_add_f32_e32 v69, v69, v71
	ds_bpermute_b32 v71, v79, v69
	s_waitcnt lgkmcnt(0)
	v_add_f32_e32 v69, v69, v71
	v_fmamk_f32 v69, v69, 0x3c800000, v143
	v_cmp_gt_f32_e32 vcc, s53, v69
	v_mul_f32_e32 v71, 0x4b800000, v69
	s_nop 0
	v_cndmask_b32_e32 v69, v69, v71, vcc
	v_rsq_f32_e32 v69, v69
	s_nop 0
	v_mul_f32_e32 v71, 0x45800000, v69
	v_cndmask_b32_e32 v69, v69, v71, vcc
	v_mul_f32_e32 v68, v68, v69
	v_mul_f32_e32 v72, 0x3e16c740, v68
	v_mul_hi_i32 v68, v70, s47
	v_lshrrev_b32_e32 v69, 31, v68
	v_ashrrev_i32_e32 v68, 9, v68
	v_add_u32_e32 v69, v68, v69
	v_mul_i32_i24_e32 v68, 0x900, v69
	v_sub_u32_e32 v68, v70, v68
	v_mad_i32_i24 v71, v69, 6, v1
	v_ashrrev_i32_e32 v69, 31, v68
	v_pk_mul_f32 v[62:63], v[62:63], v[72:73] op_sel_hi:[1,0]
	v_mad_i64_i32 v[76:77], s[2:3], v71, s20, v[68:69]
	v_mov_b64_e32 v[68:69], s[16:17]
	v_pk_mul_f32 v[62:63], v[80:81], v[62:63]
	v_mad_u64_u32 v[74:75], s[2:3], v76, s4, v[68:69]
	v_cvt_pk_bf16_f32 v76, v62, v63
	v_pk_mul_f32 v[62:63], v[64:65], v[72:73] op_sel_hi:[1,0]
	v_mad_i32_i24 v75, v77, s4, v75
	v_pk_mul_f32 v[62:63], v[82:83], v[62:63]
	v_pk_mul_f32 v[58:59], v[58:59], v[72:73] op_sel_hi:[1,0]
	v_cvt_pk_bf16_f32 v77, v62, v63
	v_lshlrev_b32_e32 v62, 3, v73
	v_mov_b32_e32 v63, v111
	v_lshl_add_u64 v[64:65], v[74:75], 0, v[62:63]
	global_store_dwordx2 v[64:65], v[76:77], off
	v_pk_mul_f32 v[60:61], v[60:61], v[72:73] op_sel_hi:[1,0]
	v_pk_mul_f32 v[54:55], v[54:55], v[72:73] op_sel_hi:[1,0]
	v_pk_mul_f32 v[56:57], v[56:57], v[72:73] op_sel_hi:[1,0]
	v_pk_mul_f32 v[50:51], v[50:51], v[72:73] op_sel_hi:[1,0]
	v_pk_mul_f32 v[52:53], v[52:53], v[72:73] op_sel_hi:[1,0]
	v_pk_mul_f32 v[58:59], v[172:173], v[58:59]
	v_pk_mul_f32 v[60:61], v[174:175], v[60:61]
	v_cvt_pk_bf16_f32 v58, v58, v59
	v_cvt_pk_bf16_f32 v59, v60, v61
	global_store_dwordx2 v[64:65], v[58:59], off offset:32
	v_pk_mul_f32 v[54:55], v[176:177], v[54:55]
	v_pk_mul_f32 v[56:57], v[178:179], v[56:57]
	v_cvt_pk_bf16_f32 v54, v54, v55
	v_cvt_pk_bf16_f32 v55, v56, v57
	global_store_dwordx2 v[64:65], v[54:55], off offset:64
	v_pk_mul_f32 v[50:51], v[180:181], v[50:51]
	v_pk_mul_f32 v[52:53], v[182:183], v[52:53]
	v_cvt_pk_bf16_f32 v50, v50, v51
	v_cvt_pk_bf16_f32 v51, v52, v53
	global_store_dwordx2 v[64:65], v[50:51], off offset:96
	v_or_b32_e32 v51, 16, v70
	v_mov_b32_e32 v50, v165
	v_fmamk_f32 v50, v50, 0x3aaaaaab, v143
	v_cmp_gt_f32_e32 vcc, s53, v50
	v_mul_f32_e32 v52, 0x4b800000, v50
	s_nop 0
	v_cndmask_b32_e32 v50, v50, v52, vcc
	v_rsq_f32_e32 v50, v50
	s_nop 0
	v_mul_f32_e32 v52, 0x45800000, v50
	v_cndmask_b32_e32 v50, v50, v52, vcc
	v_mul_f32_e32 v53, v47, v50
	v_mul_f32_e32 v52, v46, v50
	v_mul_f32_e32 v54, v53, v53
	v_fmac_f32_e32 v54, v52, v52
	v_mul_f32_e32 v52, v48, v50
	v_fmac_f32_e32 v54, v52, v52
	v_mul_f32_e32 v52, v49, v50
	v_fmac_f32_e32 v54, v52, v52
	v_mul_f32_e32 v52, v42, v50
	v_fmac_f32_e32 v54, v52, v52
	v_mul_f32_e32 v52, v43, v50
	v_fmac_f32_e32 v54, v52, v52
	v_mul_f32_e32 v52, v44, v50
	v_fmac_f32_e32 v54, v52, v52
	v_mul_f32_e32 v52, v45, v50
	v_fmac_f32_e32 v54, v52, v52
	v_pk_mul_f32 v[52:53], v[38:39], v[50:51] op_sel_hi:[1,0]
	s_nop 0
	v_pk_mul_f32 v[52:53], v[52:53], v[52:53]
	s_nop 0
	v_add_f32_e32 v52, v52, v54
	v_add_f32_e32 v54, v53, v52
	v_pk_mul_f32 v[52:53], v[40:41], v[50:51] op_sel_hi:[1,0]
	s_nop 0
	v_pk_mul_f32 v[52:53], v[52:53], v[52:53]
	s_nop 0
	v_add_f32_e32 v52, v52, v54
	v_add_f32_e32 v54, v53, v52
	v_pk_mul_f32 v[52:53], v[34:35], v[50:51] op_sel_hi:[1,0]
	s_nop 0
	v_pk_mul_f32 v[52:53], v[52:53], v[52:53]
	s_nop 0
	v_add_f32_e32 v52, v52, v54
	v_add_f32_e32 v54, v53, v52
	v_pk_mul_f32 v[52:53], v[36:37], v[50:51] op_sel_hi:[1,0]
	s_nop 0
	v_pk_mul_f32 v[52:53], v[52:53], v[52:53]
	s_nop 0
	v_add_f32_e32 v52, v52, v54
	v_add_f32_e32 v52, v53, v52
	ds_bpermute_b32 v53, v78, v52
	s_waitcnt lgkmcnt(0)
; DI unsigned pk_bf16(float lo, float hi) { f32x2 v = {lo, hi}; bf16v2 b = __builtin_convertvector(v, bf16v2); return __builtin_bit_cast(unsigned, b); }
;   DI void operator()(const f32x4 (&acc)[4][4], int r0, int c0, int fr, int fq) const {
;     ...
;       const int h = c0 >> 6;
; #pragma unroll
;       for (int m = 0; m < 4; ++m) {
;         const int row = r0 + m * 16 + fr; const float rs = rsqrtf(rstd[row] * (1.f / 768.f) + EPSF);
;         float ss = 0.f;
; #pragma unroll
;         for (int n = 0; n < 4; ++n)
; #pragma unroll
;           for (int j = 0; j < 4; ++j) { float v = acc[m][n][j] * rs; ss += v * v; }
;         ss += __shfl_xor(ss, 16); ss += __shfl_xor(ss, 32);
;         const float inv = rsqrtf(ss * (1.f / 64.f) + EPSF) * rs * QSCALE;
;         const int b = row / TB, s = row % TB;
;         bf16_t* dst = Q + ((size_t)(b * 6 + h) * TB + s) * 96;
; #pragma unroll
;         for (int n = 0; n < 4; ++n) {
;           const int d = n * 16 + fq * 4; f32x4 g = *(const f32x4*)(gn + d);
;           u32x2 v = {pk_bf16(acc[m][n][0] * inv * g[0], acc[m][n][1] * inv * g[1]), pk_bf16(acc[m][n][2] * inv * g[2], acc[m][n][3] * inv * g[3])};
;           *(u32x2*)(dst + d) = v;
;         }
;       }
	v_add_f32_e32 v52, v52, v53
	ds_bpermute_b32 v53, v79, v52
	s_waitcnt lgkmcnt(0)
	v_add_f32_e32 v52, v52, v53
	v_fmamk_f32 v52, v52, 0x3c800000, v143
	v_cmp_gt_f32_e32 vcc, s53, v52
	v_mul_f32_e32 v53, 0x4b800000, v52
	s_nop 0
	v_cndmask_b32_e32 v52, v52, v53, vcc
	v_rsq_f32_e32 v52, v52
	s_nop 0
	v_mul_f32_e32 v53, 0x45800000, v52
	v_cndmask_b32_e32 v52, v52, v53, vcc
	v_mul_f32_e32 v50, v50, v52
	v_mul_hi_i32 v52, v51, s47
	v_lshrrev_b32_e32 v53, 31, v52
	v_ashrrev_i32_e32 v52, 9, v52
	v_add_u32_e32 v53, v52, v53
	v_mul_i32_i24_e32 v52, 0x900, v53
	v_sub_u32_e32 v52, v51, v52
	v_mad_i32_i24 v51, v53, 6, v1
	v_ashrrev_i32_e32 v53, 31, v52
	v_mad_i64_i32 v[54:55], s[2:3], v51, s20, v[52:53]
	v_mad_u64_u32 v[52:53], s[2:3], v54, s4, v[68:69]
	v_mad_i32_i24 v53, v55, s4, v53
	v_mul_f32_e32 v50, 0x3e16c740, v50
	v_pk_mul_f32 v[46:47], v[46:47], v[50:51] op_sel_hi:[1,0]
	v_pk_mul_f32 v[48:49], v[48:49], v[50:51] op_sel_hi:[1,0]
	v_lshl_add_u64 v[52:53], v[52:53], 0, v[62:63]
	v_pk_mul_f32 v[42:43], v[42:43], v[50:51] op_sel_hi:[1,0]
	v_pk_mul_f32 v[44:45], v[44:45], v[50:51] op_sel_hi:[1,0]
	v_pk_mul_f32 v[38:39], v[38:39], v[50:51] op_sel_hi:[1,0]
	v_pk_mul_f32 v[40:41], v[40:41], v[50:51] op_sel_hi:[1,0]
	v_pk_mul_f32 v[34:35], v[34:35], v[50:51] op_sel_hi:[1,0]
	v_pk_mul_f32 v[36:37], v[36:37], v[50:51] op_sel_hi:[1,0]
	v_pk_mul_f32 v[46:47], v[168:169], v[46:47]
	v_pk_mul_f32 v[48:49], v[170:171], v[48:49]
	v_cvt_pk_bf16_f32 v46, v46, v47
	v_cvt_pk_bf16_f32 v47, v48, v49
	global_store_dwordx2 v[52:53], v[46:47], off
	v_pk_mul_f32 v[42:43], v[172:173], v[42:43]
	v_pk_mul_f32 v[44:45], v[174:175], v[44:45]
	v_cvt_pk_bf16_f32 v42, v42, v43
	v_cvt_pk_bf16_f32 v43, v44, v45
	global_store_dwordx2 v[52:53], v[42:43], off offset:32
	v_pk_mul_f32 v[38:39], v[176:177], v[38:39]
	v_pk_mul_f32 v[40:41], v[178:179], v[40:41]
	v_cvt_pk_bf16_f32 v38, v38, v39
	v_cvt_pk_bf16_f32 v39, v40, v41
	global_store_dwordx2 v[52:53], v[38:39], off offset:64
	v_pk_mul_f32 v[34:35], v[180:181], v[34:35]
	v_pk_mul_f32 v[36:37], v[182:183], v[36:37]
	v_cvt_pk_bf16_f32 v34, v34, v35
	v_cvt_pk_bf16_f32 v35, v36, v37
	global_store_dwordx2 v[52:53], v[34:35], off offset:96
	v_or_b32_e32 v35, 32, v70
	v_mov_b32_e32 v34, v166
	v_fmamk_f32 v34, v34, 0x3aaaaaab, v143
	v_cmp_gt_f32_e32 vcc, s53, v34
	v_mul_f32_e32 v36, 0x4b800000, v34
	s_nop 0
	v_cndmask_b32_e32 v34, v34, v36, vcc
	v_rsq_f32_e32 v34, v34
	s_nop 0
	v_mul_f32_e32 v36, 0x45800000, v34
	v_cndmask_b32_e32 v34, v34, v36, vcc
	v_mul_f32_e32 v37, v31, v34
	v_mul_f32_e32 v36, v30, v34
	v_mul_f32_e32 v38, v37, v37
	v_fmac_f32_e32 v38, v36, v36
	v_mul_f32_e32 v36, v32, v34
	v_fmac_f32_e32 v38, v36, v36
	v_mul_f32_e32 v36, v33, v34
	v_fmac_f32_e32 v38, v36, v36
	v_mul_f32_e32 v36, v26, v34
	v_fmac_f32_e32 v38, v36, v36
	v_mul_f32_e32 v36, v27, v34
	v_fmac_f32_e32 v38, v36, v36
	v_mul_f32_e32 v36, v28, v34
	v_fmac_f32_e32 v38, v36, v36
	v_mul_f32_e32 v36, v29, v34
	v_fmac_f32_e32 v38, v36, v36
	v_pk_mul_f32 v[36:37], v[22:23], v[34:35] op_sel_hi:[1,0]
	s_nop 0
	v_pk_mul_f32 v[36:37], v[36:37], v[36:37]
	s_nop 0
	v_add_f32_e32 v36, v36, v38
	v_add_f32_e32 v38, v37, v36
	v_pk_mul_f32 v[36:37], v[24:25], v[34:35] op_sel_hi:[1,0]
	s_nop 0
	v_pk_mul_f32 v[36:37], v[36:37], v[36:37]
	s_nop 0
	v_add_f32_e32 v36, v36, v38
	v_add_f32_e32 v38, v37, v36
	v_pk_mul_f32 v[36:37], v[18:19], v[34:35] op_sel_hi:[1,0]
	s_nop 0
	v_pk_mul_f32 v[36:37], v[36:37], v[36:37]
	s_nop 0
	v_add_f32_e32 v36, v36, v38
	v_add_f32_e32 v38, v37, v36
	v_pk_mul_f32 v[36:37], v[20:21], v[34:35] op_sel_hi:[1,0]
	s_nop 0
	v_pk_mul_f32 v[36:37], v[36:37], v[36:37]
	s_nop 0
	v_add_f32_e32 v36, v36, v38
	v_add_f32_e32 v36, v37, v36
	ds_bpermute_b32 v37, v78, v36
	s_waitcnt lgkmcnt(0)
	v_add_f32_e32 v36, v36, v37
	ds_bpermute_b32 v37, v79, v36
	s_waitcnt lgkmcnt(0)
; DI unsigned pk_bf16(float lo, float hi) { f32x2 v = {lo, hi}; bf16v2 b = __builtin_convertvector(v, bf16v2); return __builtin_bit_cast(unsigned, b); }
;   DI void operator()(const f32x4 (&acc)[4][4], int r0, int c0, int fr, int fq) const {
;     ...
;       const int h = c0 >> 6;
; #pragma unroll
;       for (int m = 0; m < 4; ++m) {
;         const int row = r0 + m * 16 + fr; const float rs = rsqrtf(rstd[row] * (1.f / 768.f) + EPSF);
;         float ss = 0.f;
; #pragma unroll
;         for (int n = 0; n < 4; ++n)
; #pragma unroll
;           for (int j = 0; j < 4; ++j) { float v = acc[m][n][j] * rs; ss += v * v; }
;         ss += __shfl_xor(ss, 16); ss += __shfl_xor(ss, 32);
;         const float inv = rsqrtf(ss * (1.f / 64.f) + EPSF) * rs * QSCALE;
;         const int b = row / TB, s = row % TB;
;         bf16_t* dst = Q + ((size_t)(b * 6 + h) * TB + s) * 96;
; #pragma unroll
;         for (int n = 0; n < 4; ++n) {
;           const int d = n * 16 + fq * 4; f32x4 g = *(const f32x4*)(gn + d);
;           u32x2 v = {pk_bf16(acc[m][n][0] * inv * g[0], acc[m][n][1] * inv * g[1]), pk_bf16(acc[m][n][2] * inv * g[2], acc[m][n][3] * inv * g[3])};
;           *(u32x2*)(dst + d) = v;
;         }
;       }
	v_add_f32_e32 v36, v36, v37
	v_fmamk_f32 v36, v36, 0x3c800000, v143
	v_cmp_gt_f32_e32 vcc, s53, v36
	v_mul_f32_e32 v37, 0x4b800000, v36
	s_nop 0
	v_cndmask_b32_e32 v36, v36, v37, vcc
	v_rsq_f32_e32 v36, v36
	s_nop 0
	v_mul_f32_e32 v37, 0x45800000, v36
	v_cndmask_b32_e32 v36, v36, v37, vcc
	v_mul_f32_e32 v34, v34, v36
	v_mul_hi_i32 v36, v35, s47
	v_lshrrev_b32_e32 v37, 31, v36
	v_ashrrev_i32_e32 v36, 9, v36
	v_add_u32_e32 v37, v36, v37
	v_mul_i32_i24_e32 v36, 0x900, v37
	v_sub_u32_e32 v36, v35, v36
	v_mad_i32_i24 v35, v37, 6, v1
	v_ashrrev_i32_e32 v37, 31, v36
	v_mad_i64_i32 v[38:39], s[2:3], v35, s20, v[36:37]
	v_mad_u64_u32 v[36:37], s[2:3], v38, s4, v[68:69]
	v_mad_i32_i24 v37, v39, s4, v37
	v_mul_f32_e32 v34, 0x3e16c740, v34
	v_pk_mul_f32 v[30:31], v[30:31], v[34:35] op_sel_hi:[1,0]
	v_pk_mul_f32 v[32:33], v[32:33], v[34:35] op_sel_hi:[1,0]
	v_lshl_add_u64 v[36:37], v[36:37], 0, v[62:63]
	v_pk_mul_f32 v[26:27], v[26:27], v[34:35] op_sel_hi:[1,0]
	v_pk_mul_f32 v[28:29], v[28:29], v[34:35] op_sel_hi:[1,0]
	v_pk_mul_f32 v[22:23], v[22:23], v[34:35] op_sel_hi:[1,0]
	v_pk_mul_f32 v[24:25], v[24:25], v[34:35] op_sel_hi:[1,0]
	v_pk_mul_f32 v[18:19], v[18:19], v[34:35] op_sel_hi:[1,0]
	v_pk_mul_f32 v[20:21], v[20:21], v[34:35] op_sel_hi:[1,0]
	v_pk_mul_f32 v[30:31], v[168:169], v[30:31]
	v_pk_mul_f32 v[32:33], v[170:171], v[32:33]
	v_cvt_pk_bf16_f32 v30, v30, v31
	v_cvt_pk_bf16_f32 v31, v32, v33
	global_store_dwordx2 v[36:37], v[30:31], off
	v_pk_mul_f32 v[26:27], v[172:173], v[26:27]
	v_pk_mul_f32 v[28:29], v[174:175], v[28:29]
	v_cvt_pk_bf16_f32 v26, v26, v27
	v_cvt_pk_bf16_f32 v27, v28, v29
	global_store_dwordx2 v[36:37], v[26:27], off offset:32
	v_pk_mul_f32 v[22:23], v[176:177], v[22:23]
	v_pk_mul_f32 v[24:25], v[178:179], v[24:25]
	v_cvt_pk_bf16_f32 v22, v22, v23
	v_cvt_pk_bf16_f32 v23, v24, v25
	global_store_dwordx2 v[36:37], v[22:23], off offset:64
	v_pk_mul_f32 v[18:19], v[180:181], v[18:19]
	v_pk_mul_f32 v[20:21], v[182:183], v[20:21]
	v_cvt_pk_bf16_f32 v18, v18, v19
	v_cvt_pk_bf16_f32 v19, v20, v21
	global_store_dwordx2 v[36:37], v[18:19], off offset:96
	v_or_b32_e32 v19, 48, v70
	v_mov_b32_e32 v18, v167
	v_fmamk_f32 v18, v18, 0x3aaaaaab, v143
	v_cmp_gt_f32_e32 vcc, s53, v18
	v_mul_f32_e32 v20, 0x4b800000, v18
	s_nop 0
	v_cndmask_b32_e32 v18, v18, v20, vcc
	v_rsq_f32_e32 v18, v18
	s_nop 0
	v_mul_f32_e32 v20, 0x45800000, v18
	v_cndmask_b32_e32 v18, v18, v20, vcc
	v_mul_f32_e32 v21, v15, v18
	v_mul_f32_e32 v20, v14, v18
	v_mul_f32_e32 v22, v21, v21
	v_fmac_f32_e32 v22, v20, v20
	v_mul_f32_e32 v20, v16, v18
	v_fmac_f32_e32 v22, v20, v20
	v_mul_f32_e32 v20, v17, v18
	v_fmac_f32_e32 v22, v20, v20
	v_mul_f32_e32 v20, v10, v18
	v_fmac_f32_e32 v22, v20, v20
	v_mul_f32_e32 v20, v11, v18
	v_fmac_f32_e32 v22, v20, v20
	v_mul_f32_e32 v20, v12, v18
	v_fmac_f32_e32 v22, v20, v20
	v_mul_f32_e32 v20, v13, v18
	v_fmac_f32_e32 v22, v20, v20
	v_pk_mul_f32 v[20:21], v[6:7], v[18:19] op_sel_hi:[1,0]
	s_nop 0
	v_pk_mul_f32 v[20:21], v[20:21], v[20:21]
	s_nop 0
	v_add_f32_e32 v20, v20, v22
	v_add_f32_e32 v22, v21, v20
	v_pk_mul_f32 v[20:21], v[8:9], v[18:19] op_sel_hi:[1,0]
	s_nop 0
	v_pk_mul_f32 v[20:21], v[20:21], v[20:21]
	s_nop 0
	v_add_f32_e32 v20, v20, v22
	v_add_f32_e32 v22, v21, v20
	v_pk_mul_f32 v[20:21], v[2:3], v[18:19] op_sel_hi:[1,0]
	s_nop 0
	v_pk_mul_f32 v[20:21], v[20:21], v[20:21]
	s_nop 0
	v_add_f32_e32 v20, v20, v22
	v_add_f32_e32 v22, v21, v20
	v_pk_mul_f32 v[20:21], v[4:5], v[18:19] op_sel_hi:[1,0]
	s_nop 0
	v_pk_mul_f32 v[20:21], v[20:21], v[20:21]
	s_nop 0
	v_add_f32_e32 v20, v20, v22
	v_add_f32_e32 v20, v21, v20
	ds_bpermute_b32 v21, v78, v20
	s_waitcnt lgkmcnt(0)
	v_add_f32_e32 v20, v20, v21
	ds_bpermute_b32 v21, v79, v20
	s_waitcnt lgkmcnt(0)
	v_add_f32_e32 v20, v20, v21
	v_fmamk_f32 v20, v20, 0x3c800000, v143
	v_cmp_gt_f32_e32 vcc, s53, v20
	v_mul_f32_e32 v21, 0x4b800000, v20
	s_nop 0
	v_cndmask_b32_e32 v20, v20, v21, vcc
	v_rsq_f32_e32 v20, v20
	s_nop 0
	v_mul_f32_e32 v21, 0x45800000, v20
	v_cndmask_b32_e32 v20, v20, v21, vcc
	v_mul_f32_e32 v18, v18, v20
	v_mul_hi_i32 v20, v19, s47
	v_lshrrev_b32_e32 v21, 31, v20
	v_ashrrev_i32_e32 v20, 9, v20
	v_add_u32_e32 v21, v20, v21
	v_mul_i32_i24_e32 v20, 0x900, v21
	v_sub_u32_e32 v20, v19, v20
	v_mad_i32_i24 v1, v21, 6, v1
	v_ashrrev_i32_e32 v21, 31, v20
	v_mad_i64_i32 v[22:23], s[2:3], v1, s20, v[20:21]
	v_mad_u64_u32 v[20:21], s[2:3], v22, s4, v[68:69]
	v_mad_i32_i24 v21, v23, s4, v21
	v_mul_f32_e32 v18, 0x3e16c740, v18
	v_pk_mul_f32 v[14:15], v[14:15], v[18:19] op_sel_hi:[1,0]
	v_pk_mul_f32 v[16:17], v[16:17], v[18:19] op_sel_hi:[1,0]
	v_lshl_add_u64 v[20:21], v[20:21], 0, v[62:63]
	v_pk_mul_f32 v[10:11], v[10:11], v[18:19] op_sel_hi:[1,0]
	v_pk_mul_f32 v[12:13], v[12:13], v[18:19] op_sel_hi:[1,0]
	v_pk_mul_f32 v[6:7], v[6:7], v[18:19] op_sel_hi:[1,0]
	v_pk_mul_f32 v[8:9], v[8:9], v[18:19] op_sel_hi:[1,0]
	v_pk_mul_f32 v[2:3], v[2:3], v[18:19] op_sel_hi:[1,0]
	v_pk_mul_f32 v[4:5], v[4:5], v[18:19] op_sel_hi:[1,0]
	v_pk_mul_f32 v[14:15], v[168:169], v[14:15]
	v_pk_mul_f32 v[16:17], v[170:171], v[16:17]
	v_cvt_pk_bf16_f32 v14, v14, v15
	v_cvt_pk_bf16_f32 v15, v16, v17
	global_store_dwordx2 v[20:21], v[14:15], off
	v_pk_mul_f32 v[10:11], v[172:173], v[10:11]
	v_pk_mul_f32 v[12:13], v[174:175], v[12:13]
	v_cvt_pk_bf16_f32 v10, v10, v11
	v_cvt_pk_bf16_f32 v11, v12, v13
	global_store_dwordx2 v[20:21], v[10:11], off offset:32
	v_pk_mul_f32 v[6:7], v[176:177], v[6:7]
	v_pk_mul_f32 v[8:9], v[178:179], v[8:9]
	v_cvt_pk_bf16_f32 v6, v6, v7
	v_cvt_pk_bf16_f32 v7, v8, v9
	global_store_dwordx2 v[20:21], v[6:7], off offset:64
	v_pk_mul_f32 v[2:3], v[180:181], v[2:3]
	v_pk_mul_f32 v[4:5], v[182:183], v[4:5]
	v_cvt_pk_bf16_f32 v2, v2, v3
	v_cvt_pk_bf16_f32 v3, v4, v5
	global_store_dwordx2 v[20:21], v[2:3], off offset:96
	s_branch .LBB0_510
